# 3-hop lane reductions in gla3/mla_fin via DPP; gla3 output-norm gains loaded once per phase instead of per chunk
# baseline (speedup 1.0000x reference)
; DI float shx(float v, int mask, int lane) { return __int_as_float(__builtin_amdgcn_ds_bpermute((lane ^ mask) << 2, __float_as_int(v))); }
; #define SSQ8(W_, ACC_) do { UNPK(W_, e_); ACC_ += (e_[0] * e_[0] + e_[1] * e_[1]) + (e_[2] * e_[2] + e_[3] * e_[3]) + (e_[4] * e_[4] + e_[5] * e_[5]) + (e_[6] * e_[6] + e_[7] * e_[7]); } while (0)
; DI void phase_mla_fin(ArgsP a, int tb_, int l, char* shm, int vcu, int G) {
;     ...
;             const u32x4* pz = (const u32x4*)(zkv + (size_t)m * 256); const u32x4* p = (const u32x4*)(kvraw + (size_t)m * 1024 + h * 128);
;             u32x4 st[2], krp[4], w[8], vw[8];
; #pragma unroll
;             for (int i = 0; i < 2; ++i) st[i] = pz[2 * h + i];
; #pragma unroll
;             for (int i = 0; i < 4; ++i) krp[i] = pz[16 + i];
; #pragma unroll
;             for (int i = 0; i < 8; ++i) { w[i] = p[i]; vw[i] = p[8 + i]; }
;             const float* gkn = gkn0; asm volatile("" : "+s"(gkn));
;             float sskv = 0.f, ss = 0.f, sk = 0.f;
; #pragma unroll
;             for (int i = 0; i < 2; ++i) SSQ8(st[i], sskv);
;             sskv += shx(sskv, 1, lane); sskv += shx(sskv, 2, lane); sskv += shx(sskv, 4, lane);
;             const float rkv = rsqrtf(sskv * (1.f / 128.f) + EPS);
.LBB0_965:
	v_and_b32_e32 v0, -8, v174
	v_or_b32_e32 v46, v0, v169
	v_cmp_gt_i32_e64 s[6:7], s74, v46
	v_add_u32_e32 v34, 0xffff8000, v174
	v_ashrrev_i32_e32 v33, 10, v168
	v_cndmask_b32_e64 v1, v238, v239, s[6:7]
	v_bitop3_b32 v32, v1, v0, v169 bitop3:0xe0
	v_lshlrev_b32_e32 v0, 5, v32
	v_cndmask_b32_e64 v0, 0, v0, s[6:7]
	v_lshlrev_b32_e32 v28, 2, v0
	global_load_dwordx4 v[0:3], v28, s[12:13] offset:48
	global_load_dwordx4 v[8:11], v28, s[12:13] offset:32
	global_load_dwordx4 v[16:19], v28, s[12:13] offset:16
	global_load_dwordx4 v[24:27], v28, s[12:13]
	global_load_dwordx4 v[4:7], v28, s[12:13] offset:112
	global_load_dwordx4 v[12:15], v28, s[12:13] offset:96
	global_load_dwordx4 v[20:23], v28, s[12:13] offset:80
	s_nop 0
	global_load_dwordx4 v[28:31], v28, s[12:13] offset:64
	v_lshrrev_b32_e32 v34, 8, v34
	v_cndmask_b32_e64 v33, v34, v33, s[6:7]
	v_add_u32_e32 v34, 0x100, v32
	v_ashrrev_i32_e32 v47, 31, v46
	v_lshl_or_b32 v142, v33, 3, v170
	v_cndmask_b32_e64 v188, v32, v34, s[6:7]
	v_lshlrev_b64 v[52:53], 9, v[46:47]
	s_and_saveexec_b64 s[4:5], vcc
	s_xor_b64 s[30:31], exec, s[4:5]
	s_cbranch_execz .LBB0_967
	v_lshl_add_u64 v[32:33], s[14:15], 0, v[52:53]
	v_mov_b32_e32 v119, v189
	v_lshl_add_u64 v[36:37], v[32:33], 0, v[118:119]
	global_load_dwordx4 v[120:123], v[36:37], off
	global_load_dwordx4 v[124:127], v[36:37], off offset:16
	global_load_dwordx4 v[48:51], v[32:33], off offset:304
	global_load_dwordx4 v[52:55], v[32:33], off offset:288
	global_load_dwordx4 v[56:59], v[32:33], off offset:272
	global_load_dwordx4 v[60:63], v[32:33], off offset:256
	v_lshlrev_b64 v[34:35], 11, v[46:47]
	v_lshl_add_u64 v[92:93], v[112:113], 0, v[34:35]
	global_load_dwordx4 v[40:43], v[92:93], off offset:16
	global_load_dwordx4 v[44:47], v[92:93], off
	global_load_dwordx4 v[68:71], v[92:93], off offset:48
	global_load_dwordx4 v[76:79], v[92:93], off offset:32
	global_load_dwordx4 v[96:99], v[92:93], off offset:176
	global_load_dwordx4 v[100:103], v[92:93], off offset:160
	global_load_dwordx4 v[104:107], v[92:93], off offset:144
	global_load_dwordx4 v[108:111], v[92:93], off offset:128
	global_load_dwordx4 v[32:35], v[92:93], off offset:112
	global_load_dwordx4 v[36:39], v[92:93], off offset:96
	global_load_dwordx4 v[64:67], v[92:93], off offset:80
	global_load_dwordx4 v[72:75], v[92:93], off offset:64
	global_load_dwordx4 v[80:83], v[92:93], off offset:240
	global_load_dwordx4 v[84:87], v[92:93], off offset:224
	global_load_dwordx4 v[88:91], v[92:93], off offset:208
	s_nop 0
	global_load_dwordx4 v[92:95], v[92:93], off offset:192
	s_mov_b32 s2, 0x88000
	s_mov_b64 s[34:35], s[24:25]
	s_waitcnt vmcnt(0)
	v_cndmask_b32_e64 v25, 1.0, v25, s[6:7]
	v_cndmask_b32_e64 v24, 1.0, v24, s[6:7]
	v_cndmask_b32_e64 v29, 0, v29, s[6:7]
	v_cndmask_b32_e64 v28, 0, v28, s[6:7]
	v_cndmask_b32_e64 v27, 1.0, v27, s[6:7]
	v_cndmask_b32_e64 v26, 1.0, v26, s[6:7]
	v_cndmask_b32_e64 v31, 0, v31, s[6:7]
	v_cndmask_b32_e64 v30, 0, v30, s[6:7]
	v_cndmask_b32_e64 v17, 1.0, v17, s[6:7]
	v_cndmask_b32_e64 v16, 1.0, v16, s[6:7]
	v_cndmask_b32_e64 v21, 0, v21, s[6:7]
	v_cndmask_b32_e64 v20, 0, v20, s[6:7]
	v_cndmask_b32_e64 v19, 1.0, v19, s[6:7]
	v_cndmask_b32_e64 v18, 1.0, v18, s[6:7]
	v_cndmask_b32_e64 v23, 0, v23, s[6:7]
	v_cndmask_b32_e64 v22, 0, v22, s[6:7]
	v_cndmask_b32_e64 v9, 1.0, v9, s[6:7]
	v_cndmask_b32_e64 v8, 1.0, v8, s[6:7]
	v_cndmask_b32_e64 v13, 0, v13, s[6:7]
	v_cndmask_b32_e64 v12, 0, v12, s[6:7]
	v_cndmask_b32_e64 v11, 1.0, v11, s[6:7]
	v_cndmask_b32_e64 v10, 1.0, v10, s[6:7]
	v_cndmask_b32_e64 v15, 0, v15, s[6:7]
	v_cndmask_b32_e64 v14, 0, v14, s[6:7]
	v_lshlrev_b32_e32 v156, 16, v45
	v_and_b32_e32 v157, 0xffff0000, v45
	v_lshlrev_b32_e32 v158, 16, v44
	v_and_b32_e32 v159, 0xffff0000, v44
	v_lshlrev_b32_e32 v150, 16, v47
	v_and_b32_e32 v151, 0xffff0000, v47
	v_and_b32_e32 v130, 0xffff0000, v120
	v_lshlrev_b32_e32 v129, 16, v124
	v_and_b32_e32 v131, 0xffff0000, v124
	v_lshlrev_b32_e32 v133, 16, v125
	v_and_b32_e32 v125, 0xffff0000, v125
	v_and_b32_e32 v124, 0xffff0000, v121
	v_lshlrev_b32_e32 v128, 16, v120
	v_lshlrev_b32_e32 v132, 16, v121
	v_lshlrev_b32_e32 v121, 16, v126
	v_lshlrev_b32_e32 v120, 16, v122
	v_and_b32_e32 v135, 0xffff0000, v126
	v_and_b32_e32 v134, 0xffff0000, v122
	v_lshlrev_b32_e32 v136, 16, v123
	v_and_b32_e32 v126, 0xffff0000, v123
	v_pk_mul_f32 v[122:123], v[130:131], v[130:131]
	v_pk_mul_f32 v[124:125], v[124:125], v[124:125]
	v_pk_fma_f32 v[122:123], v[128:129], v[128:129], v[122:123]
	v_pk_fma_f32 v[124:125], v[132:133], v[132:133], v[124:125]
	v_lshlrev_b32_e32 v137, 16, v127
	v_pk_add_f32 v[122:123], v[122:123], v[124:125]
	v_pk_mul_f32 v[124:125], v[134:135], v[134:135]
	v_and_b32_e32 v127, 0xffff0000, v127
	v_pk_fma_f32 v[120:121], v[120:121], v[120:121], v[124:125]
	v_and_b32_e32 v124, 0xffff0000, v109
	v_pk_add_f32 v[120:121], v[120:121], v[122:123]
	v_pk_mul_f32 v[122:123], v[126:127], v[126:127]
	v_lshlrev_b32_e32 v125, 16, v110
	v_pk_fma_f32 v[122:123], v[136:137], v[136:137], v[122:123]
	v_and_b32_e32 v110, 0xffff0000, v110
	v_pk_add_f32 v[120:121], v[122:123], v[120:121]
	v_lshlrev_b32_e32 v122, 1, v188
	v_add_f32_e32 v119, v120, v121
	v_mov_b32_e32 v123, v189
	v_lshlrev_b32_e32 v126, 16, v111
	v_and_b32_e32 v111, 0xffff0000, v111
	v_and_b32_e32 v127, 0xffff0000, v68
	s_waitcnt lgkmcnt(0)
	s_nop 1
	v_add_f32_dpp v119, v119, v119 quad_perm:[1,0,3,2] row_mask:0xf bank_mask:0xf
	v_and_b32_e32 v131, 0xffff0000, v72
	v_and_b32_e32 v130, 0xffff0000, v74
	v_and_b32_e32 v133, 0xffff0000, v64
	v_and_b32_e32 v132, 0xffff0000, v66
	s_waitcnt lgkmcnt(0)
; DI bf16_t f2bf(float f) { return (bf16_t)(cvtpk(f, f) & 0xffffu); }
; DI float shx(float v, int mask, int lane) { return __int_as_float(__builtin_amdgcn_ds_bpermute((lane ^ mask) << 2, __float_as_int(v))); }
; #define UNPK(W_, E_) const float E_[8] = {bflo((W_).x), bfhi((W_).x), bflo((W_).y), bfhi((W_).y), bflo((W_).z), bfhi((W_).z), bflo((W_).w), bfhi((W_).w)}
; DI void phase_mla_fin(ArgsP a, int tb_, int l, char* shm, int vcu, int G) {
;     ...
;             sskv += shx(sskv, 1, lane); sskv += shx(sskv, 2, lane); sskv += shx(sskv, 4, lane);
;             const float rkv = rsqrtf(sskv * (1.f / 128.f) + EPS);
;             { bf16_t* vo = Vt + bh * 64 * KVLEN + pos;
; #pragma unroll
;               for (int i = 0; i < 8; ++i) { UNPK(vw[i], e);
; #pragma unroll
;                   for (int j = 0; j < 8; ++j) vo[(size_t)(8 * i + j) * KVLEN] = f2bf(e[j] * rkv); } }
	s_nop 1
	v_add_f32_dpp v119, v119, v119 quad_perm:[2,3,0,1] row_mask:0xf bank_mask:0xf
	v_lshlrev_b32_e32 v154, 16, v46
	v_and_b32_e32 v155, 0xffff0000, v46
	s_waitcnt lgkmcnt(0)
	s_nop 1
	v_add_f32_dpp v119, v119, v119 row_half_mirror row_mask:0xf bank_mask:0xf
	v_fmamk_f32 v119, v119, 0x3c000000, v230
	v_cmp_gt_f32_e64 s[8:9], s76, v119
	v_mul_f32_e32 v120, 0x4b800000, v119
	s_nop 0
	v_cndmask_b32_e64 v119, v119, v120, s[8:9]
	v_rsq_f32_e32 v119, v119
	s_nop 0
	v_mul_f32_e32 v120, 0x45800000, v119
	v_cndmask_b32_e64 v119, v119, v120, s[8:9]
	v_mov_b64_e32 v[120:121], s[20:21]
	v_mad_i64_i32 v[120:121], s[4:5], v142, s2, v[120:121]
	v_lshl_add_u64 v[120:121], v[120:121], 0, v[122:123]
	v_lshlrev_b32_e32 v122, 16, v108
	v_and_b32_e32 v108, 0xffff0000, v108
	v_lshlrev_b32_e32 v123, 16, v109
	v_mul_f32_e32 v109, v119, v122
	v_mul_f32_e32 v108, v119, v108
	s_movk_i32 s2, 0x2000
	v_cvt_pk_bf16_f32 v109, v109, s0
	v_cvt_pk_bf16_f32 v122, v108, s0
	v_add_co_u32_e64 v108, s[8:9], s2, v120
	global_store_short v[120:121], v109, off
	s_nop 0
	v_addc_co_u32_e64 v109, s[8:9], 0, v121, s[8:9]
	global_store_short v[108:109], v122, off offset:512
	v_mul_f32_e32 v108, v119, v123
	v_cvt_pk_bf16_f32 v122, v108, s0
	s_movk_i32 s0, 0x4000
	v_add_co_u32_e64 v108, s[8:9], s0, v120
	s_movk_i32 s2, 0x6000
	s_nop 0
	v_addc_co_u32_e64 v109, s[8:9], 0, v121, s[8:9]
	global_store_short v[108:109], v122, off offset:1024
	v_mul_f32_e32 v108, v119, v124
	v_cvt_pk_bf16_f32 v122, v108, s0
	v_add_co_u32_e64 v108, s[8:9], s2, v120
	s_mov_b32 s2, 0xa000
	s_nop 0
	v_addc_co_u32_e64 v109, s[8:9], 0, v121, s[8:9]
	global_store_short v[108:109], v122, off offset:1536
	v_mul_f32_e32 v108, v119, v125
	v_cvt_pk_bf16_f32 v122, v108, s0
	v_add_co_u32_e64 v108, s[8:9], s74, v120
	v_lshlrev_b32_e32 v123, 16, v107
	s_nop 0
	v_addc_co_u32_e64 v109, s[8:9], 0, v121, s[8:9]
	global_store_short v[108:109], v122, off offset:2048
	v_mul_f32_e32 v108, v119, v110
	v_cvt_pk_bf16_f32 v110, v108, s0
	v_add_co_u32_e64 v108, s[8:9], s2, v120
	s_mov_b32 s2, 0xe000
	s_nop 0
	v_addc_co_u32_e64 v109, s[8:9], 0, v121, s[8:9]
	global_store_short v[108:109], v110, off offset:2560
	v_mul_f32_e32 v108, v119, v126
	v_cvt_pk_bf16_f32 v110, v108, s0
	s_mov_b32 s0, 0xc000
	v_add_co_u32_e64 v108, s[8:9], s0, v120
	v_lshlrev_b32_e32 v122, 16, v106
	s_nop 0
	v_addc_co_u32_e64 v109, s[8:9], 0, v121, s[8:9]
	global_store_short v[108:109], v110, off offset:3072
	v_mul_f32_e32 v108, v119, v111
	v_cvt_pk_bf16_f32 v110, v108, s0
	v_add_co_u32_e64 v108, s[8:9], s2, v120
	s_mov_b32 s2, 0x11000
	s_nop 0
	v_addc_co_u32_e64 v109, s[8:9], 0, v121, s[8:9]
	global_store_short v[108:109], v110, off offset:3584
	v_lshlrev_b32_e32 v108, 16, v104
	v_and_b32_e32 v109, 0xffff0000, v104
	v_mul_f32_e32 v104, v119, v108
	v_cvt_pk_bf16_f32 v108, v104, s0
	v_add_co_u32_e64 v104, s[8:9], s2, v120
	v_lshlrev_b32_e32 v110, 16, v105
	v_and_b32_e32 v111, 0xffff0000, v105
	v_addc_co_u32_e64 v105, s[8:9], 0, v121, s[8:9]
	global_store_short v[104:105], v108, off
	v_mul_f32_e32 v104, v119, v109
	s_mov_b32 s2, 0x13000
	v_cvt_pk_bf16_f32 v108, v104, s0
	v_add_co_u32_e64 v104, s[8:9], s2, v120
	s_mov_b32 s2, 0x15000
	s_nop 0
	v_addc_co_u32_e64 v105, s[8:9], 0, v121, s[8:9]
	global_store_short v[104:105], v108, off offset:512
	v_mul_f32_e32 v104, v119, v110
	v_cvt_pk_bf16_f32 v108, v104, s0
	v_add_co_u32_e64 v104, s[8:9], s2, v120
	s_mov_b32 s2, 0x17000
	s_nop 0
	v_addc_co_u32_e64 v105, s[8:9], 0, v121, s[8:9]
	global_store_short v[104:105], v108, off offset:1024
	v_mul_f32_e32 v104, v119, v111
	v_cvt_pk_bf16_f32 v108, v104, s0
	v_add_co_u32_e64 v104, s[8:9], s2, v120
	s_mov_b32 s2, 0x19000
	s_nop 0
	v_addc_co_u32_e64 v105, s[8:9], 0, v121, s[8:9]
	global_store_short v[104:105], v108, off offset:1536
	v_mul_f32_e32 v104, v119, v122
	v_cvt_pk_bf16_f32 v108, v104, s0
	v_add_co_u32_e64 v104, s[8:9], s2, v120
	v_and_b32_e32 v106, 0xffff0000, v106
	s_nop 0
	v_addc_co_u32_e64 v105, s[8:9], 0, v121, s[8:9]
	global_store_short v[104:105], v108, off offset:2048
	v_mul_f32_e32 v104, v119, v106
	v_cvt_pk_bf16_f32 v106, v104, s0
	v_add_co_u32_e64 v104, s[8:9], s56, v120
	s_mov_b32 s2, 0x1d000
	s_nop 0
	v_addc_co_u32_e64 v105, s[8:9], 0, v121, s[8:9]
	global_store_short v[104:105], v106, off offset:2560
	v_mul_f32_e32 v104, v119, v123
	v_cvt_pk_bf16_f32 v106, v104, s0
	v_add_co_u32_e64 v104, s[8:9], s2, v120
	v_and_b32_e32 v107, 0xffff0000, v107
	s_nop 0
	v_addc_co_u32_e64 v105, s[8:9], 0, v121, s[8:9]
	global_store_short v[104:105], v106, off offset:3072
	v_mul_f32_e32 v104, v119, v107
	s_mov_b32 s2, 0x1f000
	v_cvt_pk_bf16_f32 v106, v104, s0
	v_add_co_u32_e64 v104, s[8:9], s2, v120
	s_mov_b32 s2, 0x22000
	s_nop 0
	v_addc_co_u32_e64 v105, s[8:9], 0, v121, s[8:9]
	global_store_short v[104:105], v106, off offset:3584
	v_lshlrev_b32_e32 v104, 16, v100
	v_and_b32_e32 v105, 0xffff0000, v100
	v_mul_f32_e32 v100, v119, v104
	v_cvt_pk_bf16_f32 v104, v100, s0
	v_add_co_u32_e64 v100, s[8:9], s2, v120
	v_lshlrev_b32_e32 v106, 16, v101
	v_and_b32_e32 v107, 0xffff0000, v101
	v_addc_co_u32_e64 v101, s[8:9], 0, v121, s[8:9]
	global_store_short v[100:101], v104, off
	v_mul_f32_e32 v100, v119, v105
	v_cvt_pk_bf16_f32 v104, v100, s0
	s_mov_b32 s0, 0x24000
	v_add_co_u32_e64 v100, s[8:9], s0, v120
	s_mov_b32 s2, 0x26000
	s_nop 0
	v_addc_co_u32_e64 v101, s[8:9], 0, v121, s[8:9]
	global_store_short v[100:101], v104, off offset:512
	v_mul_f32_e32 v100, v119, v106
	v_cvt_pk_bf16_f32 v104, v100, s0
	v_add_co_u32_e64 v100, s[8:9], s2, v120
	v_lshlrev_b32_e32 v108, 16, v102
	s_nop 0
	v_addc_co_u32_e64 v101, s[8:9], 0, v121, s[8:9]
	global_store_short v[100:101], v104, off offset:1024
; DI bf16_t f2bf(float f) { return (bf16_t)(cvtpk(f, f) & 0xffffu); }
; #define UNPK(W_, E_) const float E_[8] = {bflo((W_).x), bfhi((W_).x), bflo((W_).y), bfhi((W_).y), bflo((W_).z), bfhi((W_).z), bflo((W_).w), bfhi((W_).w)}
; DI void phase_mla_fin(ArgsP a, int tb_, int l, char* shm, int vcu, int G) {
;     ...
;             { bf16_t* vo = Vt + bh * 64 * KVLEN + pos;
; #pragma unroll
;               for (int i = 0; i < 8; ++i) { UNPK(vw[i], e);
; #pragma unroll
;                   for (int j = 0; j < 8; ++j) vo[(size_t)(8 * i + j) * KVLEN] = f2bf(e[j] * rkv); } }
	v_mul_f32_e32 v100, v119, v107
	v_cvt_pk_bf16_f32 v104, v100, s0
	s_mov_b32 s0, 0x28000
	v_add_co_u32_e64 v100, s[8:9], s0, v120
	s_mov_b32 s2, 0x2a000
	s_nop 0
	v_addc_co_u32_e64 v101, s[8:9], 0, v121, s[8:9]
	global_store_short v[100:101], v104, off offset:1536
	v_mul_f32_e32 v100, v119, v108
	v_cvt_pk_bf16_f32 v104, v100, s0
	v_add_co_u32_e64 v100, s[8:9], s2, v120
	v_and_b32_e32 v102, 0xffff0000, v102
	s_nop 0
	v_addc_co_u32_e64 v101, s[8:9], 0, v121, s[8:9]
	global_store_short v[100:101], v104, off offset:2048
	v_mul_f32_e32 v100, v119, v102
	v_cvt_pk_bf16_f32 v102, v100, s0
	s_mov_b32 s0, 0x2c000
	v_add_co_u32_e64 v100, s[8:9], s0, v120
	v_lshlrev_b32_e32 v109, 16, v103
	s_nop 0
	v_addc_co_u32_e64 v101, s[8:9], 0, v121, s[8:9]
	global_store_short v[100:101], v102, off offset:2560
	v_mul_f32_e32 v100, v119, v109
	s_mov_b32 s2, 0x2e000
	v_cvt_pk_bf16_f32 v102, v100, s0
	v_add_co_u32_e64 v100, s[8:9], s2, v120
	v_and_b32_e32 v103, 0xffff0000, v103
	s_nop 0
	v_addc_co_u32_e64 v101, s[8:9], 0, v121, s[8:9]
	global_store_short v[100:101], v102, off offset:3072
	v_mul_f32_e32 v100, v119, v103
	s_mov_b32 s2, 0x30000
	v_cvt_pk_bf16_f32 v102, v100, s0
	v_add_co_u32_e64 v100, s[8:9], s2, v120
	s_mov_b32 s2, 0x33000
	s_nop 0
	v_addc_co_u32_e64 v101, s[8:9], 0, v121, s[8:9]
	global_store_short v[100:101], v102, off offset:3584
	v_lshlrev_b32_e32 v100, 16, v96
	v_and_b32_e32 v101, 0xffff0000, v96
	v_mul_f32_e32 v96, v119, v100
	v_cvt_pk_bf16_f32 v100, v96, s0
	v_add_co_u32_e64 v96, s[8:9], s2, v120
	v_lshlrev_b32_e32 v102, 16, v97
	v_and_b32_e32 v103, 0xffff0000, v97
	v_addc_co_u32_e64 v97, s[8:9], 0, v121, s[8:9]
	global_store_short v[96:97], v100, off
	v_mul_f32_e32 v96, v119, v101
	s_mov_b32 s2, 0x35000
	v_cvt_pk_bf16_f32 v100, v96, s0
	v_add_co_u32_e64 v96, s[8:9], s2, v120
	s_mov_b32 s2, 0x37000
	s_nop 0
	v_addc_co_u32_e64 v97, s[8:9], 0, v121, s[8:9]
	global_store_short v[96:97], v100, off offset:512
	v_mul_f32_e32 v96, v119, v102
	v_cvt_pk_bf16_f32 v100, v96, s0
	v_add_co_u32_e64 v96, s[8:9], s2, v120
	s_mov_b32 s2, 0x39000
	s_nop 0
	v_addc_co_u32_e64 v97, s[8:9], 0, v121, s[8:9]
	global_store_short v[96:97], v100, off offset:1024
	v_mul_f32_e32 v96, v119, v103
	v_cvt_pk_bf16_f32 v100, v96, s0
	v_add_co_u32_e64 v96, s[8:9], s2, v120
	v_lshlrev_b32_e32 v104, 16, v98
	s_nop 0
	v_addc_co_u32_e64 v97, s[8:9], 0, v121, s[8:9]
	global_store_short v[96:97], v100, off offset:1536
	v_mul_f32_e32 v96, v119, v104
	s_mov_b32 s2, 0x3b000
	v_cvt_pk_bf16_f32 v100, v96, s0
	v_add_co_u32_e64 v96, s[8:9], s2, v120
	v_and_b32_e32 v98, 0xffff0000, v98
	s_nop 0
	v_addc_co_u32_e64 v97, s[8:9], 0, v121, s[8:9]
	global_store_short v[96:97], v100, off offset:2048
	v_mul_f32_e32 v96, v119, v98
	s_mov_b32 s2, 0x3d000
	v_cvt_pk_bf16_f32 v98, v96, s0
	v_add_co_u32_e64 v96, s[8:9], s2, v120
	v_lshlrev_b32_e32 v105, 16, v99
	s_nop 0
	v_addc_co_u32_e64 v97, s[8:9], 0, v121, s[8:9]
	global_store_short v[96:97], v98, off offset:2560
	v_mul_f32_e32 v96, v119, v105
	s_mov_b32 s2, 0x3f000
	v_cvt_pk_bf16_f32 v98, v96, s0
	v_add_co_u32_e64 v96, s[8:9], s2, v120
	v_and_b32_e32 v99, 0xffff0000, v99
	s_nop 0
	v_addc_co_u32_e64 v97, s[8:9], 0, v121, s[8:9]
	global_store_short v[96:97], v98, off offset:3072
	v_mul_f32_e32 v96, v119, v99
	s_mov_b32 s2, 0x41000
	v_cvt_pk_bf16_f32 v98, v96, s0
	v_add_co_u32_e64 v96, s[8:9], s2, v120
	s_mov_b32 s2, 0x44000
	s_nop 0
	v_addc_co_u32_e64 v97, s[8:9], 0, v121, s[8:9]
	global_store_short v[96:97], v98, off offset:3584
	v_lshlrev_b32_e32 v96, 16, v92
	v_and_b32_e32 v97, 0xffff0000, v92
	v_mul_f32_e32 v92, v119, v96
	v_cvt_pk_bf16_f32 v96, v92, s0
	v_add_co_u32_e64 v92, s[8:9], s2, v120
	v_lshlrev_b32_e32 v98, 16, v93
	v_and_b32_e32 v99, 0xffff0000, v93
	v_addc_co_u32_e64 v93, s[8:9], 0, v121, s[8:9]
	global_store_short v[92:93], v96, off
	v_mul_f32_e32 v92, v119, v97
	s_mov_b32 s2, 0x46000
	v_cvt_pk_bf16_f32 v96, v92, s0
	v_add_co_u32_e64 v92, s[8:9], s2, v120
	s_mov_b32 s2, 0x4a000
	s_nop 0
	v_addc_co_u32_e64 v93, s[8:9], 0, v121, s[8:9]
	global_store_short v[92:93], v96, off offset:512
	v_mul_f32_e32 v92, v119, v98
	v_cvt_pk_bf16_f32 v96, v92, s0
	s_mov_b32 s0, 0x48000
	v_add_co_u32_e64 v92, s[8:9], s0, v120
	v_lshlrev_b32_e32 v100, 16, v94
	s_nop 0
	v_addc_co_u32_e64 v93, s[8:9], 0, v121, s[8:9]
	global_store_short v[92:93], v96, off offset:1024
	v_mul_f32_e32 v92, v119, v99
	v_cvt_pk_bf16_f32 v96, v92, s0
	v_add_co_u32_e64 v92, s[8:9], s2, v120
	s_mov_b32 s2, 0x4c000
	s_nop 0
	v_addc_co_u32_e64 v93, s[8:9], 0, v121, s[8:9]
	global_store_short v[92:93], v96, off offset:1536
	v_mul_f32_e32 v92, v119, v100
	v_cvt_pk_bf16_f32 v96, v92, s0
	v_add_co_u32_e64 v92, s[8:9], s2, v120
	v_and_b32_e32 v94, 0xffff0000, v94
	s_nop 0
	v_addc_co_u32_e64 v93, s[8:9], 0, v121, s[8:9]
	global_store_short v[92:93], v96, off offset:2048
	v_mul_f32_e32 v92, v119, v94
	s_mov_b32 s2, 0x4e000
	v_cvt_pk_bf16_f32 v94, v92, s0
	v_add_co_u32_e64 v92, s[8:9], s2, v120
	v_lshlrev_b32_e32 v101, 16, v95
	s_nop 0
	v_addc_co_u32_e64 v93, s[8:9], 0, v121, s[8:9]
	global_store_short v[92:93], v94, off offset:2560
	v_mul_f32_e32 v92, v119, v101
	v_cvt_pk_bf16_f32 v94, v92, s0
	s_mov_b32 s0, 0x50000
	v_add_co_u32_e64 v92, s[8:9], s0, v120
	v_and_b32_e32 v95, 0xffff0000, v95
	s_nop 0
	v_addc_co_u32_e64 v93, s[8:9], 0, v121, s[8:9]
	global_store_short v[92:93], v94, off offset:3072
	v_mul_f32_e32 v92, v119, v95
	s_mov_b32 s2, 0x52000
	v_cvt_pk_bf16_f32 v94, v92, s0
	v_add_co_u32_e64 v92, s[8:9], s2, v120
	s_mov_b32 s2, 0x55000
	s_nop 0
	v_addc_co_u32_e64 v93, s[8:9], 0, v121, s[8:9]
	global_store_short v[92:93], v94, off offset:3584
	v_lshlrev_b32_e32 v92, 16, v88
; DI bf16_t f2bf(float f) { return (bf16_t)(cvtpk(f, f) & 0xffffu); }
; #define UNPK(W_, E_) const float E_[8] = {bflo((W_).x), bfhi((W_).x), bflo((W_).y), bfhi((W_).y), bflo((W_).z), bfhi((W_).z), bflo((W_).w), bfhi((W_).w)}
; DI void phase_mla_fin(ArgsP a, int tb_, int l, char* shm, int vcu, int G) {
;     ...
;             { bf16_t* vo = Vt + bh * 64 * KVLEN + pos;
; #pragma unroll
;               for (int i = 0; i < 8; ++i) { UNPK(vw[i], e);
; #pragma unroll
;                   for (int j = 0; j < 8; ++j) vo[(size_t)(8 * i + j) * KVLEN] = f2bf(e[j] * rkv); } }
	v_and_b32_e32 v93, 0xffff0000, v88
	v_mul_f32_e32 v88, v119, v92
	v_cvt_pk_bf16_f32 v92, v88, s0
	v_add_co_u32_e64 v88, s[8:9], s2, v120
	v_lshlrev_b32_e32 v94, 16, v89
	v_and_b32_e32 v95, 0xffff0000, v89
	v_addc_co_u32_e64 v89, s[8:9], 0, v121, s[8:9]
	global_store_short v[88:89], v92, off
	v_mul_f32_e32 v88, v119, v93
	s_mov_b32 s2, 0x57000
	v_cvt_pk_bf16_f32 v92, v88, s0
	v_add_co_u32_e64 v88, s[8:9], s2, v120
	s_mov_b32 s2, 0x59000
	s_nop 0
	v_addc_co_u32_e64 v89, s[8:9], 0, v121, s[8:9]
	global_store_short v[88:89], v92, off offset:512
	v_mul_f32_e32 v88, v119, v94
	v_cvt_pk_bf16_f32 v92, v88, s0
	v_add_co_u32_e64 v88, s[8:9], s2, v120
	s_mov_b32 s2, 0x5b000
	s_nop 0
	v_addc_co_u32_e64 v89, s[8:9], 0, v121, s[8:9]
	global_store_short v[88:89], v92, off offset:1024
	v_mul_f32_e32 v88, v119, v95
	v_cvt_pk_bf16_f32 v92, v88, s0
	v_add_co_u32_e64 v88, s[8:9], s2, v120
	v_lshlrev_b32_e32 v96, 16, v90
	s_nop 0
	v_addc_co_u32_e64 v89, s[8:9], 0, v121, s[8:9]
	global_store_short v[88:89], v92, off offset:1536
	v_mul_f32_e32 v88, v119, v96
	s_mov_b32 s2, 0x5d000
	v_cvt_pk_bf16_f32 v92, v88, s0
	v_add_co_u32_e64 v88, s[8:9], s2, v120
	v_and_b32_e32 v90, 0xffff0000, v90
	s_nop 0
	v_addc_co_u32_e64 v89, s[8:9], 0, v121, s[8:9]
	global_store_short v[88:89], v92, off offset:2048
	v_mul_f32_e32 v88, v119, v90
	s_mov_b32 s2, 0x5f000
	v_cvt_pk_bf16_f32 v90, v88, s0
	v_add_co_u32_e64 v88, s[8:9], s2, v120
	v_lshlrev_b32_e32 v97, 16, v91
	s_nop 0
	v_addc_co_u32_e64 v89, s[8:9], 0, v121, s[8:9]
	global_store_short v[88:89], v90, off offset:2560
	v_mul_f32_e32 v88, v119, v97
	s_mov_b32 s2, 0x61000
	v_cvt_pk_bf16_f32 v90, v88, s0
	v_add_co_u32_e64 v88, s[8:9], s2, v120
	v_and_b32_e32 v91, 0xffff0000, v91
	s_nop 0
	v_addc_co_u32_e64 v89, s[8:9], 0, v121, s[8:9]
	global_store_short v[88:89], v90, off offset:3072
	v_mul_f32_e32 v88, v119, v91
	s_mov_b32 s2, 0x63000
	v_cvt_pk_bf16_f32 v90, v88, s0
	v_add_co_u32_e64 v88, s[8:9], s2, v120
	s_mov_b32 s2, 0x66000
	s_nop 0
	v_addc_co_u32_e64 v89, s[8:9], 0, v121, s[8:9]
	global_store_short v[88:89], v90, off offset:3584
	v_lshlrev_b32_e32 v88, 16, v84
	v_and_b32_e32 v89, 0xffff0000, v84
	v_mul_f32_e32 v84, v119, v88
	v_cvt_pk_bf16_f32 v88, v84, s0
	v_add_co_u32_e64 v84, s[8:9], s2, v120
	v_lshlrev_b32_e32 v90, 16, v85
	v_and_b32_e32 v91, 0xffff0000, v85
	v_addc_co_u32_e64 v85, s[8:9], 0, v121, s[8:9]
	global_store_short v[84:85], v88, off
	v_mul_f32_e32 v84, v119, v89
	s_mov_b32 s2, 0x68000
	v_cvt_pk_bf16_f32 v88, v84, s0
	v_add_co_u32_e64 v84, s[8:9], s2, v120
	s_mov_b32 s2, 0x6a000
	s_nop 0
	v_addc_co_u32_e64 v85, s[8:9], 0, v121, s[8:9]
	global_store_short v[84:85], v88, off offset:512
	v_mul_f32_e32 v84, v119, v90
	v_cvt_pk_bf16_f32 v88, v84, s0
	v_add_co_u32_e64 v84, s[8:9], s2, v120
	s_mov_b32 s2, 0x6c000
	s_nop 0
	v_addc_co_u32_e64 v85, s[8:9], 0, v121, s[8:9]
	global_store_short v[84:85], v88, off offset:1024
	v_mul_f32_e32 v84, v119, v91
	v_cvt_pk_bf16_f32 v88, v84, s0
	v_add_co_u32_e64 v84, s[8:9], s2, v120
	v_lshlrev_b32_e32 v92, 16, v86
	s_nop 0
	v_addc_co_u32_e64 v85, s[8:9], 0, v121, s[8:9]
	global_store_short v[84:85], v88, off offset:1536
	v_mul_f32_e32 v84, v119, v92
	s_mov_b32 s2, 0x6e000
	v_cvt_pk_bf16_f32 v88, v84, s0
	v_add_co_u32_e64 v84, s[8:9], s2, v120
	v_and_b32_e32 v86, 0xffff0000, v86
	s_nop 0
	v_addc_co_u32_e64 v85, s[8:9], 0, v121, s[8:9]
	global_store_short v[84:85], v88, off offset:2048
	v_mul_f32_e32 v84, v119, v86
	s_mov_b32 s2, 0x70000
	v_cvt_pk_bf16_f32 v86, v84, s0
	v_add_co_u32_e64 v84, s[8:9], s2, v120
	v_lshlrev_b32_e32 v93, 16, v87
	s_nop 0
	v_addc_co_u32_e64 v85, s[8:9], 0, v121, s[8:9]
	global_store_short v[84:85], v86, off offset:2560
	v_mul_f32_e32 v84, v119, v93
	s_mov_b32 s2, 0x72000
	v_cvt_pk_bf16_f32 v86, v84, s0
	v_add_co_u32_e64 v84, s[8:9], s2, v120
	v_and_b32_e32 v87, 0xffff0000, v87
	s_nop 0
	v_addc_co_u32_e64 v85, s[8:9], 0, v121, s[8:9]
	global_store_short v[84:85], v86, off offset:3072
	v_mul_f32_e32 v84, v119, v87
	s_mov_b32 s2, 0x74000
	v_cvt_pk_bf16_f32 v86, v84, s0
	v_add_co_u32_e64 v84, s[8:9], s2, v120
	s_mov_b32 s2, 0x77000
	s_nop 0
	v_addc_co_u32_e64 v85, s[8:9], 0, v121, s[8:9]
	global_store_short v[84:85], v86, off offset:3584
	v_lshlrev_b32_e32 v84, 16, v80
	v_and_b32_e32 v85, 0xffff0000, v80
	v_mul_f32_e32 v80, v119, v84
	v_cvt_pk_bf16_f32 v84, v80, s0
	v_add_co_u32_e64 v80, s[8:9], s2, v120
	v_lshlrev_b32_e32 v86, 16, v81
	v_and_b32_e32 v87, 0xffff0000, v81
	v_addc_co_u32_e64 v81, s[8:9], 0, v121, s[8:9]
	global_store_short v[80:81], v84, off
	v_mul_f32_e32 v80, v119, v85
	s_mov_b32 s2, 0x79000
	v_cvt_pk_bf16_f32 v84, v80, s0
	v_add_co_u32_e64 v80, s[8:9], s2, v120
	s_mov_b32 s2, 0x7b000
	s_nop 0
	v_addc_co_u32_e64 v81, s[8:9], 0, v121, s[8:9]
	global_store_short v[80:81], v84, off offset:512
	v_mul_f32_e32 v80, v119, v86
	v_cvt_pk_bf16_f32 v84, v80, s0
	v_add_co_u32_e64 v80, s[8:9], s2, v120
	s_mov_b32 s2, 0x7d000
	s_nop 0
	v_addc_co_u32_e64 v81, s[8:9], 0, v121, s[8:9]
	global_store_short v[80:81], v84, off offset:1024
	v_mul_f32_e32 v80, v119, v87
	v_cvt_pk_bf16_f32 v84, v80, s0
	v_add_co_u32_e64 v80, s[8:9], s2, v120
	v_lshlrev_b32_e32 v88, 16, v82
	s_nop 0
	v_addc_co_u32_e64 v81, s[8:9], 0, v121, s[8:9]
	global_store_short v[80:81], v84, off offset:1536
	v_mul_f32_e32 v80, v119, v88
	s_mov_b32 s2, 0x7f000
	v_cvt_pk_bf16_f32 v84, v80, s0
	v_add_co_u32_e64 v80, s[8:9], s2, v120
	v_and_b32_e32 v82, 0xffff0000, v82
	s_nop 0
	v_addc_co_u32_e64 v81, s[8:9], 0, v121, s[8:9]
	global_store_short v[80:81], v84, off offset:2048
	v_mul_f32_e32 v80, v119, v82
	s_mov_b32 s2, 0x81000
	v_cvt_pk_bf16_f32 v82, v80, s0
	v_add_co_u32_e64 v80, s[8:9], s2, v120
; DI unsigned cvtpk(float lo, float hi) { f32x2_t v = {lo, hi}; bf16x2_t b = __builtin_convertvector(v, bf16x2_t); return __builtin_bit_cast(unsigned, b); }
; DI bf16_t f2bf(float f) { return (bf16_t)(cvtpk(f, f) & 0xffffu); }
; #define UNPK(W_, E_) const float E_[8] = {bflo((W_).x), bfhi((W_).x), bflo((W_).y), bfhi((W_).y), bflo((W_).z), bfhi((W_).z), bflo((W_).w), bfhi((W_).w)}
; #define SSQ8(W_, ACC_) do { UNPK(W_, e_); ACC_ += (e_[0] * e_[0] + e_[1] * e_[1]) + (e_[2] * e_[2] + e_[3] * e_[3]) + (e_[4] * e_[4] + e_[5] * e_[5]) + (e_[6] * e_[6] + e_[7] * e_[7]); } while (0)
; DI void phase_mla_fin(ArgsP a, int tb_, int l, char* shm, int vcu, int G) {
;     ...
;               for (int i = 0; i < 8; ++i) { UNPK(vw[i], e);
; #pragma unroll
;                   for (int j = 0; j < 8; ++j) vo[(size_t)(8 * i + j) * KVLEN] = f2bf(e[j] * rkv); } }
; #pragma unroll
;             for (int i = 0; i < 8; ++i) SSQ8(w[i], ss);
; #pragma unroll
;             for (int i = 0; i < 4; ++i) SSQ8(krp[i], sk);
;             const float rn = rsqrtf((ss * rkv * rkv + sk) * (1.f / 96.f) + EPS);
;             u32x4* o = (u32x4*)(Kb + (bh * KVLEN + pos) * 96);
; #pragma unroll
;             for (int i = 0; i < 8; ++i) { UNPK(w[i], e); const float sc = rn * rkv; u32x4 ow;
;                 ow.x = cvtpk(e[0] * sc * gkn[8 * i], e[1] * sc * gkn[8 * i + 1]); ow.y = cvtpk(e[2] * sc * gkn[8 * i + 2], e[3] * sc * gkn[8 * i + 3]);
;                 ow.z = cvtpk(e[4] * sc * gkn[8 * i + 4], e[5] * sc * gkn[8 * i + 5]); ow.w = cvtpk(e[6] * sc * gkn[8 * i + 6], e[7] * sc * gkn[8 * i + 7]); o[i] = ow; }
;             float cs[16], sn[16];
; #pragma unroll
;             for (int i = 0; i < 4; ++i) { cs[4 * i] = lat ? rc[i].x : 1.f; cs[4 * i + 1] = lat ? rc[i].y : 1.f; cs[4 * i + 2] = lat ? rc[i].z : 1.f; cs[4 * i + 3] = lat ? rc[i].w : 1.f;
;                 sn[4 * i] = lat ? rs[i].x : 0.f; sn[4 * i + 1] = lat ? rs[i].y : 0.f; sn[4 * i + 2] = lat ? rs[i].z : 0.f; sn[4 * i + 3] = lat ? rs[i].w : 0.f; }
;             float xr[32];
; #pragma unroll
;             for (int i = 0; i < 4; ++i) { UNPK(krp[i], e);
; #pragma unroll
;                 for (int j = 0; j < 8; ++j) xr[8 * i + j] = e[j] * rn * gkn[64 + 8 * i + j]; }
	v_lshlrev_b32_e32 v89, 16, v83
	s_nop 0
	v_addc_co_u32_e64 v81, s[8:9], 0, v121, s[8:9]
	global_store_short v[80:81], v82, off offset:2560
	v_mul_f32_e32 v80, v119, v89
	s_mov_b32 s2, 0x83000
	v_cvt_pk_bf16_f32 v82, v80, s0
	v_add_co_u32_e64 v80, s[8:9], s2, v120
	v_and_b32_e32 v83, 0xffff0000, v83
	s_nop 0
	v_addc_co_u32_e64 v81, s[8:9], 0, v121, s[8:9]
	global_store_short v[80:81], v82, off offset:3072
	v_mul_f32_e32 v80, v119, v83
	s_mov_b32 s2, 0x85000
	v_cvt_pk_bf16_f32 v82, v80, s0
	v_add_co_u32_e64 v80, s[8:9], s2, v120
	v_and_b32_e32 v120, 0xffff0000, v76
	s_nop 0
	v_addc_co_u32_e64 v81, s[8:9], 0, v121, s[8:9]
	v_and_b32_e32 v121, 0xffff0000, v77
	v_lshlrev_b32_e32 v123, 16, v77
	v_lshlrev_b32_e32 v122, 16, v76
	v_pk_mul_f32 v[76:77], v[120:121], v[120:121]
	v_and_b32_e32 v111, 0xffff0000, v79
	v_and_b32_e32 v110, 0xffff0000, v78
	v_pk_fma_f32 v[76:77], v[122:123], v[122:123], v[76:77]
	v_lshlrev_b32_e32 v125, 16, v79
	v_lshlrev_b32_e32 v124, 16, v78
	v_pk_mul_f32 v[78:79], v[110:111], v[110:111]
	v_add_f32_e32 v76, v76, v77
	v_pk_fma_f32 v[78:79], v[124:125], v[124:125], v[78:79]
	v_and_b32_e32 v107, 0xffff0000, v69
	v_add_f32_e32 v76, v78, v76
	v_and_b32_e32 v126, 0xffff0000, v70
	v_pk_add_f32 v[128:129], v[78:79], v[76:77] op_sel_hi:[1,0]
	v_lshlrev_b32_e32 v106, 16, v69
	v_mul_f32_e32 v76, v107, v107
	v_lshlrev_b32_e32 v109, 16, v68
	v_lshlrev_b32_e32 v108, 16, v70
	v_pk_mul_f32 v[68:69], v[126:127], v[126:127]
	v_pk_fma_f32 v[76:77], v[106:107], v[106:107], v[76:77] op_sel_hi:[1,1,0]
	v_pk_fma_f32 v[68:69], v[108:109], v[108:109], v[68:69]
	v_lshlrev_b32_e32 v104, 16, v71
	v_pk_add_f32 v[76:77], v[68:69], v[76:77] op_sel:[1,0] op_sel_hi:[0,1]
	v_pk_add_f32 v[134:135], v[68:69], v[76:77]
	v_and_b32_e32 v105, 0xffff0000, v71
	v_mul_f32_e32 v68, v104, v104
	v_and_b32_e32 v101, 0xffff0000, v73
	v_pk_fma_f32 v[136:137], v[104:105], v[104:105], v[68:69] op_sel_hi:[1,1,0]
	v_lshlrev_b32_e32 v100, 16, v73
	v_mul_f32_e32 v68, v101, v101
	v_lshlrev_b32_e32 v103, 16, v72
	v_lshlrev_b32_e32 v102, 16, v74
	v_pk_mul_f32 v[70:71], v[130:131], v[130:131]
	v_pk_fma_f32 v[68:69], v[100:101], v[100:101], v[68:69] op_sel_hi:[1,1,0]
	v_pk_fma_f32 v[70:71], v[102:103], v[102:103], v[70:71]
	v_lshlrev_b32_e32 v98, 16, v75
	v_pk_add_f32 v[68:69], v[70:71], v[68:69] op_sel:[1,0] op_sel_hi:[0,1]
	v_pk_add_f32 v[138:139], v[70:71], v[68:69]
	v_and_b32_e32 v99, 0xffff0000, v75
	v_mul_f32_e32 v68, v98, v98
	v_and_b32_e32 v95, 0xffff0000, v65
	v_pk_fma_f32 v[144:145], v[98:99], v[98:99], v[68:69] op_sel_hi:[1,1,0]
	v_lshlrev_b32_e32 v94, 16, v65
	v_mul_f32_e32 v68, v95, v95
	v_lshlrev_b32_e32 v97, 16, v64
	v_lshlrev_b32_e32 v96, 16, v66
	v_pk_mul_f32 v[64:65], v[132:133], v[132:133]
	v_pk_fma_f32 v[68:69], v[94:95], v[94:95], v[68:69] op_sel_hi:[1,1,0]
	v_pk_fma_f32 v[64:65], v[96:97], v[96:97], v[64:65]
	v_lshlrev_b32_e32 v92, 16, v67
	v_pk_add_f32 v[68:69], v[64:65], v[68:69] op_sel:[1,0] op_sel_hi:[0,1]
	v_pk_add_f32 v[146:147], v[64:65], v[68:69]
	v_and_b32_e32 v93, 0xffff0000, v67
	v_mul_f32_e32 v64, v92, v92
	s_movk_i32 s0, 0x1100
	v_lshlrev_b32_e32 v84, 16, v63
	v_and_b32_e32 v85, 0xffff0000, v63
	v_lshlrev_b32_e32 v74, 16, v59
	v_and_b32_e32 v75, 0xffff0000, v59
	v_and_b32_e32 v59, 0xffff0000, v48
	v_and_b32_e32 v63, 0xffff0000, v49
	global_store_short v[80:81], v82, off offset:3584
	v_pk_fma_f32 v[148:149], v[92:93], v[92:93], v[64:65] op_sel_hi:[1,1,0]
	v_mad_i64_i32 v[64:65], s[4:5], v142, s0, v[188:189]
	v_mov_b64_e32 v[66:67], s[18:19]
	s_movk_i32 s0, 0xc0
	v_lshlrev_b32_e32 v78, 16, v62
	v_and_b32_e32 v79, 0xffff0000, v62
	v_lshlrev_b32_e32 v70, 16, v58
	v_and_b32_e32 v71, 0xffff0000, v58
	v_lshlrev_b32_e32 v76, 16, v52
	v_and_b32_e32 v77, 0xffff0000, v52
	v_lshlrev_b32_e32 v58, 16, v48
	v_lshlrev_b32_e32 v82, 16, v53
	v_and_b32_e32 v83, 0xffff0000, v53
	v_lshlrev_b32_e32 v62, 16, v49
	v_mov_b32_e32 v52, v59
	v_mov_b32_e32 v53, v63
	v_mad_u64_u32 v[68:69], s[4:5], v64, s0, v[66:67]
	v_lshlrev_b32_e32 v66, 16, v60
	v_and_b32_e32 v67, 0xffff0000, v60
	v_lshlrev_b32_e32 v72, 16, v61
	v_and_b32_e32 v73, 0xffff0000, v61
	v_lshlrev_b32_e32 v60, 16, v57
	v_and_b32_e32 v61, 0xffff0000, v57
	v_mov_b32_e32 v48, v58
	v_mov_b32_e32 v49, v62
	v_pk_mul_f32 v[52:53], v[52:53], v[52:53]
	v_and_b32_e32 v81, 0xffff0000, v50
	v_and_b32_e32 v57, 0xffff0000, v51
	v_mad_i32_i24 v69, v65, s0, v69
	v_lshlrev_b32_e32 v64, 16, v56
	v_and_b32_e32 v65, 0xffff0000, v56
	v_pk_fma_f32 v[140:141], v[48:49], v[48:49], v[52:53]
	v_lshlrev_b32_e32 v80, 16, v50
	v_cndmask_b32_e64 v53, 0, v5, s[6:7]
	v_cndmask_b32_e64 v52, 0, v4, s[6:7]
	v_lshlrev_b32_e32 v56, 16, v51
	v_mov_b32_e32 v4, v57
	v_mov_b32_e32 v5, v81
	v_cndmask_b32_e64 v49, 1.0, v1, s[6:7]
	v_cndmask_b32_e64 v48, 1.0, v0, s[6:7]
	v_mov_b32_e32 v0, v56
	v_mov_b32_e32 v1, v80
	v_pk_mul_f32 v[4:5], v[4:5], v[4:5]
	v_mov_b64_e32 v[88:89], s[34:35]
	v_lshlrev_b32_e32 v86, 16, v54
	v_and_b32_e32 v87, 0xffff0000, v54
	v_lshlrev_b32_e32 v90, 16, v55
	v_and_b32_e32 v91, 0xffff0000, v55
	v_pk_fma_f32 v[152:153], v[0:1], v[0:1], v[4:5]
	v_cndmask_b32_e64 v51, 1.0, v3, s[6:7]
	v_cndmask_b32_e64 v50, 1.0, v2, s[6:7]
	v_cndmask_b32_e64 v55, 0, v7, s[6:7]
	v_cndmask_b32_e64 v54, 0, v6, s[6:7]
	flat_load_dwordx4 v[0:3], v[88:89] offset:16
	flat_load_dwordx4 v[4:7], v[88:89]
	v_pk_mul_f32 v[160:161], v[72:73], v[72:73]
	v_pk_mul_f32 v[162:163], v[78:79], v[78:79]
	v_mov_b32_e32 v136, v160
	v_pk_mov_b32 v[44:45], v[160:161], v[134:135] op_sel:[1,0]
	v_mov_b32_e32 v144, v162
	v_pk_add_f32 v[44:45], v[136:137], v[44:45]
	v_pk_mov_b32 v[46:47], v[162:163], v[138:139] op_sel:[1,0]
	v_and_b32_e32 v137, 0xffff0000, v43
; DI unsigned cvtpk(float lo, float hi) { f32x2_t v = {lo, hi}; bf16x2_t b = __builtin_convertvector(v, bf16x2_t); return __builtin_bit_cast(unsigned, b); }
; #define UNPK(W_, E_) const float E_[8] = {bflo((W_).x), bfhi((W_).x), bflo((W_).y), bfhi((W_).y), bflo((W_).z), bfhi((W_).z), bflo((W_).w), bfhi((W_).w)}
; #define SSQ8(W_, ACC_) do { UNPK(W_, e_); ACC_ += (e_[0] * e_[0] + e_[1] * e_[1]) + (e_[2] * e_[2] + e_[3] * e_[3]) + (e_[4] * e_[4] + e_[5] * e_[5]) + (e_[6] * e_[6] + e_[7] * e_[7]); } while (0)
; DI void phase_mla_fin(ArgsP a, int tb_, int l, char* shm, int vcu, int G) {
;     ...
; #pragma unroll
;             for (int i = 0; i < 8; ++i) SSQ8(w[i], ss);
; #pragma unroll
;             for (int i = 0; i < 4; ++i) SSQ8(krp[i], sk);
;             const float rn = rsqrtf((ss * rkv * rkv + sk) * (1.f / 96.f) + EPS);
;             u32x4* o = (u32x4*)(Kb + (bh * KVLEN + pos) * 96);
; #pragma unroll
;             for (int i = 0; i < 8; ++i) { UNPK(w[i], e); const float sc = rn * rkv; u32x4 ow;
;                 ow.x = cvtpk(e[0] * sc * gkn[8 * i], e[1] * sc * gkn[8 * i + 1]); ow.y = cvtpk(e[2] * sc * gkn[8 * i + 2], e[3] * sc * gkn[8 * i + 3]);
	v_pk_add_f32 v[46:47], v[144:145], v[46:47]
	v_lshlrev_b32_e32 v136, 16, v43
	v_mov_b32_e32 v144, v151
	v_mov_b32_e32 v145, v137
	v_mov_b32_e32 v138, v150
	v_mov_b32_e32 v139, v136
	v_pk_mul_f32 v[144:145], v[144:145], v[144:145]
	v_pk_mul_f32 v[164:165], v[84:85], v[84:85]
	v_pk_fma_f32 v[138:139], v[138:139], v[138:139], v[144:145]
	v_and_b32_e32 v145, 0xffff0000, v42
	v_pk_mov_b32 v[134:135], v[164:165], v[146:147] op_sel:[1,0]
	v_lshlrev_b32_e32 v144, 16, v42
	v_mov_b32_e32 v146, v155
	v_mov_b32_e32 v147, v145
	v_mov_b32_e32 v42, v154
	v_mov_b32_e32 v43, v144
	v_pk_mul_f32 v[146:147], v[146:147], v[146:147]
	v_mov_b32_e32 v148, v164
	v_pk_fma_f32 v[42:43], v[42:43], v[42:43], v[146:147]
	v_and_b32_e32 v147, 0xffff0000, v41
	v_lshlrev_b32_e32 v146, 16, v41
	v_mov_b32_e32 v160, v157
	v_mov_b32_e32 v161, v147
	v_pk_add_f32 v[134:135], v[148:149], v[134:135]
	v_mov_b32_e32 v148, v156
	v_mov_b32_e32 v149, v146
	v_pk_mul_f32 v[160:161], v[160:161], v[160:161]
	v_mov_b32_e32 v162, v158
	v_pk_fma_f32 v[148:149], v[148:149], v[148:149], v[160:161]
	v_and_b32_e32 v161, 0xffff0000, v40
	v_lshlrev_b32_e32 v160, 16, v40
	v_mov_b32_e32 v40, v159
	v_mov_b32_e32 v41, v161
	v_pk_mul_f32 v[40:41], v[40:41], v[40:41]
	v_mov_b32_e32 v163, v160
	v_pk_fma_f32 v[40:41], v[162:163], v[162:163], v[40:41]
	v_pk_mul_f32 v[142:143], v[66:67], v[66:67]
	v_pk_add_f32 v[40:41], v[40:41], v[148:149]
	v_mov_b32_e32 v128, v143
	v_pk_add_f32 v[40:41], v[42:43], v[40:41]
	v_mov_b32_e32 v148, v83
	v_pk_add_f32 v[40:41], v[138:139], v[40:41]
	v_mov_b32_e32 v138, v124
	v_pk_add_f32 v[40:41], v[40:41], v[40:41] op_sel_hi:[0,1]
	v_mov_b32_e32 v143, v41
	v_pk_add_f32 v[40:41], v[142:143], v[128:129]
	v_mov_b32_e32 v142, v122
	v_pk_add_f32 v[40:41], v[40:41], v[44:45]
	v_mov_b32_e32 v44, v74
	v_pk_add_f32 v[40:41], v[40:41], v[46:47]
	v_mov_b32_e32 v46, v75
	v_pk_add_f32 v[42:43], v[40:41], v[134:135]
	v_and_b32_e32 v41, 0xffff0000, v39
	v_lshlrev_b32_e32 v40, 16, v39
	v_mov_b32_e32 v47, v41
	v_mov_b32_e32 v45, v40
	v_pk_mul_f32 v[46:47], v[46:47], v[46:47]
	v_mov_b32_e32 v143, v120
	v_pk_fma_f32 v[44:45], v[44:45], v[44:45], v[46:47]
	v_and_b32_e32 v47, 0xffff0000, v38
	v_mov_b32_e32 v120, v123
	v_lshlrev_b32_e32 v46, 16, v38
	v_mov_b32_e32 v122, v71
	v_mov_b32_e32 v123, v47
	v_mov_b32_e32 v38, v70
	v_mov_b32_e32 v39, v46
	v_pk_mul_f32 v[122:123], v[122:123], v[122:123]
	v_mov_b32_e32 v128, v103
	v_pk_fma_f32 v[38:39], v[38:39], v[38:39], v[122:123]
	v_and_b32_e32 v123, 0xffff0000, v37
	v_mov_b32_e32 v129, v131
	v_mov_b32_e32 v103, v130
	v_lshlrev_b32_e32 v122, 16, v37
	v_mov_b32_e32 v130, v61
	v_mov_b32_e32 v131, v123
	v_mov_b32_e32 v134, v109
	v_mov_b32_e32 v135, v127
	v_mov_b32_e32 v109, v126
	v_mov_b32_e32 v126, v60
	v_mov_b32_e32 v127, v122
	v_pk_mul_f32 v[130:131], v[130:131], v[130:131]
	v_mov_b32_e32 v139, v110
	v_pk_fma_f32 v[130:131], v[126:127], v[126:127], v[130:131]
	v_and_b32_e32 v127, 0xffff0000, v36
	v_mov_b32_e32 v110, v125
	v_mov_b32_e32 v124, v97
	v_mov_b32_e32 v125, v133
	v_mov_b32_e32 v97, v132
	v_lshlrev_b32_e32 v126, 16, v36
	v_mov_b32_e32 v132, v65
	v_mov_b32_e32 v133, v127
	v_mov_b32_e32 v36, v64
	v_mov_b32_e32 v37, v126
	v_pk_mul_f32 v[132:133], v[132:133], v[132:133]
	v_mov_b32_e32 v162, v77
	v_pk_fma_f32 v[36:37], v[36:37], v[36:37], v[132:133]
	s_nop 0
	v_pk_add_f32 v[36:37], v[36:37], v[130:131]
	s_nop 0
	v_pk_add_f32 v[36:37], v[38:39], v[36:37]
	v_mov_b32_e32 v38, v90
	v_pk_add_f32 v[36:37], v[44:45], v[36:37]
	v_mov_b32_e32 v44, v82
	v_pk_add_f32 v[130:131], v[42:43], v[36:37]
	v_and_b32_e32 v37, 0xffff0000, v35
	v_lshlrev_b32_e32 v36, 16, v35
	v_mov_b32_e32 v42, v91
	v_mov_b32_e32 v43, v37
	v_mov_b32_e32 v39, v36
	v_pk_mul_f32 v[42:43], v[42:43], v[42:43]
	s_nop 0
	v_pk_fma_f32 v[132:133], v[38:39], v[38:39], v[42:43]
	v_and_b32_e32 v39, 0xffff0000, v34
	v_lshlrev_b32_e32 v38, 16, v34
	v_mov_b32_e32 v42, v87
	v_mov_b32_e32 v43, v39
	v_mov_b32_e32 v34, v86
	v_mov_b32_e32 v35, v38
	v_pk_mul_f32 v[42:43], v[42:43], v[42:43]
	s_nop 0
	v_pk_fma_f32 v[34:35], v[34:35], v[34:35], v[42:43]
	v_and_b32_e32 v43, 0xffff0000, v33
	v_lshlrev_b32_e32 v42, 16, v33
	v_mov_b32_e32 v149, v43
	v_mov_b32_e32 v45, v42
	v_pk_mul_f32 v[148:149], v[148:149], v[148:149]
	s_nop 0
	v_pk_fma_f32 v[148:149], v[44:45], v[44:45], v[148:149]
	v_and_b32_e32 v45, 0xffff0000, v32
	v_lshlrev_b32_e32 v44, 16, v32
	v_mov_b32_e32 v163, v45
	v_mov_b32_e32 v32, v76
	v_mov_b32_e32 v33, v44
	v_pk_mul_f32 v[162:163], v[162:163], v[162:163]
	s_nop 0
	v_pk_fma_f32 v[32:33], v[32:33], v[32:33], v[162:163]
	s_nop 0
	v_pk_add_f32 v[32:33], v[32:33], v[148:149]
	s_nop 0
	v_pk_add_f32 v[32:33], v[34:35], v[32:33]
	v_add_f32_e32 v34, v140, v141
	v_pk_add_f32 v[32:33], v[132:133], v[32:33]
	v_add_f32_e32 v34, v153, v34
	v_pk_add_f32 v[32:33], v[130:131], v[32:33]
	v_add_f32_e32 v34, v152, v34
	v_mul_f32_e32 v33, v33, v119
	v_add_f32_e32 v32, v32, v34
	v_fmac_f32_e32 v32, v119, v33
	v_fmamk_f32 v32, v32, 0x3c2aaaab, v230
	v_cmp_gt_f32_e64 s[8:9], s76, v32
	v_mul_f32_e32 v33, 0x4b800000, v32
	s_nop 0
	v_cndmask_b32_e64 v32, v32, v33, s[8:9]
	v_rsq_f32_e32 v32, v32
	s_nop 0
	v_mul_f32_e32 v33, 0x45800000, v32
	v_cndmask_b32_e64 v32, v32, v33, s[8:9]
	v_mul_f32_e32 v34, v119, v32
	v_pk_mul_f32 v[130:131], v[34:35], v[158:159] op_sel_hi:[0,1]
	s_waitcnt vmcnt(0) lgkmcnt(0)
; DI unsigned cvtpk(float lo, float hi) { f32x2_t v = {lo, hi}; bf16x2_t b = __builtin_convertvector(v, bf16x2_t); return __builtin_bit_cast(unsigned, b); }
; #define UNPK(W_, E_) const float E_[8] = {bflo((W_).x), bfhi((W_).x), bflo((W_).y), bfhi((W_).y), bflo((W_).z), bfhi((W_).z), bflo((W_).w), bfhi((W_).w)}
; DI void phase_mla_fin(ArgsP a, int tb_, int l, char* shm, int vcu, int G) {
;     ...
;             u32x4* o = (u32x4*)(Kb + (bh * KVLEN + pos) * 96);
; #pragma unroll
;             for (int i = 0; i < 8; ++i) { UNPK(w[i], e); const float sc = rn * rkv; u32x4 ow;
;                 ow.x = cvtpk(e[0] * sc * gkn[8 * i], e[1] * sc * gkn[8 * i + 1]); ow.y = cvtpk(e[2] * sc * gkn[8 * i + 2], e[3] * sc * gkn[8 * i + 3]);
;                 ow.z = cvtpk(e[4] * sc * gkn[8 * i + 4], e[5] * sc * gkn[8 * i + 5]); ow.w = cvtpk(e[6] * sc * gkn[8 * i + 6], e[7] * sc * gkn[8 * i + 7]); o[i] = ow; }
;             float cs[16], sn[16];
; #pragma unroll
;             for (int i = 0; i < 4; ++i) { cs[4 * i] = lat ? rc[i].x : 1.f; cs[4 * i + 1] = lat ? rc[i].y : 1.f; cs[4 * i + 2] = lat ? rc[i].z : 1.f; cs[4 * i + 3] = lat ? rc[i].w : 1.f;
;                 sn[4 * i] = lat ? rs[i].x : 0.f; sn[4 * i + 1] = lat ? rs[i].y : 0.f; sn[4 * i + 2] = lat ? rs[i].z : 0.f; sn[4 * i + 3] = lat ? rs[i].w : 0.f; }
;             float xr[32];
; #pragma unroll
;             for (int i = 0; i < 4; ++i) { UNPK(krp[i], e);
; #pragma unroll
;                 for (int j = 0; j < 8; ++j) xr[8 * i + j] = e[j] * rn * gkn[64 + 8 * i + j]; }
	v_pk_mul_f32 v[4:5], v[130:131], v[4:5]
	v_pk_mul_f32 v[130:131], v[34:35], v[156:157] op_sel_hi:[0,1]
	v_pk_mul_f32 v[6:7], v[130:131], v[6:7]
	v_cvt_pk_bf16_f32 v4, v4, v5
	v_cvt_pk_bf16_f32 v5, v6, v7
	v_pk_mul_f32 v[6:7], v[34:35], v[154:155] op_sel_hi:[0,1]
	v_pk_mul_f32 v[0:1], v[6:7], v[0:1]
	v_pk_mul_f32 v[58:59], v[32:33], v[58:59] op_sel_hi:[0,1]
	v_cvt_pk_bf16_f32 v6, v0, v1
	v_pk_mul_f32 v[0:1], v[34:35], v[150:151] op_sel_hi:[0,1]
	v_pk_mul_f32 v[0:1], v[0:1], v[2:3]
	s_nop 0
	v_cvt_pk_bf16_f32 v7, v0, v1
	global_store_dwordx4 v[68:69], v[4:7], off
	flat_load_dwordx4 v[0:3], v[88:89] offset:32
	s_nop 0
	v_pk_mul_f32 v[4:5], v[34:35], v[160:161] op_sel_hi:[0,1]
	v_pk_mul_f32 v[6:7], v[34:35], v[144:145] op_sel_hi:[0,1]
	s_waitcnt vmcnt(0) lgkmcnt(0)
	v_pk_mul_f32 v[0:1], v[4:5], v[0:1]
	v_pk_mul_f32 v[4:5], v[34:35], v[146:147] op_sel_hi:[0,1]
	v_pk_mul_f32 v[2:3], v[4:5], v[2:3]
	v_cvt_pk_bf16_f32 v0, v0, v1
	v_cvt_pk_bf16_f32 v1, v2, v3
	flat_load_dwordx4 v[2:5], v[88:89] offset:48
	s_waitcnt vmcnt(0) lgkmcnt(0)
	v_pk_mul_f32 v[2:3], v[6:7], v[2:3]
	v_pk_mul_f32 v[6:7], v[34:35], v[136:137] op_sel_hi:[0,1]
	v_pk_mul_f32 v[4:5], v[6:7], v[4:5]
	v_cvt_pk_bf16_f32 v2, v2, v3
	v_cvt_pk_bf16_f32 v3, v4, v5
	global_store_dwordx4 v[68:69], v[0:3], off offset:16
	flat_load_dwordx4 v[0:3], v[88:89] offset:64
	v_pk_mul_f32 v[4:5], v[34:35], v[142:143] op_sel_hi:[0,1]
	v_pk_mul_f32 v[6:7], v[34:35], v[138:139] op_sel_hi:[0,1]
	s_waitcnt vmcnt(0) lgkmcnt(0)
	v_pk_mul_f32 v[0:1], v[4:5], v[0:1]
	v_pk_mul_f32 v[4:5], v[34:35], v[120:121] op_sel_hi:[0,1]
	v_pk_mul_f32 v[2:3], v[4:5], v[2:3]
	v_cvt_pk_bf16_f32 v0, v0, v1
	v_cvt_pk_bf16_f32 v1, v2, v3
	flat_load_dwordx4 v[2:5], v[88:89] offset:80
	s_waitcnt vmcnt(0) lgkmcnt(0)
	v_pk_mul_f32 v[2:3], v[6:7], v[2:3]
	v_pk_mul_f32 v[6:7], v[34:35], v[110:111] op_sel_hi:[0,1]
	v_pk_mul_f32 v[4:5], v[6:7], v[4:5]
	v_cvt_pk_bf16_f32 v2, v2, v3
	v_cvt_pk_bf16_f32 v3, v4, v5
	global_store_dwordx4 v[68:69], v[0:3], off offset:32
	flat_load_dwordx4 v[0:3], v[88:89] offset:96
	v_pk_mul_f32 v[4:5], v[34:35], v[134:135] op_sel_hi:[0,1]
	v_pk_mul_f32 v[6:7], v[34:35], v[108:109] op_sel_hi:[0,1]
	s_waitcnt vmcnt(0) lgkmcnt(0)
	v_pk_mul_f32 v[0:1], v[4:5], v[0:1]
	v_pk_mul_f32 v[4:5], v[34:35], v[106:107] op_sel_hi:[0,1]
	v_pk_mul_f32 v[2:3], v[4:5], v[2:3]
	v_cvt_pk_bf16_f32 v0, v0, v1
	v_cvt_pk_bf16_f32 v1, v2, v3
	flat_load_dwordx4 v[2:5], v[88:89] offset:112
	s_waitcnt vmcnt(0) lgkmcnt(0)
	v_pk_mul_f32 v[2:3], v[6:7], v[2:3]
	v_pk_mul_f32 v[6:7], v[34:35], v[104:105] op_sel_hi:[0,1]
	v_pk_mul_f32 v[4:5], v[6:7], v[4:5]
	v_cvt_pk_bf16_f32 v2, v2, v3
	v_cvt_pk_bf16_f32 v3, v4, v5
	global_store_dwordx4 v[68:69], v[0:3], off offset:48
	flat_load_dwordx4 v[0:3], v[88:89] offset:128
	v_pk_mul_f32 v[4:5], v[34:35], v[128:129] op_sel_hi:[0,1]
	v_pk_mul_f32 v[6:7], v[34:35], v[102:103] op_sel_hi:[0,1]
	s_waitcnt vmcnt(0) lgkmcnt(0)
	v_pk_mul_f32 v[0:1], v[4:5], v[0:1]
	v_pk_mul_f32 v[4:5], v[34:35], v[100:101] op_sel_hi:[0,1]
	v_pk_mul_f32 v[2:3], v[4:5], v[2:3]
	v_cvt_pk_bf16_f32 v0, v0, v1
	v_cvt_pk_bf16_f32 v1, v2, v3
	flat_load_dwordx4 v[2:5], v[88:89] offset:144
	s_waitcnt vmcnt(0) lgkmcnt(0)
	v_pk_mul_f32 v[2:3], v[6:7], v[2:3]
	v_pk_mul_f32 v[6:7], v[34:35], v[98:99] op_sel_hi:[0,1]
	v_pk_mul_f32 v[4:5], v[6:7], v[4:5]
	v_cvt_pk_bf16_f32 v2, v2, v3
	v_cvt_pk_bf16_f32 v3, v4, v5
	global_store_dwordx4 v[68:69], v[0:3], off offset:64
	flat_load_dwordx4 v[0:3], v[88:89] offset:160
	v_pk_mul_f32 v[4:5], v[34:35], v[124:125] op_sel_hi:[0,1]
	v_pk_mul_f32 v[6:7], v[34:35], v[96:97] op_sel_hi:[0,1]
	s_waitcnt vmcnt(0) lgkmcnt(0)
	v_pk_mul_f32 v[0:1], v[4:5], v[0:1]
	v_pk_mul_f32 v[4:5], v[34:35], v[94:95] op_sel_hi:[0,1]
	v_pk_mul_f32 v[2:3], v[4:5], v[2:3]
	v_cvt_pk_bf16_f32 v0, v0, v1
	v_cvt_pk_bf16_f32 v1, v2, v3
	flat_load_dwordx4 v[2:5], v[88:89] offset:176
	s_waitcnt vmcnt(0) lgkmcnt(0)
	v_pk_mul_f32 v[2:3], v[6:7], v[2:3]
	v_pk_mul_f32 v[6:7], v[34:35], v[92:93] op_sel_hi:[0,1]
	v_pk_mul_f32 v[4:5], v[6:7], v[4:5]
	v_cvt_pk_bf16_f32 v2, v2, v3
	v_cvt_pk_bf16_f32 v3, v4, v5
	global_store_dwordx4 v[68:69], v[0:3], off offset:80
	flat_load_dwordx4 v[0:3], v[88:89] offset:192
	v_pk_mul_f32 v[4:5], v[34:35], v[126:127] op_sel_hi:[0,1]
	v_pk_mul_f32 v[6:7], v[34:35], v[46:47] op_sel_hi:[0,1]
	s_waitcnt vmcnt(0) lgkmcnt(0)
	v_pk_mul_f32 v[0:1], v[4:5], v[0:1]
	v_pk_mul_f32 v[4:5], v[34:35], v[122:123] op_sel_hi:[0,1]
	v_pk_mul_f32 v[2:3], v[4:5], v[2:3]
	v_cvt_pk_bf16_f32 v0, v0, v1
	v_cvt_pk_bf16_f32 v1, v2, v3
	flat_load_dwordx4 v[2:5], v[88:89] offset:208
	s_waitcnt vmcnt(0) lgkmcnt(0)
	v_pk_mul_f32 v[2:3], v[6:7], v[2:3]
	v_pk_mul_f32 v[6:7], v[34:35], v[40:41] op_sel_hi:[0,1]
	v_pk_mul_f32 v[4:5], v[6:7], v[4:5]
	v_cvt_pk_bf16_f32 v2, v2, v3
	v_cvt_pk_bf16_f32 v3, v4, v5
	global_store_dwordx4 v[68:69], v[0:3], off offset:96
	flat_load_dwordx4 v[0:3], v[88:89] offset:224
	v_pk_mul_f32 v[4:5], v[34:35], v[44:45] op_sel_hi:[0,1]
	v_pk_mul_f32 v[6:7], v[34:35], v[38:39] op_sel_hi:[0,1]
	s_waitcnt vmcnt(0) lgkmcnt(0)
	v_pk_mul_f32 v[0:1], v[4:5], v[0:1]
	v_pk_mul_f32 v[4:5], v[34:35], v[42:43] op_sel_hi:[0,1]
	v_pk_mul_f32 v[2:3], v[4:5], v[2:3]
	v_cvt_pk_bf16_f32 v0, v0, v1
	v_cvt_pk_bf16_f32 v1, v2, v3
	flat_load_dwordx4 v[2:5], v[88:89] offset:240
	s_waitcnt vmcnt(0) lgkmcnt(0)
	v_pk_mul_f32 v[2:3], v[6:7], v[2:3]
	v_pk_mul_f32 v[6:7], v[34:35], v[36:37] op_sel_hi:[0,1]
	v_pk_mul_f32 v[4:5], v[6:7], v[4:5]
	v_cvt_pk_bf16_f32 v2, v2, v3
	v_cvt_pk_bf16_f32 v3, v4, v5
	global_store_dwordx4 v[68:69], v[0:3], off offset:112
	flat_load_dwordx4 v[2:5], v[88:89] offset:256
	s_nop 0
	flat_load_dwordx4 v[34:37], v[88:89] offset:272
	v_pk_mul_f32 v[0:1], v[32:33], v[66:67] op_sel_hi:[0,1]
	flat_load_dwordx4 v[40:43], v[88:89] offset:304
	flat_load_dwordx4 v[44:47], v[88:89] offset:320
	s_waitcnt vmcnt(0) lgkmcnt(0)
; DI unsigned cvtpk(float lo, float hi) { f32x2_t v = {lo, hi}; bf16x2_t b = __builtin_convertvector(v, bf16x2_t); return __builtin_bit_cast(unsigned, b); }
; #define UNPK(W_, E_) const float E_[8] = {bflo((W_).x), bfhi((W_).x), bflo((W_).y), bfhi((W_).y), bflo((W_).z), bfhi((W_).z), bflo((W_).w), bfhi((W_).w)}
; #define ROPE32(xr) _Pragma("unroll") for (int ax = 0; ax < 2; ++ax) _Pragma("unroll") for (int f = 0; f < 8; ++f) { const float x1 = xr[16 * ax + f], x2 = xr[16 * ax + 8 + f], c = cs[8 * ax + f], sv = sn[8 * ax + f]; xr[16 * ax + f] = x1 * c - x2 * sv; xr[16 * ax + 8 + f] = x2 * c + x1 * sv; }
; DI void phase_mla_fin(ArgsP a, int tb_, int l, char* shm, int vcu, int G) {
;     ...
;         if (!(it & 1)) {
;             const u32x4* ps = (const u32x4*)(zcq + (size_t)m * 256) + 4 * h; const u32x4* p = (const u32x4*)(qraw + (size_t)m * 768 + h * 96);
;             u32x4 st[4], w[12];
; #pragma unroll
;             for (int i = 0; i < 4; ++i) st[i] = ps[i];
; #pragma unroll
;             for (int i = 0; i < 12; ++i) w[i] = p[i];
;     ...
;             float cs[16], sn[16];
; #pragma unroll
;             for (int i = 0; i < 4; ++i) { cs[4 * i] = lat ? rc[i].x : 1.f; cs[4 * i + 1] = lat ? rc[i].y : 1.f; cs[4 * i + 2] = lat ? rc[i].z : 1.f; cs[4 * i + 3] = lat ? rc[i].w : 1.f;
;                 sn[4 * i] = lat ? rs[i].x : 0.f; sn[4 * i + 1] = lat ? rs[i].y : 0.f; sn[4 * i + 2] = lat ? rs[i].z : 0.f; sn[4 * i + 3] = lat ? rs[i].w : 0.f; }
;             float xr[32];
; #pragma unroll
;             for (int i = 0; i < 4; ++i) { UNPK(krp[i], e);
; #pragma unroll
;                 for (int j = 0; j < 8; ++j) xr[8 * i + j] = e[j] * rn * gkn[64 + 8 * i + j]; }
;             ROPE32(xr)
; #pragma unroll
;             for (int i = 0; i < 4; ++i) { u32x4 ow; ow.x = cvtpk(xr[8 * i], xr[8 * i + 1]); ow.y = cvtpk(xr[8 * i + 2], xr[8 * i + 3]); ow.z = cvtpk(xr[8 * i + 4], xr[8 * i + 5]); ow.w = cvtpk(xr[8 * i + 6], xr[8 * i + 7]); o[8 + i] = ow; }
	v_pk_mul_f32 v[2:3], v[0:1], v[2:3]
	v_pk_mul_f32 v[0:1], v[32:33], v[72:73] op_sel_hi:[0,1]
	v_pk_mul_f32 v[0:1], v[0:1], v[4:5]
	v_pk_mul_f32 v[4:5], v[32:33], v[78:79] op_sel_hi:[0,1]
	v_pk_mul_f32 v[6:7], v[4:5], v[34:35]
	v_pk_mul_f32 v[4:5], v[32:33], v[84:85] op_sel_hi:[0,1]
	v_pk_mul_f32 v[4:5], v[4:5], v[36:37]
	flat_load_dwordx4 v[36:39], v[88:89] offset:288
	v_pk_mul_f32 v[34:35], v[32:33], v[64:65] op_sel_hi:[0,1]
	flat_load_dwordx4 v[64:67], v[88:89] offset:336
	s_waitcnt vmcnt(0) lgkmcnt(0)
	v_pk_mul_f32 v[36:37], v[34:35], v[36:37]
	v_pk_mul_f32 v[34:35], v[32:33], v[60:61] op_sel_hi:[0,1]
	v_pk_mul_f32 v[34:35], v[34:35], v[38:39]
	v_pk_mul_f32 v[38:39], v[32:33], v[70:71] op_sel_hi:[0,1]
	flat_load_dwordx4 v[70:73], v[88:89] offset:352
	v_pk_mul_f32 v[40:41], v[38:39], v[40:41]
	v_pk_mul_f32 v[38:39], v[32:33], v[74:75] op_sel_hi:[0,1]
	v_pk_mul_f32 v[38:39], v[38:39], v[42:43]
	v_pk_mul_f32 v[42:43], v[32:33], v[76:77] op_sel_hi:[0,1]
	v_pk_mul_f32 v[44:45], v[42:43], v[44:45]
	v_pk_mul_f32 v[42:43], v[32:33], v[82:83] op_sel_hi:[0,1]
	v_pk_mul_f32 v[42:43], v[42:43], v[46:47]
	v_pk_mul_f32 v[46:47], v[32:33], v[86:87] op_sel_hi:[0,1]
	v_pk_mul_f32 v[60:61], v[46:47], v[64:65]
	v_pk_mul_f32 v[46:47], v[32:33], v[90:91] op_sel_hi:[0,1]
	v_pk_mul_f32 v[46:47], v[46:47], v[66:67]
	s_waitcnt vmcnt(0) lgkmcnt(0)
	v_pk_mul_f32 v[66:67], v[58:59], v[70:71]
	v_pk_mul_f32 v[58:59], v[32:33], v[62:63] op_sel_hi:[0,1]
	v_pk_mul_f32 v[62:63], v[58:59], v[72:73]
	flat_load_dwordx4 v[70:73], v[88:89] offset:368
	v_pk_mul_f32 v[58:59], v[32:33], v[80:81] op_sel_hi:[0,1]
	v_pk_mul_f32 v[32:33], v[32:33], v[56:57] op_sel_hi:[0,1]
	s_waitcnt vmcnt(0) lgkmcnt(0)
	v_pk_mul_f32 v[56:57], v[32:33], v[72:73]
	v_pk_mul_f32 v[32:33], v[24:25], v[36:37]
	v_pk_mul_f32 v[36:37], v[28:29], v[36:37]
	v_pk_mul_f32 v[70:71], v[58:59], v[70:71]
	v_pk_fma_f32 v[58:59], v[24:25], v[2:3], v[36:37] neg_lo:[0,0,1] neg_hi:[0,0,1]
	v_pk_fma_f32 v[64:65], v[28:29], v[2:3], v[32:33]
	v_pk_mul_f32 v[2:3], v[26:27], v[34:35]
	v_pk_mul_f32 v[24:25], v[30:31], v[34:35]
	v_pk_fma_f32 v[74:75], v[30:31], v[0:1], v[2:3]
	v_pk_fma_f32 v[34:35], v[26:27], v[0:1], v[24:25] neg_lo:[0,0,1] neg_hi:[0,0,1]
	v_pk_mul_f32 v[0:1], v[16:17], v[40:41]
	v_pk_mul_f32 v[2:3], v[20:21], v[40:41]
	v_pk_fma_f32 v[78:79], v[20:21], v[6:7], v[0:1]
	v_pk_fma_f32 v[76:77], v[16:17], v[6:7], v[2:3] neg_lo:[0,0,1] neg_hi:[0,0,1]
	v_pk_mul_f32 v[0:1], v[18:19], v[38:39]
	v_pk_mul_f32 v[2:3], v[22:23], v[38:39]
	v_pk_fma_f32 v[80:81], v[22:23], v[4:5], v[0:1]
	v_pk_fma_f32 v[38:39], v[18:19], v[4:5], v[2:3] neg_lo:[0,0,1] neg_hi:[0,0,1]
	v_pk_mul_f32 v[0:1], v[8:9], v[66:67]
	v_pk_mul_f32 v[2:3], v[12:13], v[66:67]
	v_pk_fma_f32 v[66:67], v[12:13], v[44:45], v[0:1]
	v_pk_fma_f32 v[36:37], v[8:9], v[44:45], v[2:3] neg_lo:[0,0,1] neg_hi:[0,0,1]
	v_pk_mul_f32 v[0:1], v[10:11], v[62:63]
	v_pk_mul_f32 v[2:3], v[14:15], v[62:63]
	s_nop 0
	v_pk_fma_f32 v[32:33], v[10:11], v[42:43], v[2:3] neg_lo:[0,0,1] neg_hi:[0,0,1]
	v_pk_fma_f32 v[42:43], v[14:15], v[42:43], v[0:1]
	v_pk_mul_f32 v[0:1], v[48:49], v[70:71]
	v_pk_mul_f32 v[2:3], v[52:53], v[70:71]
	s_nop 0
	v_pk_fma_f32 v[44:45], v[48:49], v[60:61], v[2:3] neg_lo:[0,0,1] neg_hi:[0,0,1]
	v_pk_fma_f32 v[48:49], v[52:53], v[60:61], v[0:1]
	v_pk_mul_f32 v[0:1], v[50:51], v[56:57]
	v_pk_mul_f32 v[2:3], v[54:55], v[56:57]
	v_pk_fma_f32 v[40:41], v[54:55], v[46:47], v[0:1]
	v_pk_fma_f32 v[50:51], v[50:51], v[46:47], v[2:3] neg_lo:[0,0,1] neg_hi:[0,0,1]
.LBB0_967:
	s_andn2_saveexec_b64 s[30:31], s[30:31]
	s_cbranch_execz .LBB0_964
	v_lshl_add_u64 v[32:33], v[114:115], 0, v[52:53]
	global_load_dwordx4 v[80:83], v[32:33], off offset:48
	global_load_dwordx4 v[84:87], v[32:33], off offset:32
	global_load_dwordx4 v[90:93], v[32:33], off offset:16
	global_load_dwordx4 v[94:97], v[32:33], off
	s_movk_i32 s0, 0x600
	v_mad_i64_i32 v[64:65], s[4:5], v46, s0, v[116:117]
	global_load_dwordx4 v[40:43], v[64:65], off offset:16
	global_load_dwordx4 v[48:51], v[64:65], off
	global_load_dwordx4 v[72:75], v[64:65], off offset:48
	global_load_dwordx4 v[76:79], v[64:65], off offset:32
	global_load_dwordx4 v[32:35], v[64:65], off offset:112
	global_load_dwordx4 v[36:39], v[64:65], off offset:80
	global_load_dwordx4 v[44:47], v[64:65], off offset:64
	global_load_dwordx4 v[68:71], v[64:65], off offset:96
	global_load_dwordx4 v[56:59], v[64:65], off offset:160
	global_load_dwordx4 v[52:55], v[64:65], off offset:176
	global_load_dwordx4 v[60:63], v[64:65], off offset:144
	s_nop 0
	global_load_dwordx4 v[64:67], v[64:65], off offset:128
	s_movk_i32 s0, 0x1100
	s_mov_b64 s[34:35], s[22:23]
	s_waitcnt vmcnt(0)
; DI float shx(float v, int mask, int lane) { return __int_as_float(__builtin_amdgcn_ds_bpermute((lane ^ mask) << 2, __float_as_int(v))); }
; #define SSQ8(W_, ACC_) do { UNPK(W_, e_); ACC_ += (e_[0] * e_[0] + e_[1] * e_[1]) + (e_[2] * e_[2] + e_[3] * e_[3]) + (e_[4] * e_[4] + e_[5] * e_[5]) + (e_[6] * e_[6] + e_[7] * e_[7]); } while (0)
; DI void phase_mla_fin(ArgsP a, int tb_, int l, char* shm, int vcu, int G) {
;     ...
;             float cs[16], sn[16];
; #pragma unroll
;             for (int i = 0; i < 4; ++i) { cs[4 * i] = lat ? rc[i].x : 1.f; cs[4 * i + 1] = lat ? rc[i].y : 1.f; cs[4 * i + 2] = lat ? rc[i].z : 1.f; cs[4 * i + 3] = lat ? rc[i].w : 1.f;
;                 sn[4 * i] = lat ? rs[i].x : 0.f; sn[4 * i + 1] = lat ? rs[i].y : 0.f; sn[4 * i + 2] = lat ? rs[i].z : 0.f; sn[4 * i + 3] = lat ? rs[i].w : 0.f; }
;             float ssq = 0.f, ss = 0.f;
; #pragma unroll
;             for (int i = 0; i < 4; ++i) SSQ8(st[i], ssq);
;             ssq += shx(ssq, 1, lane); ssq += shx(ssq, 2, lane); ssq += shx(ssq, 4, lane);
	v_cndmask_b32_e64 v25, 1.0, v25, s[6:7]
	v_cndmask_b32_e64 v24, 1.0, v24, s[6:7]
	v_cndmask_b32_e64 v29, 0, v29, s[6:7]
	v_cndmask_b32_e64 v28, 0, v28, s[6:7]
	v_cndmask_b32_e64 v27, 1.0, v27, s[6:7]
	v_cndmask_b32_e64 v26, 1.0, v26, s[6:7]
	v_cndmask_b32_e64 v31, 0, v31, s[6:7]
	v_cndmask_b32_e64 v30, 0, v30, s[6:7]
	v_cndmask_b32_e64 v17, 1.0, v17, s[6:7]
	v_cndmask_b32_e64 v16, 1.0, v16, s[6:7]
	v_cndmask_b32_e64 v21, 0, v21, s[6:7]
	v_cndmask_b32_e64 v20, 0, v20, s[6:7]
	v_cndmask_b32_e64 v19, 1.0, v19, s[6:7]
	v_cndmask_b32_e64 v18, 1.0, v18, s[6:7]
	v_cndmask_b32_e64 v23, 0, v23, s[6:7]
	v_cndmask_b32_e64 v22, 0, v22, s[6:7]
	v_cndmask_b32_e64 v9, 1.0, v9, s[6:7]
	v_cndmask_b32_e64 v8, 1.0, v8, s[6:7]
	v_cndmask_b32_e64 v13, 0, v13, s[6:7]
	v_cndmask_b32_e64 v12, 0, v12, s[6:7]
	v_and_b32_e32 v193, 0xffff0000, v40
	v_lshlrev_b32_e32 v150, 16, v51
	v_and_b32_e32 v109, 0xffff0000, v73
	v_and_b32_e32 v108, 0xffff0000, v72
	v_and_b32_e32 v101, 0xffff0000, v80
	v_and_b32_e32 v100, 0xffff0000, v83
	v_mul_f32_e32 v106, v100, v100
	v_and_b32_e32 v89, 0xffff0000, v95
	v_lshlrev_b32_e32 v88, 16, v95
	v_mul_f32_e32 v98, v89, v89
	v_pk_fma_f32 v[88:89], v[88:89], v[88:89], v[98:99] op_sel_hi:[1,1,0]
	v_lshlrev_b32_e32 v99, 16, v94
	v_and_b32_e32 v95, 0xffff0000, v94
	v_and_b32_e32 v94, 0xffff0000, v96
	v_lshlrev_b32_e32 v98, 16, v96
	v_pk_mul_f32 v[94:95], v[94:95], v[94:95]
	v_lshlrev_b32_e32 v96, 16, v90
	v_pk_fma_f32 v[94:95], v[98:99], v[98:99], v[94:95]
	v_and_b32_e32 v90, 0xffff0000, v90
	v_pk_add_f32 v[88:89], v[94:95], v[88:89] op_sel:[1,0] op_sel_hi:[0,1]
	v_pk_add_f32 v[88:89], v[94:95], v[88:89]
	v_lshlrev_b32_e32 v94, 16, v97
	v_and_b32_e32 v95, 0xffff0000, v97
	v_lshlrev_b32_e32 v97, 16, v91
	v_and_b32_e32 v91, 0xffff0000, v91
	v_pk_mul_f32 v[90:91], v[90:91], v[90:91]
	v_and_b32_e32 v99, 0xffff0000, v81
	v_pk_fma_f32 v[90:91], v[96:97], v[96:97], v[90:91]
	v_lshlrev_b32_e32 v98, 16, v81
	v_pk_add_f32 v[96:97], v[90:91], v[90:91] op_sel:[0,1] op_sel_hi:[1,0]
	v_lshlrev_b32_e32 v91, 16, v93
	v_lshlrev_b32_e32 v90, 16, v92
	v_and_b32_e32 v93, 0xffff0000, v93
	v_and_b32_e32 v92, 0xffff0000, v92
	v_pk_mul_f32 v[92:93], v[92:93], v[92:93]
	v_lshlrev_b32_e32 v81, 16, v83
	v_pk_fma_f32 v[90:91], v[90:91], v[90:91], v[92:93]
	v_mul_f32_e32 v105, v99, v99
	v_pk_add_f32 v[92:93], v[90:91], v[96:97]
	v_and_b32_e32 v97, 0xffff0000, v84
	v_lshlrev_b32_e32 v96, 16, v84
	v_lshlrev_b32_e32 v84, 16, v85
	v_and_b32_e32 v85, 0xffff0000, v85
	v_lshlrev_b32_e32 v99, 16, v80
	v_mul_f32_e32 v80, v97, v97
	v_pk_fma_f32 v[96:97], v[96:97], v[96:97], v[80:81] op_sel_hi:[1,1,0]
	v_mul_f32_e32 v80, v85, v85
	v_mul_f32_e32 v104, v98, v98
	v_and_b32_e32 v100, 0xffff0000, v86
	v_pk_mov_b32 v[102:103], v[86:87], v[82:83] op_sel:[1,0]
	v_pk_fma_f32 v[84:85], v[84:85], v[84:85], v[80:81] op_sel_hi:[1,1,0]
	v_lshlrev_b32_e32 v98, 16, v86
	v_lshlrev_b32_e32 v83, 16, v82
	v_lshlrev_b32_e32 v82, 16, v87
	v_and_b32_e32 v87, 0xffff0000, v103
	v_and_b32_e32 v86, 0xffff0000, v102
	v_pk_mul_f32 v[100:101], v[100:101], v[100:101]
	v_mov_b32_e32 v97, v104
	v_mov_b32_e32 v85, v105
	v_pk_fma_f32 v[98:99], v[98:99], v[98:99], v[100:101]
	v_pk_add_f32 v[84:85], v[96:97], v[84:85]
	v_pk_mul_f32 v[86:87], v[86:87], v[86:87]
	v_pk_add_f32 v[84:85], v[98:99], v[84:85]
	v_pk_fma_f32 v[82:83], v[82:83], v[82:83], v[86:87]
	v_mul_f32_e32 v80, v95, v95
	v_pk_add_f32 v[82:83], v[82:83], v[84:85]
	v_pk_fma_f32 v[84:85], v[94:95], v[94:95], v[80:81] op_sel_hi:[1,1,0]
	v_mov_b32_e32 v86, v88
	v_mov_b32_e32 v80, v84
	v_mov_b32_e32 v87, v81
	v_pk_add_f32 v[84:85], v[84:85], v[88:89]
	v_pk_mul_f32 v[80:81], v[80:81], v[86:87]
	v_and_b32_e32 v105, 0xffff0000, v44
	v_mov_b32_e32 v85, v81
	v_pk_add_f32 v[80:81], v[90:91], v[92:93] op_sel:[1,0] op_sel_hi:[0,1]
	v_mov_b32_e32 v81, v106
	v_pk_add_f32 v[80:81], v[84:85], v[80:81]
	v_lshlrev_b32_e32 v104, 16, v44
	v_pk_add_f32 v[80:81], v[80:81], v[82:83]
	v_mul_f32_e32 v44, v105, v105
	v_add_f32_e32 v80, v80, v81
	v_and_b32_e32 v101, 0xffff0000, v45
	v_pk_fma_f32 v[126:127], v[104:105], v[104:105], v[44:45] op_sel_hi:[1,1,0]
	v_lshlrev_b32_e32 v100, 16, v45
	v_mul_f32_e32 v44, v101, v101
	s_waitcnt lgkmcnt(0)
	s_nop 1
	v_add_f32_dpp v80, v80, v80 quad_perm:[1,0,3,2] row_mask:0xf bank_mask:0xf
	v_and_b32_e32 v99, 0xffff0000, v69
	v_and_b32_e32 v98, 0xffff0000, v68
	v_pk_fma_f32 v[132:133], v[100:101], v[100:101], v[44:45] op_sel_hi:[1,1,0]
	v_lshlrev_b32_e32 v125, 16, v69
	s_waitcnt lgkmcnt(0)
	s_nop 1
	v_add_f32_dpp v80, v80, v80 quad_perm:[2,3,0,1] row_mask:0xf bank_mask:0xf
	v_lshlrev_b32_e32 v124, 16, v68
	v_pk_mul_f32 v[44:45], v[98:99], v[98:99]
	v_and_b32_e32 v93, 0xffff0000, v71
	v_and_b32_e32 v92, 0xffff0000, v70
	s_waitcnt lgkmcnt(0)
; DI float shx(float v, int mask, int lane) { return __int_as_float(__builtin_amdgcn_ds_bpermute((lane ^ mask) << 2, __float_as_int(v))); }
; #define SSQ8(W_, ACC_) do { UNPK(W_, e_); ACC_ += (e_[0] * e_[0] + e_[1] * e_[1]) + (e_[2] * e_[2] + e_[3] * e_[3]) + (e_[4] * e_[4] + e_[5] * e_[5]) + (e_[6] * e_[6] + e_[7] * e_[7]); } while (0)
; DI void phase_mla_fin(ArgsP a, int tb_, int l, char* shm, int vcu, int G) {
;     ...
;             ssq += shx(ssq, 1, lane); ssq += shx(ssq, 2, lane); ssq += shx(ssq, 4, lane);
;             const float rq = rsqrtf(ssq * (1.f / 256.f) + EPS);
; #pragma unroll
;             for (int i = 0; i < 12; ++i) SSQ8(w[i], ss);
;             const float rn = rsqrtf(ss * rq * rq * (1.f / 96.f) + EPS) * rq;
;             u32x4* o = (u32x4*)(Qb + (bh * KVLEN + pos) * 96);
	s_nop 1
	v_add_f32_dpp v80, v80, v80 row_half_mirror row_mask:0xf bank_mask:0xf
	v_fmamk_f32 v80, v80, 0x3b800000, v230
	v_lshlrev_b32_e32 v139, 16, v73
	v_lshlrev_b32_e32 v138, 16, v72
	v_pk_mul_f32 v[72:73], v[108:109], v[108:109]
	v_and_b32_e32 v103, 0xffff0000, v75
	v_and_b32_e32 v102, 0xffff0000, v74
	v_pk_fma_f32 v[44:45], v[124:125], v[124:125], v[44:45]
	v_lshlrev_b32_e32 v129, 16, v71
	v_lshlrev_b32_e32 v128, 16, v70
	v_pk_mul_f32 v[68:69], v[92:93], v[92:93]
	v_and_b32_e32 v87, 0xffff0000, v32
	v_cmp_gt_f32_e64 s[8:9], s76, v80
	v_mul_f32_e32 v81, 0x4b800000, v80
	v_pk_fma_f32 v[72:73], v[138:139], v[138:139], v[72:73]
	v_lshlrev_b32_e32 v141, 16, v75
	v_lshlrev_b32_e32 v140, 16, v74
	v_pk_mul_f32 v[74:75], v[102:103], v[102:103]
	v_pk_add_f32 v[44:45], v[44:45], v[44:45] op_sel:[0,1] op_sel_hi:[1,0]
	v_pk_fma_f32 v[68:69], v[128:129], v[128:129], v[68:69]
	v_lshlrev_b32_e32 v86, 16, v32
	v_mul_f32_e32 v32, v87, v87
	v_and_b32_e32 v85, 0xffff0000, v33
	v_cndmask_b32_e64 v80, v80, v81, s[8:9]
	v_pk_add_f32 v[72:73], v[72:73], v[72:73] op_sel:[0,1] op_sel_hi:[1,0]
	v_pk_fma_f32 v[74:75], v[140:141], v[140:141], v[74:75]
	v_pk_add_f32 v[44:45], v[68:69], v[44:45]
	v_pk_fma_f32 v[144:145], v[86:87], v[86:87], v[32:33] op_sel_hi:[1,1,0]
	v_lshlrev_b32_e32 v84, 16, v33
	v_mul_f32_e32 v32, v85, v85
	v_rsq_f32_e32 v80, v80
	v_pk_add_f32 v[72:73], v[74:75], v[72:73]
	v_pk_add_f32 v[136:137], v[68:69], v[44:45] op_sel:[1,0] op_sel_hi:[0,1]
	v_pk_fma_f32 v[148:149], v[84:85], v[84:85], v[32:33] op_sel_hi:[1,1,0]
	v_mad_i64_i32 v[32:33], s[4:5], v142, s0, v[188:189]
	v_mov_b64_e32 v[44:45], s[16:17]
	s_movk_i32 s0, 0xc0
	v_lshlrev_b32_e32 v70, 16, v60
	v_and_b32_e32 v71, 0xffff0000, v60
	v_lshlrev_b32_e32 v60, 16, v61
	v_and_b32_e32 v61, 0xffff0000, v61
	v_pk_add_f32 v[130:131], v[74:75], v[72:73] op_sel:[1,0] op_sel_hi:[0,1]
	v_mad_u64_u32 v[68:69], s[4:5], v32, s0, v[44:45]
	v_mov_b32_e32 v44, v71
	v_mov_b32_e32 v45, v61
	v_and_b32_e32 v73, 0xffff0000, v62
	v_lshlrev_b32_e32 v90, 16, v67
	v_and_b32_e32 v91, 0xffff0000, v67
	v_and_b32_e32 v67, 0xffff0000, v63
	v_mad_i32_i24 v69, v33, s0, v69
	v_mov_b32_e32 v32, v70
	v_mov_b32_e32 v33, v60
	v_pk_mul_f32 v[44:45], v[44:45], v[44:45]
	v_lshlrev_b32_e32 v88, 16, v66
	v_and_b32_e32 v89, 0xffff0000, v66
	v_lshlrev_b32_e32 v72, 16, v62
	v_lshlrev_b32_e32 v66, 16, v63
	v_mov_b32_e32 v62, v67
	v_mov_b32_e32 v63, v73
	v_and_b32_e32 v111, 0xffff0000, v77
	v_and_b32_e32 v110, 0xffff0000, v76
	v_pk_fma_f32 v[32:33], v[32:33], v[32:33], v[44:45]
	v_mov_b32_e32 v44, v66
	v_mov_b32_e32 v45, v72
	v_pk_mul_f32 v[62:63], v[62:63], v[62:63]
	v_mul_f32_e32 v81, 0x45800000, v80
	v_lshlrev_b32_e32 v123, 16, v77
	v_lshlrev_b32_e32 v122, 16, v76
	v_pk_mul_f32 v[76:77], v[110:111], v[110:111]
	v_and_b32_e32 v107, 0xffff0000, v79
	v_and_b32_e32 v106, 0xffff0000, v78
	v_pk_add_f32 v[32:33], v[32:33], v[32:33] op_sel:[0,1] op_sel_hi:[1,0]
	v_pk_fma_f32 v[44:45], v[44:45], v[44:45], v[62:63]
	v_pk_fma_f32 v[76:77], v[122:123], v[122:123], v[76:77]
	v_lshlrev_b32_e32 v135, 16, v79
	v_lshlrev_b32_e32 v134, 16, v78
	v_pk_mul_f32 v[78:79], v[106:107], v[106:107]
	v_cndmask_b32_e64 v119, v80, v81, s[8:9]
	v_pk_add_f32 v[32:33], v[44:45], v[32:33] op_sel:[1,0] op_sel_hi:[0,1]
	v_and_b32_e32 v81, 0xffff0000, v56
	v_pk_add_f32 v[76:77], v[76:77], v[76:77] op_sel:[0,1] op_sel_hi:[1,0]
	v_pk_fma_f32 v[78:79], v[134:135], v[134:135], v[78:79]
	v_pk_add_f32 v[142:143], v[44:45], v[32:33]
	v_lshlrev_b32_e32 v80, 16, v56
	v_mul_f32_e32 v32, v81, v81
	v_and_b32_e32 v83, 0xffff0000, v57
	v_pk_add_f32 v[76:77], v[78:79], v[76:77]
	v_pk_fma_f32 v[162:163], v[80:81], v[80:81], v[32:33] op_sel_hi:[1,1,0]
	v_cndmask_b32_e64 v32, 1.0, v10, s[6:7]
	v_lshlrev_b32_e32 v82, 16, v57
	v_mul_f32_e32 v10, v83, v83
	v_lshlrev_b32_e32 v94, 16, v58
	v_and_b32_e32 v95, 0xffff0000, v58
	v_lshlrev_b32_e32 v96, 16, v59
	v_and_b32_e32 v97, 0xffff0000, v59
	v_mov_b64_e32 v[58:59], s[34:35]
	v_pk_add_f32 v[120:121], v[78:79], v[76:77] op_sel:[1,0] op_sel_hi:[0,1]
	v_lshlrev_b32_e32 v74, 16, v64
	v_and_b32_e32 v75, 0xffff0000, v64
	v_lshlrev_b32_e32 v78, 16, v65
	v_and_b32_e32 v79, 0xffff0000, v65
	v_lshlrev_b32_e32 v62, 16, v52
	v_and_b32_e32 v63, 0xffff0000, v52
	v_cndmask_b32_e64 v33, 1.0, v11, s[6:7]
	v_cndmask_b32_e64 v45, 0, v15, s[6:7]
	v_cndmask_b32_e64 v44, 0, v14, s[6:7]
	v_pk_fma_f32 v[164:165], v[82:83], v[82:83], v[10:11] op_sel_hi:[1,1,0]
	v_lshlrev_b32_e32 v64, 16, v53
	v_and_b32_e32 v65, 0xffff0000, v53
	v_cndmask_b32_e64 v53, 1.0, v1, s[6:7]
	v_cndmask_b32_e64 v52, 1.0, v0, s[6:7]
	v_cndmask_b32_e64 v57, 0, v5, s[6:7]
	v_cndmask_b32_e64 v56, 0, v4, s[6:7]
	v_cndmask_b32_e64 v11, 1.0, v3, s[6:7]
	v_cndmask_b32_e64 v10, 1.0, v2, s[6:7]
	v_cndmask_b32_e64 v15, 0, v7, s[6:7]
	v_cndmask_b32_e64 v14, 0, v6, s[6:7]
	flat_load_dwordx4 v[0:3], v[58:59] offset:16
	flat_load_dwordx4 v[4:7], v[58:59]
	v_pk_mul_f32 v[156:157], v[78:79], v[78:79]
	v_and_b32_e32 v151, 0xffff0000, v51
	v_lshlrev_b32_e32 v152, 16, v50
	v_and_b32_e32 v153, 0xffff0000, v50
	v_lshlrev_b32_e32 v154, 16, v49
	v_and_b32_e32 v155, 0xffff0000, v49
	v_lshlrev_b32_e32 v158, 16, v48
	v_and_b32_e32 v159, 0xffff0000, v48
	v_and_b32_e32 v49, 0xffff0000, v36
	v_and_b32_e32 v48, 0xffff0000, v46
	v_pk_mov_b32 v[50:51], v[46:47], v[38:39] op_sel:[1,0]
	v_mov_b32_e32 v145, v156
	v_mov_b32_e32 v149, v157
	v_pk_mul_f32 v[166:167], v[64:65], v[64:65]
	v_lshlrev_b32_e32 v177, 16, v36
	v_lshlrev_b32_e32 v176, 16, v46
	v_lshlrev_b32_e32 v178, 16, v47
	v_and_b32_e32 v47, 0xffff0000, v51
	v_and_b32_e32 v46, 0xffff0000, v50
	v_pk_mul_f32 v[50:51], v[48:49], v[48:49]
	v_pk_add_f32 v[184:185], v[144:145], v[148:149]
; DI unsigned cvtpk(float lo, float hi) { f32x2_t v = {lo, hi}; bf16x2_t b = __builtin_convertvector(v, bf16x2_t); return __builtin_bit_cast(unsigned, b); }
; #define UNPK(W_, E_) const float E_[8] = {bflo((W_).x), bfhi((W_).x), bflo((W_).y), bfhi((W_).y), bflo((W_).z), bfhi((W_).z), bflo((W_).w), bfhi((W_).w)}
; #define SSQ8(W_, ACC_) do { UNPK(W_, e_); ACC_ += (e_[0] * e_[0] + e_[1] * e_[1]) + (e_[2] * e_[2] + e_[3] * e_[3]) + (e_[4] * e_[4] + e_[5] * e_[5]) + (e_[6] * e_[6] + e_[7] * e_[7]); } while (0)
; DI void phase_mla_fin(ArgsP a, int tb_, int l, char* shm, int vcu, int G) {
;     ...
;             for (int i = 0; i < 12; ++i) SSQ8(w[i], ss);
;             const float rn = rsqrtf(ss * rq * rq * (1.f / 96.f) + EPS) * rq;
;             u32x4* o = (u32x4*)(Qb + (bh * KVLEN + pos) * 96);
; #pragma unroll
;             for (int i = 0; i < 8; ++i) { UNPK(w[i], e); const float sc = rn * C2; u32x4 ow;
;                 ow.x = cvtpk(e[0] * sc * gqn[8 * i], e[1] * sc * gqn[8 * i + 1]); ow.y = cvtpk(e[2] * sc * gqn[8 * i + 2], e[3] * sc * gqn[8 * i + 3]);
;                 ow.z = cvtpk(e[4] * sc * gqn[8 * i + 4], e[5] * sc * gqn[8 * i + 5]); ow.w = cvtpk(e[6] * sc * gqn[8 * i + 6], e[7] * sc * gqn[8 * i + 7]); o[i] = ow; }
	v_mov_b32_e32 v148, v95
	v_mov_b32_e32 v149, v63
	v_and_b32_e32 v77, 0xffff0000, v54
	v_lshlrev_b32_e32 v179, 16, v38
	v_pk_fma_f32 v[180:181], v[176:177], v[176:177], v[50:51]
	v_pk_mul_f32 v[50:51], v[46:47], v[46:47]
	v_mov_b32_e32 v163, v166
	v_mov_b32_e32 v165, v167
	v_mov_b32_e32 v144, v94
	v_mov_b32_e32 v145, v62
	v_pk_mul_f32 v[148:149], v[148:149], v[148:149]
	v_lshlrev_b32_e32 v76, 16, v54
	v_pk_fma_f32 v[182:183], v[178:179], v[178:179], v[50:51]
	v_pk_add_f32 v[50:51], v[162:163], v[164:165]
	v_pk_fma_f32 v[144:145], v[144:145], v[144:145], v[148:149]
	v_mov_b32_e32 v148, v97
	v_mov_b32_e32 v149, v77
	v_pk_add_f32 v[50:51], v[144:145], v[50:51]
	v_mov_b32_e32 v144, v96
	v_mov_b32_e32 v145, v76
	v_pk_mul_f32 v[148:149], v[148:149], v[148:149]
	v_and_b32_e32 v165, 0xffff0000, v42
	v_pk_fma_f32 v[144:145], v[144:145], v[144:145], v[148:149]
	v_and_b32_e32 v149, 0xffff0000, v43
	v_pk_add_f32 v[186:187], v[144:145], v[50:51]
	v_lshlrev_b32_e32 v148, 16, v43
	v_mov_b32_e32 v144, v151
	v_mov_b32_e32 v145, v149
	v_mov_b32_e32 v50, v150
	v_mov_b32_e32 v51, v148
	v_pk_mul_f32 v[144:145], v[144:145], v[144:145]
	v_lshlrev_b32_e32 v164, 16, v42
	v_pk_fma_f32 v[50:51], v[50:51], v[50:51], v[144:145]
	v_mov_b32_e32 v144, v153
	v_mov_b32_e32 v145, v165
	v_and_b32_e32 v167, 0xffff0000, v41
	v_mov_b32_e32 v42, v152
	v_mov_b32_e32 v43, v164
	v_pk_mul_f32 v[144:145], v[144:145], v[144:145]
	v_lshlrev_b32_e32 v166, 16, v41
	v_mov_b32_e32 v156, v155
	v_mov_b32_e32 v157, v167
	v_pk_fma_f32 v[42:43], v[42:43], v[42:43], v[144:145]
	v_mov_b32_e32 v144, v154
	v_mov_b32_e32 v145, v166
	v_pk_mul_f32 v[156:157], v[156:157], v[156:157]
	v_lshlrev_b32_e32 v192, 16, v40
	v_pk_fma_f32 v[144:145], v[144:145], v[144:145], v[156:157]
	v_mov_b32_e32 v156, v159
	v_mov_b32_e32 v157, v193
	v_mov_b32_e32 v40, v158
	v_mov_b32_e32 v41, v192
	v_pk_mul_f32 v[156:157], v[156:157], v[156:157]
	v_pk_mul_f32 v[146:147], v[90:91], v[90:91]
	v_pk_fma_f32 v[40:41], v[40:41], v[40:41], v[156:157]
	v_mov_b32_e32 v137, v147
	v_pk_add_f32 v[40:41], v[40:41], v[144:145]
	v_lshlrev_b32_e32 v54, 16, v55
	v_pk_add_f32 v[40:41], v[42:43], v[40:41]
	v_and_b32_e32 v55, 0xffff0000, v55
	v_pk_add_f32 v[40:41], v[50:51], v[40:41]
	v_lshlrev_b32_e32 v50, 16, v39
	v_pk_add_f32 v[40:41], v[40:41], v[40:41] op_sel:[0,1] op_sel_hi:[1,0]
	v_and_b32_e32 v51, 0xffff0000, v39
	v_pk_mul_f32 v[38:39], v[50:51], v[50:51]
	v_pk_add_f32 v[40:41], v[40:41], v[120:121]
	v_mov_b32_e32 v131, v39
	v_mov_b32_e32 v41, v38
	v_pk_add_f32 v[38:39], v[40:41], v[130:131]
	v_lshlrev_b32_e32 v130, 16, v37
	v_and_b32_e32 v131, 0xffff0000, v37
	v_pk_mul_f32 v[36:37], v[130:131], v[130:131]
	v_mov_b32_e32 v120, v124
	v_mov_b32_e32 v127, v36
	v_mov_b32_e32 v133, v37
	v_pk_add_f32 v[36:37], v[126:127], v[132:133]
	v_mov_b32_e32 v121, v98
	v_pk_add_f32 v[36:37], v[180:181], v[36:37]
	v_mov_b32_e32 v98, v125
	v_pk_add_f32 v[36:37], v[182:183], v[36:37]
	v_mov_b32_e32 v125, v89
	v_pk_add_f32 v[36:37], v[38:39], v[36:37]
	v_mov_b32_e32 v41, v88
	v_pk_add_f32 v[36:37], v[36:37], v[36:37] op_sel:[0,1] op_sel_hi:[1,0]
	v_mov_b32_e32 v127, v75
	v_mov_b32_e32 v37, v146
	v_pk_add_f32 v[38:39], v[36:37], v[136:137]
	v_and_b32_e32 v37, 0xffff0000, v35
	v_lshlrev_b32_e32 v36, 16, v35
	v_mov_b32_e32 v124, v37
	v_mov_b32_e32 v40, v36
	v_pk_mul_f32 v[124:125], v[124:125], v[124:125]
	v_mov_b32_e32 v35, v74
	v_pk_fma_f32 v[124:125], v[40:41], v[40:41], v[124:125]
	v_and_b32_e32 v41, 0xffff0000, v34
	v_lshlrev_b32_e32 v40, 16, v34
	v_mov_b32_e32 v126, v41
	v_mov_b32_e32 v34, v40
	v_pk_mul_f32 v[126:127], v[126:127], v[126:127]
	v_pk_mul_f32 v[160:161], v[54:55], v[54:55]
	v_pk_fma_f32 v[34:35], v[34:35], v[34:35], v[126:127]
	v_mov_b32_e32 v143, v161
	v_pk_add_f32 v[34:35], v[34:35], v[184:185]
	v_mov_b32_e32 v162, v122
	v_pk_add_f32 v[34:35], v[124:125], v[34:35]
	v_mov_b32_e32 v163, v110
	v_pk_add_f32 v[34:35], v[38:39], v[34:35]
	v_mov_b32_e32 v110, v123
	v_pk_add_f32 v[34:35], v[34:35], v[34:35] op_sel:[0,1] op_sel_hi:[1,0]
	v_mov_b32_e32 v156, v134
	v_mov_b32_e32 v35, v160
	v_pk_add_f32 v[34:35], v[34:35], v[142:143]
	v_mov_b32_e32 v157, v106
	v_pk_add_f32 v[34:35], v[34:35], v[186:187]
	v_mov_b32_e32 v106, v135
	v_add_f32_e32 v34, v34, v35
	v_mul_f32_e32 v34, v34, v119
	v_mul_f32_e32 v34, v119, v34
	v_fmamk_f32 v34, v34, 0x3c2aaaab, v230
	v_cmp_gt_f32_e64 s[6:7], s76, v34
	v_mul_f32_e32 v35, 0x4b800000, v34
	v_mov_b32_e32 v144, v138
	v_cndmask_b32_e64 v34, v34, v35, s[6:7]
	v_rsq_f32_e32 v34, v34
	v_mov_b32_e32 v145, v108
	v_mov_b32_e32 v108, v139
	v_mov_b32_e32 v138, v140
	v_mul_f32_e32 v35, 0x45800000, v34
	v_cndmask_b32_e64 v34, v34, v35, s[6:7]
	v_mul_f32_e32 v34, v119, v34
	v_mul_f32_e32 v38, 0x3e16c740, v34
	v_pk_mul_f32 v[124:125], v[38:39], v[158:159] op_sel_hi:[0,1]
	s_waitcnt vmcnt(0) lgkmcnt(0)
	v_pk_mul_f32 v[4:5], v[4:5], v[124:125]
	v_pk_mul_f32 v[124:125], v[38:39], v[154:155] op_sel_hi:[0,1]
	v_pk_mul_f32 v[6:7], v[6:7], v[124:125]
	v_cvt_pk_bf16_f32 v4, v4, v5
	v_cvt_pk_bf16_f32 v5, v6, v7
	v_pk_mul_f32 v[6:7], v[38:39], v[152:153] op_sel_hi:[0,1]
	v_pk_mul_f32 v[0:1], v[0:1], v[6:7]
	v_mov_b32_e32 v139, v102
	v_cvt_pk_bf16_f32 v6, v0, v1
	v_pk_mul_f32 v[0:1], v[38:39], v[150:151] op_sel_hi:[0,1]
	v_pk_mul_f32 v[0:1], v[2:3], v[0:1]
	v_mov_b32_e32 v102, v141
	v_cvt_pk_bf16_f32 v7, v0, v1
	global_store_dwordx4 v[68:69], v[4:7], off
	flat_load_dwordx4 v[0:3], v[58:59] offset:32
	v_mov_b32_e32 v134, v176
	v_pk_mul_f32 v[4:5], v[38:39], v[192:193] op_sel_hi:[0,1]
	v_pk_mul_f32 v[6:7], v[38:39], v[164:165] op_sel_hi:[0,1]
	v_mov_b32_e32 v135, v48
	v_mov_b32_e32 v122, v178
	v_mov_b32_e32 v123, v46
	v_mov_b32_e32 v48, v177
	v_mov_b32_e32 v46, v179
	v_mov_b32_e32 v42, v128
	v_mov_b32_e32 v43, v92
	v_mov_b32_e32 v92, v129
	s_mov_b32 s0, 0x3e16c740
	s_waitcnt vmcnt(0) lgkmcnt(0)
; DI unsigned cvtpk(float lo, float hi) { f32x2_t v = {lo, hi}; bf16x2_t b = __builtin_convertvector(v, bf16x2_t); return __builtin_bit_cast(unsigned, b); }
; #define UNPK(W_, E_) const float E_[8] = {bflo((W_).x), bfhi((W_).x), bflo((W_).y), bfhi((W_).y), bflo((W_).z), bfhi((W_).z), bflo((W_).w), bfhi((W_).w)}
; DI void phase_mla_fin(ArgsP a, int tb_, int l, char* shm, int vcu, int G) {
;     ...
;             u32x4* o = (u32x4*)(Qb + (bh * KVLEN + pos) * 96);
; #pragma unroll
;             for (int i = 0; i < 8; ++i) { UNPK(w[i], e); const float sc = rn * C2; u32x4 ow;
;                 ow.x = cvtpk(e[0] * sc * gqn[8 * i], e[1] * sc * gqn[8 * i + 1]); ow.y = cvtpk(e[2] * sc * gqn[8 * i + 2], e[3] * sc * gqn[8 * i + 3]);
;                 ow.z = cvtpk(e[4] * sc * gqn[8 * i + 4], e[5] * sc * gqn[8 * i + 5]); ow.w = cvtpk(e[6] * sc * gqn[8 * i + 6], e[7] * sc * gqn[8 * i + 7]); o[i] = ow; }
;             float xr[32];
; #pragma unroll
;             for (int i = 0; i < 4; ++i) { UNPK(w[8 + i], e);
; #pragma unroll
;                 for (int j = 0; j < 8; ++j) xr[8 * i + j] = e[j] * rn * C2 * gqn[64 + 8 * i + j]; }
	v_pk_mul_f32 v[0:1], v[0:1], v[4:5]
	v_pk_mul_f32 v[4:5], v[38:39], v[166:167] op_sel_hi:[0,1]
	v_pk_mul_f32 v[2:3], v[2:3], v[4:5]
	v_cvt_pk_bf16_f32 v0, v0, v1
	v_cvt_pk_bf16_f32 v1, v2, v3
	flat_load_dwordx4 v[2:5], v[58:59] offset:48
	s_waitcnt vmcnt(0) lgkmcnt(0)
	v_pk_mul_f32 v[2:3], v[2:3], v[6:7]
	v_pk_mul_f32 v[6:7], v[38:39], v[148:149] op_sel_hi:[0,1]
	v_pk_mul_f32 v[4:5], v[4:5], v[6:7]
	v_cvt_pk_bf16_f32 v2, v2, v3
	v_cvt_pk_bf16_f32 v3, v4, v5
	global_store_dwordx4 v[68:69], v[0:3], off offset:16
	flat_load_dwordx4 v[0:3], v[58:59] offset:64
	v_pk_mul_f32 v[4:5], v[38:39], v[162:163] op_sel_hi:[0,1]
	v_pk_mul_f32 v[6:7], v[38:39], v[156:157] op_sel_hi:[0,1]
	s_waitcnt vmcnt(0) lgkmcnt(0)
	v_pk_mul_f32 v[0:1], v[0:1], v[4:5]
	v_pk_mul_f32 v[4:5], v[38:39], v[110:111] op_sel_hi:[0,1]
	v_pk_mul_f32 v[2:3], v[2:3], v[4:5]
	v_cvt_pk_bf16_f32 v0, v0, v1
	v_cvt_pk_bf16_f32 v1, v2, v3
	flat_load_dwordx4 v[2:5], v[58:59] offset:80
	s_waitcnt vmcnt(0) lgkmcnt(0)
	v_pk_mul_f32 v[2:3], v[6:7], v[2:3]
	v_pk_mul_f32 v[6:7], v[38:39], v[106:107] op_sel_hi:[0,1]
	v_pk_mul_f32 v[4:5], v[6:7], v[4:5]
	v_cvt_pk_bf16_f32 v2, v2, v3
	v_cvt_pk_bf16_f32 v3, v4, v5
	global_store_dwordx4 v[68:69], v[0:3], off offset:32
	flat_load_dwordx4 v[0:3], v[58:59] offset:96
	v_pk_mul_f32 v[4:5], v[38:39], v[144:145] op_sel_hi:[0,1]
	v_pk_mul_f32 v[6:7], v[38:39], v[138:139] op_sel_hi:[0,1]
	s_waitcnt vmcnt(0) lgkmcnt(0)
	v_pk_mul_f32 v[0:1], v[4:5], v[0:1]
	v_pk_mul_f32 v[4:5], v[38:39], v[108:109] op_sel_hi:[0,1]
	v_pk_mul_f32 v[2:3], v[4:5], v[2:3]
	v_cvt_pk_bf16_f32 v0, v0, v1
	v_cvt_pk_bf16_f32 v1, v2, v3
	flat_load_dwordx4 v[2:5], v[58:59] offset:112
	s_waitcnt vmcnt(0) lgkmcnt(0)
	v_pk_mul_f32 v[2:3], v[6:7], v[2:3]
	v_pk_mul_f32 v[6:7], v[38:39], v[102:103] op_sel_hi:[0,1]
	v_pk_mul_f32 v[4:5], v[6:7], v[4:5]
	v_cvt_pk_bf16_f32 v2, v2, v3
	v_cvt_pk_bf16_f32 v3, v4, v5
	global_store_dwordx4 v[68:69], v[0:3], off offset:48
	flat_load_dwordx4 v[0:3], v[58:59] offset:128
	v_pk_mul_f32 v[4:5], v[38:39], v[104:105] op_sel_hi:[0,1]
	v_pk_mul_f32 v[6:7], v[38:39], v[134:135] op_sel_hi:[0,1]
	s_waitcnt vmcnt(0) lgkmcnt(0)
	v_pk_mul_f32 v[0:1], v[4:5], v[0:1]
	v_pk_mul_f32 v[4:5], v[38:39], v[100:101] op_sel_hi:[0,1]
	v_pk_mul_f32 v[2:3], v[4:5], v[2:3]
	v_cvt_pk_bf16_f32 v0, v0, v1
	v_cvt_pk_bf16_f32 v1, v2, v3
	flat_load_dwordx4 v[2:5], v[58:59] offset:144
	s_waitcnt vmcnt(0) lgkmcnt(0)
	v_pk_mul_f32 v[2:3], v[6:7], v[2:3]
	v_pk_mul_f32 v[6:7], v[38:39], v[122:123] op_sel_hi:[0,1]
	v_pk_mul_f32 v[4:5], v[6:7], v[4:5]
	v_cvt_pk_bf16_f32 v2, v2, v3
	v_cvt_pk_bf16_f32 v3, v4, v5
	global_store_dwordx4 v[68:69], v[0:3], off offset:64
	flat_load_dwordx4 v[0:3], v[58:59] offset:160
	v_pk_mul_f32 v[4:5], v[38:39], v[48:49] op_sel_hi:[0,1]
	v_pk_mul_f32 v[6:7], v[38:39], v[46:47] op_sel_hi:[0,1]
	s_waitcnt vmcnt(0) lgkmcnt(0)
	v_pk_mul_f32 v[0:1], v[4:5], v[0:1]
	v_pk_mul_f32 v[4:5], v[38:39], v[130:131] op_sel_hi:[0,1]
	v_pk_mul_f32 v[2:3], v[4:5], v[2:3]
	v_cvt_pk_bf16_f32 v0, v0, v1
	v_cvt_pk_bf16_f32 v1, v2, v3
	flat_load_dwordx4 v[2:5], v[58:59] offset:176
	s_waitcnt vmcnt(0) lgkmcnt(0)
	v_pk_mul_f32 v[2:3], v[6:7], v[2:3]
	v_pk_mul_f32 v[6:7], v[38:39], v[50:51] op_sel_hi:[0,1]
	v_pk_mul_f32 v[4:5], v[6:7], v[4:5]
	v_cvt_pk_bf16_f32 v2, v2, v3
	v_cvt_pk_bf16_f32 v3, v4, v5
	global_store_dwordx4 v[68:69], v[0:3], off offset:80
	flat_load_dwordx4 v[0:3], v[58:59] offset:192
	v_pk_mul_f32 v[4:5], v[38:39], v[120:121] op_sel_hi:[0,1]
	v_pk_mul_f32 v[6:7], v[38:39], v[42:43] op_sel_hi:[0,1]
	s_waitcnt vmcnt(0) lgkmcnt(0)
	v_pk_mul_f32 v[0:1], v[4:5], v[0:1]
	v_pk_mul_f32 v[4:5], v[38:39], v[98:99] op_sel_hi:[0,1]
	v_pk_mul_f32 v[2:3], v[4:5], v[2:3]
	v_cvt_pk_bf16_f32 v0, v0, v1
	v_cvt_pk_bf16_f32 v1, v2, v3
	flat_load_dwordx4 v[2:5], v[58:59] offset:208
	s_waitcnt vmcnt(0) lgkmcnt(0)
	v_pk_mul_f32 v[2:3], v[6:7], v[2:3]
	v_pk_mul_f32 v[6:7], v[38:39], v[92:93] op_sel_hi:[0,1]
	v_pk_mul_f32 v[4:5], v[6:7], v[4:5]
	v_cvt_pk_bf16_f32 v2, v2, v3
	v_cvt_pk_bf16_f32 v3, v4, v5
	global_store_dwordx4 v[68:69], v[0:3], off offset:96
	flat_load_dwordx4 v[0:3], v[58:59] offset:224
	v_pk_mul_f32 v[4:5], v[38:39], v[86:87] op_sel_hi:[0,1]
	v_pk_mul_f32 v[6:7], v[38:39], v[40:41] op_sel_hi:[0,1]
	s_waitcnt vmcnt(0) lgkmcnt(0)
	v_pk_mul_f32 v[0:1], v[4:5], v[0:1]
	v_pk_mul_f32 v[4:5], v[38:39], v[84:85] op_sel_hi:[0,1]
	v_pk_mul_f32 v[2:3], v[4:5], v[2:3]
	v_cvt_pk_bf16_f32 v0, v0, v1
	v_cvt_pk_bf16_f32 v1, v2, v3
	flat_load_dwordx4 v[2:5], v[58:59] offset:240
	s_waitcnt vmcnt(0) lgkmcnt(0)
	v_pk_mul_f32 v[2:3], v[6:7], v[2:3]
	v_pk_mul_f32 v[6:7], v[38:39], v[36:37] op_sel_hi:[0,1]
	v_pk_mul_f32 v[4:5], v[6:7], v[4:5]
	v_cvt_pk_bf16_f32 v2, v2, v3
	v_cvt_pk_bf16_f32 v3, v4, v5
	global_store_dwordx4 v[68:69], v[0:3], off offset:112
	s_nop 1
	v_pk_mul_f32 v[0:1], v[34:35], v[74:75] op_sel_hi:[0,1]
	v_pk_mul_f32 v[4:5], v[0:1], s[0:1] op_sel_hi:[1,0]
	flat_load_dwordx4 v[0:3], v[58:59] offset:256
	s_waitcnt vmcnt(0) lgkmcnt(0)
; DI unsigned cvtpk(float lo, float hi) { f32x2_t v = {lo, hi}; bf16x2_t b = __builtin_convertvector(v, bf16x2_t); return __builtin_bit_cast(unsigned, b); }
; #define UNPK(W_, E_) const float E_[8] = {bflo((W_).x), bfhi((W_).x), bflo((W_).y), bfhi((W_).y), bflo((W_).z), bfhi((W_).z), bflo((W_).w), bfhi((W_).w)}
; #define ROPE32(xr) _Pragma("unroll") for (int ax = 0; ax < 2; ++ax) _Pragma("unroll") for (int f = 0; f < 8; ++f) { const float x1 = xr[16 * ax + f], x2 = xr[16 * ax + 8 + f], c = cs[8 * ax + f], sv = sn[8 * ax + f]; xr[16 * ax + f] = x1 * c - x2 * sv; xr[16 * ax + 8 + f] = x2 * c + x1 * sv; }
; DI void phase_mla_fin(ArgsP a, int tb_, int l, char* shm, int vcu, int G) {
;     ...
;             for (int i = 0; i < 4; ++i) { UNPK(w[8 + i], e);
; #pragma unroll
;                 for (int j = 0; j < 8; ++j) xr[8 * i + j] = e[j] * rn * C2 * gqn[64 + 8 * i + j]; }
;             ROPE32(xr)
; #pragma unroll
;             for (int i = 0; i < 4; ++i) { u32x4 ow; ow.x = cvtpk(xr[8 * i], xr[8 * i + 1]); ow.y = cvtpk(xr[8 * i + 2], xr[8 * i + 3]); ow.z = cvtpk(xr[8 * i + 4], xr[8 * i + 5]); ow.w = cvtpk(xr[8 * i + 6], xr[8 * i + 7]); o[8 + i] = ow; }
	v_pk_mul_f32 v[6:7], v[4:5], v[0:1]
	v_pk_mul_f32 v[0:1], v[34:35], v[78:79] op_sel_hi:[0,1]
	v_pk_mul_f32 v[0:1], v[0:1], s[0:1] op_sel_hi:[1,0]
	s_nop 0
	v_pk_mul_f32 v[4:5], v[0:1], v[2:3]
	v_pk_mul_f32 v[0:1], v[34:35], v[88:89] op_sel_hi:[0,1]
	v_pk_mul_f32 v[36:37], v[0:1], s[0:1] op_sel_hi:[1,0]
	flat_load_dwordx4 v[0:3], v[58:59] offset:272
	s_waitcnt vmcnt(0) lgkmcnt(0)
	v_pk_mul_f32 v[38:39], v[36:37], v[0:1]
	v_pk_mul_f32 v[0:1], v[34:35], v[90:91] op_sel_hi:[0,1]
	v_pk_mul_f32 v[0:1], v[0:1], s[0:1] op_sel_hi:[1,0]
	s_nop 0
	v_pk_mul_f32 v[36:37], v[0:1], v[2:3]
	v_pk_mul_f32 v[0:1], v[34:35], v[70:71] op_sel_hi:[0,1]
	v_pk_mul_f32 v[40:41], v[0:1], s[0:1] op_sel_hi:[1,0]
	flat_load_dwordx4 v[0:3], v[58:59] offset:288
	s_waitcnt vmcnt(0) lgkmcnt(0)
	v_pk_mul_f32 v[46:47], v[40:41], v[0:1]
	v_pk_mul_f32 v[0:1], v[34:35], v[60:61] op_sel_hi:[0,1]
	v_pk_mul_f32 v[0:1], v[0:1], s[0:1] op_sel_hi:[1,0]
	s_nop 0
	v_pk_mul_f32 v[42:43], v[0:1], v[2:3]
	v_pk_mul_f32 v[0:1], v[34:35], v[72:73] op_sel_hi:[0,1]
	v_pk_mul_f32 v[40:41], v[0:1], s[0:1] op_sel_hi:[1,0]
	flat_load_dwordx4 v[0:3], v[58:59] offset:304
	s_waitcnt vmcnt(0) lgkmcnt(0)
	v_pk_mul_f32 v[60:61], v[40:41], v[0:1]
	v_pk_mul_f32 v[0:1], v[34:35], v[66:67] op_sel_hi:[0,1]
	v_pk_mul_f32 v[0:1], v[0:1], s[0:1] op_sel_hi:[1,0]
	s_nop 0
	v_pk_mul_f32 v[48:49], v[0:1], v[2:3]
	v_pk_mul_f32 v[0:1], v[34:35], v[80:81] op_sel_hi:[0,1]
	v_pk_mul_f32 v[40:41], v[0:1], s[0:1] op_sel_hi:[1,0]
	flat_load_dwordx4 v[0:3], v[58:59] offset:320
	s_waitcnt vmcnt(0) lgkmcnt(0)
	v_pk_mul_f32 v[66:67], v[40:41], v[0:1]
	v_pk_mul_f32 v[0:1], v[34:35], v[82:83] op_sel_hi:[0,1]
	v_pk_mul_f32 v[0:1], v[0:1], s[0:1] op_sel_hi:[1,0]
	s_nop 0
	v_pk_mul_f32 v[50:51], v[0:1], v[2:3]
	v_pk_mul_f32 v[0:1], v[34:35], v[94:95] op_sel_hi:[0,1]
	v_pk_mul_f32 v[40:41], v[0:1], s[0:1] op_sel_hi:[1,0]
	flat_load_dwordx4 v[0:3], v[58:59] offset:336
	s_waitcnt vmcnt(0) lgkmcnt(0)
	v_pk_mul_f32 v[70:71], v[40:41], v[0:1]
	v_pk_mul_f32 v[0:1], v[34:35], v[96:97] op_sel_hi:[0,1]
	v_pk_mul_f32 v[0:1], v[0:1], s[0:1] op_sel_hi:[1,0]
	s_nop 0
	v_pk_mul_f32 v[40:41], v[0:1], v[2:3]
	v_pk_mul_f32 v[0:1], v[34:35], v[62:63] op_sel_hi:[0,1]
	v_pk_mul_f32 v[62:63], v[0:1], s[0:1] op_sel_hi:[1,0]
	flat_load_dwordx4 v[0:3], v[58:59] offset:352
	s_waitcnt vmcnt(0) lgkmcnt(0)
	v_pk_mul_f32 v[72:73], v[62:63], v[0:1]
	v_pk_mul_f32 v[0:1], v[34:35], v[64:65] op_sel_hi:[0,1]
	v_pk_mul_f32 v[0:1], v[0:1], s[0:1] op_sel_hi:[1,0]
	s_nop 0
	v_pk_mul_f32 v[62:63], v[0:1], v[2:3]
	v_pk_mul_f32 v[0:1], v[34:35], v[76:77] op_sel_hi:[0,1]
	v_pk_mul_f32 v[64:65], v[0:1], s[0:1] op_sel_hi:[1,0]
	flat_load_dwordx4 v[0:3], v[58:59] offset:368
	v_pk_mul_f32 v[34:35], v[34:35], v[54:55] op_sel_hi:[0,1]
	v_pk_mul_f32 v[34:35], v[34:35], s[0:1] op_sel_hi:[1,0]
	s_waitcnt vmcnt(0) lgkmcnt(0)
	v_pk_mul_f32 v[0:1], v[64:65], v[0:1]
	v_pk_mul_f32 v[2:3], v[34:35], v[2:3]
	v_pk_mul_f32 v[34:35], v[24:25], v[46:47]
	v_pk_mul_f32 v[46:47], v[28:29], v[46:47]
	v_pk_fma_f32 v[64:65], v[28:29], v[6:7], v[34:35]
	v_pk_fma_f32 v[58:59], v[24:25], v[6:7], v[46:47] neg_lo:[0,0,1] neg_hi:[0,0,1]
	v_pk_mul_f32 v[6:7], v[26:27], v[42:43]
	v_pk_mul_f32 v[24:25], v[30:31], v[42:43]
	v_pk_fma_f32 v[74:75], v[30:31], v[4:5], v[6:7]
	v_pk_fma_f32 v[34:35], v[26:27], v[4:5], v[24:25] neg_lo:[0,0,1] neg_hi:[0,0,1]
	v_pk_mul_f32 v[4:5], v[16:17], v[60:61]
	v_pk_mul_f32 v[6:7], v[20:21], v[60:61]
	v_pk_fma_f32 v[78:79], v[20:21], v[38:39], v[4:5]
	v_pk_fma_f32 v[76:77], v[16:17], v[38:39], v[6:7] neg_lo:[0,0,1] neg_hi:[0,0,1]
	v_pk_mul_f32 v[4:5], v[18:19], v[48:49]
	v_pk_mul_f32 v[6:7], v[22:23], v[48:49]
	v_pk_fma_f32 v[80:81], v[22:23], v[36:37], v[4:5]
	v_pk_fma_f32 v[38:39], v[18:19], v[36:37], v[6:7] neg_lo:[0,0,1] neg_hi:[0,0,1]
	v_pk_mul_f32 v[4:5], v[8:9], v[72:73]
	v_pk_mul_f32 v[6:7], v[12:13], v[72:73]
	s_nop 0
	v_pk_fma_f32 v[36:37], v[8:9], v[66:67], v[6:7] neg_lo:[0,0,1] neg_hi:[0,0,1]
	v_pk_fma_f32 v[66:67], v[12:13], v[66:67], v[4:5]
	v_pk_mul_f32 v[4:5], v[32:33], v[62:63]
	v_pk_mul_f32 v[6:7], v[44:45], v[62:63]
	v_pk_fma_f32 v[42:43], v[44:45], v[50:51], v[4:5]
	v_pk_mul_f32 v[4:5], v[52:53], v[0:1]
	v_pk_mul_f32 v[0:1], v[56:57], v[0:1]
	v_pk_fma_f32 v[32:33], v[32:33], v[50:51], v[6:7] neg_lo:[0,0,1] neg_hi:[0,0,1]
	v_pk_fma_f32 v[44:45], v[52:53], v[70:71], v[0:1] neg_lo:[0,0,1] neg_hi:[0,0,1]
	v_pk_mul_f32 v[0:1], v[10:11], v[2:3]
	v_pk_mul_f32 v[2:3], v[14:15], v[2:3]
	v_pk_fma_f32 v[48:49], v[56:57], v[70:71], v[4:5]
	v_pk_fma_f32 v[50:51], v[10:11], v[40:41], v[2:3] neg_lo:[0,0,1] neg_hi:[0,0,1]
	v_pk_fma_f32 v[40:41], v[14:15], v[40:41], v[0:1]
	s_branch .LBB0_964

; DI int lane_asm() { int l_; asm volatile("v_mbcnt_lo_u32_b32 %0, -1, 0\n\tv_mbcnt_hi_u32_b32 %0, -1, %0" : "=v"(l_)); return l_; }
; DI void phase_gla3(ArgsP a, int tb_, int l, bool with_ctx, char* shm, int vcu, int G) {
;     int tid_ = tb_ + lane_asm(); asm volatile("" : "+v"(tid_)); const int tid = tid_, lane = tid & 63, r32 = lane & 31, hi = lane >> 5, wid = tid >> 6;
;     const bf16_t* zr = (const bf16_t*)(a->ws + A_ZR); const bf16_t* ST = (const bf16_t*)(a->ws + A_ST); bf16_t* og = (bf16_t*)(a->ws + A_OG);
;     float* LA = (float*)shm; char* QT = shm + 33792; char* KTt = shm + 52224; char* VT = shm + 70656; char* AM = shm + 89088; float* OS = (float*)shm;
;     const float* ggl = a->in[I_GGLA] + l * 128;
;     for (int bh = vcu >> 3; bh < 32; bh += (G >> 3)) {
;         const int h = bh & 3, b = bh >> 2;
;         const int ldir = wid >> 2, ljb = (wid >> 1) & 1, lkb = wid & 1;
;         const float* wa2 = a->in[I_WA2] + ((size_t)l * 2 + ldir) * 16 * 256 + h * 64; const float* ba2 = a->in[I_BA2] + ((size_t)l * 2 + ldir) * 256 + h * 64;
;         const bf16x8 wfr = gla_wfrag(wa2, lkb * 32 + r32, hi); const float bias = ba2[lkb * 32 + r32];
;         const int j = tid >> 3, kg = tid & 7;
;     ...
;         int pst = vcu & 7; if (pst < 4 && !with_ctx) pst += 8;
;         bf16x8 ngfr; u32x4 nqw, nkw, nv0, nv1;
;         GLA3_LOAD(pst, ngfr, nqw, nkw, nv0, nv1);
;         for (int p = pst; p < NSLOT; p += 8) {
;             const int m0 = GLA3_M0(p);
;             const int slot_f = p, slot_b = p < 4 ? 3 - p : 71 - p;
.LBB0_1413:
	s_mov_b64 s[6:7], s[64:65]
	s_ashr_i32 s5, s2, 3
	v_mbcnt_lo_u32_b32 v0, -1, 0
	v_mbcnt_hi_u32_b32 v0, -1, v0
	s_cmp_gt_i32 s5, 31
	v_add_u32_e32 v0, s1, v0
	s_cbranch_scc1 .LBB0_1421
	s_and_b32 s2, s2, 7
	s_cmp_gt_u32 s2, 3
	s_cselect_b64 s[8:9], -1, 0
	s_or_b64 s[8:9], s[68:69], s[8:9]
	s_or_b32 s10, s2, 8
	s_and_b64 s[8:9], s[8:9], exec
	s_load_dwordx2 s[54:55], s[6:7], 0xf0
	s_cselect_b32 s85, s2, s10
	s_load_dwordx4 s[8:11], s[6:7], 0xa0
	s_nop 0
	s_load_dwordx2 s[6:7], s[6:7], 0xb0
	v_ashrrev_i32_e32 v2, 8, v0
	s_cmp_lt_u32 s85, 4
	s_mov_b32 s35, s81
	v_ashrrev_i32_e32 v1, 6, v0
	v_ashrrev_i32_e32 v3, 31, v2
	s_cselect_b64 s[82:83], -1, 0
	s_lshl_b32 s2, s85, 6
	v_lshl_add_u64 v[4:5], v[2:3], 0, s[34:35]
	v_lshlrev_b32_e32 v3, 5, v1
	s_add_i32 s71, s2, 0xffffff00
	s_or_b32 s75, s2, 0x8000
	v_and_b32_e32 v10, 31, v0
	v_bfe_u32 v13, v0, 5, 1
	v_lshlrev_b64 v[6:7], 14, v[4:5]
	v_and_b32_e32 v3, 32, v3
	s_waitcnt lgkmcnt(0)
	s_add_u32 s68, s54, 0xe800000
	v_lshl_add_u64 v[6:7], s[8:9], 0, v[6:7]
	v_lshlrev_b64 v[4:5], 10, v[4:5]
	v_or_b32_e32 v14, v3, v10
	v_lshlrev_b32_e32 v188, 13, v13
	s_addc_u32 s69, s55, 0
	s_lshl_b32 s80, s26, 7
	v_lshl_add_u64 v[4:5], s[10:11], 0, v[4:5]
	v_lshl_add_u64 v[6:7], v[6:7], 0, v[188:189]
	v_lshlrev_b32_e32 v188, 2, v14
	s_lshl_b64 s[12:13], s[80:81], 2
	v_lshl_add_u64 v[58:59], v[4:5], 0, v[188:189]
	v_and_b32_e32 v15, 7, v0
	v_lshrrev_b32_e32 v4, 2, v0
	s_add_u32 s60, s6, s12
	v_and_b32_e32 v16, 32, v4
	v_lshlrev_b32_e32 v4, 5, v15
	v_mov_b32_e32 v5, v189
	s_addc_u32 s61, s7, s13
	v_lshl_add_u64 v[8:9], s[54:55], 0, v[4:5]
	s_mov_b64 s[6:7], 0xc600000
	v_lshl_add_u32 v11, v10, 2, 0
	v_lshl_add_u64 v[56:57], v[6:7], 0, v[188:189]
	v_lshlrev_b32_e32 v62, 3, v13
	v_lshlrev_b32_e32 v3, 2, v3
	v_lshlrev_b32_e32 v188, 4, v13
	v_lshl_add_u64 v[68:69], v[8:9], 0, s[6:7]
	v_lshlrev_b32_e32 v8, 2, v13
	v_mul_i32_i24_e32 v13, 0x4100, v2
	v_and_b32_e32 v12, 63, v0
	v_add3_u32 v13, v11, v3, v13
	v_bitop3_b32 v3, v0, 63, v0 bitop3:0xc
	v_cmp_gt_u32_e32 vcc, s96, v0
	s_movk_i32 s6, 0x4100
	v_ashrrev_i32_e32 v63, 3, v0
	v_cndmask_b32_e32 v3, v3, v12, vcc
	v_or_b32_e32 v65, v16, v10
	v_or_b32_e32 v9, v8, v16
	v_mad_i32_i24 v16, v2, s6, 0
	v_mul_u32_u24_e32 v3, 0x104, v3
	v_and_b32_e32 v0, 0xc0, v0
	v_add3_u32 v67, v16, v3, v0
	v_and_b32_e32 v21, 3, v1
	v_lshlrev_b32_e32 v0, 7, v10
	v_lshl_add_u64 v[6:7], s[54:55], 0, v[188:189]
	s_movk_i32 s18, 0x104
	v_lshl_or_b32 v0, v21, 12, v0
	v_mov_b32_e32 v1, v189
	v_lshlrev_b32_e32 v3, 2, v12
	v_cmp_eq_u32_e64 s[6:7], 0, v12
	v_cmp_gt_u32_e64 s[8:9], 2, v12
	v_cmp_gt_u32_e64 s[10:11], 4, v12
	v_cmp_gt_u32_e64 s[12:13], 8, v12
	v_cmp_gt_u32_e64 s[14:15], 16, v12
	v_cmp_gt_u32_e64 s[16:17], 32, v12
	v_mul_lo_u32 v12, v63, s18
	v_lshl_add_u64 v[6:7], v[6:7], 0, v[0:1]
	s_mov_b64 s[20:21], 0x1a300000
	s_movk_i32 s18, 0x2400
	v_lshl_add_u64 v[70:71], v[6:7], 0, s[20:21]
	v_mul_i32_i24_e32 v1, 0x2400, v2
	v_mad_i32_i24 v6, v2, s18, 0
	v_lshlrev_b32_e32 v22, 1, v14
	v_readlane_b32 s18, v255, 8
	v_lshlrev_b32_e32 v60, 4, v2
	s_movk_i32 s19, 0x90
	v_add3_u32 v22, s18, v1, v22
	v_lshlrev_b32_e32 v1, 5, v2
	v_or_b32_e32 v2, v1, v10
	v_mul_lo_u32 v2, v2, s19
	v_add_u32_e32 v23, s18, v2
	v_readlane_b32 s18, v255, 9
	v_lshl_or_b32 v10, v21, 5, v10
	v_mul_lo_u32 v16, v63, s19
	v_mov_b32_e32 v24, s18
	s_movk_i32 s18, 0x900
	v_mad_u32_u24 v7, v65, s19, v6
	v_mad_u32_u24 v6, v14, s19, v6
	v_mad_u32_u24 v10, v10, s19, v24
	v_mad_u32_u24 v24, v15, s18, v24
	v_cmp_le_u32_e64 s[18:19], v14, v9
	v_add_u32_e32 v25, 0, v2
	v_or_b32_e32 v2, 1, v9
	v_cndmask_b32_e64 v39, 0, 1, s[18:19]
	v_cmp_ge_u32_e64 s[18:19], v14, v9
	v_cmp_le_u32_e64 s[20:21], v14, v2
	v_add_u32_e32 v88, -4, v3
	v_cndmask_b32_e64 v40, 0, 1, s[18:19]
	v_cndmask_b32_e32 v39, v40, v39, vcc
	v_and_b32_e32 v39, 1, v39
	v_cndmask_b32_e64 v2, 0, 1, s[20:21]
	v_cmp_gt_u32_e64 s[20:21], v14, v9
	v_add_u32_e32 v89, -8, v3
	v_add_u32_e32 v90, -16, v3
	v_subrev_u32_e32 v91, 32, v3
	v_subrev_u32_e32 v92, 64, v3
	v_add_u32_e32 v93, 0xffffff80, v3
	v_or_b32_e32 v1, v8, v1
	v_lshl_add_u32 v8, v21, 7, v11
	v_xor_b32_e32 v94, 4, v3
	v_xor_b32_e32 v95, 8, v3
	v_xor_b32_e32 v96, 16, v3
	v_mul_u32_u24_e32 v21, 0x104, v9
	v_or_b32_e32 v3, 2, v9
	v_or_b32_e32 v26, 3, v9
	v_or_b32_e32 v27, 8, v9
	v_or_b32_e32 v28, 9, v9
	v_or_b32_e32 v29, 10, v9
	v_or_b32_e32 v30, 11, v9
	v_or_b32_e32 v31, 16, v9
	v_or_b32_e32 v32, 17, v9
	v_or_b32_e32 v33, 18, v9
	v_or_b32_e32 v34, 19, v9
	v_or_b32_e32 v35, 24, v9
	v_or_b32_e32 v36, 25, v9
	v_or_b32_e32 v37, 26, v9
	v_or_b32_e32 v38, 27, v9
	v_cmp_eq_u32_e64 s[18:19], 1, v39
	v_mul_u32_u24_e32 v39, 0x90, v9
	v_cndmask_b32_e64 v9, 0, 1, s[20:21]
	v_cndmask_b32_e32 v2, v9, v2, vcc
	v_and_b32_e32 v2, 1, v2
	v_cmp_le_u32_e64 s[22:23], v14, v3
	v_cmp_eq_u32_e64 s[20:21], 1, v2
; DI float silu_f(float x) { return x * sigm_f(x); }
; DI int lane_asm() { int l_; asm volatile("v_mbcnt_lo_u32_b32 %0, -1, 0\n\tv_mbcnt_hi_u32_b32 %0, -1, %0" : "=v"(l_)); return l_; }
; DI void phase_gla3(ArgsP a, int tb_, int l, bool with_ctx, char* shm, int vcu, int G) {
;     int tid_ = tb_ + lane_asm(); asm volatile("" : "+v"(tid_)); const int tid = tid_, lane = tid & 63, r32 = lane & 31, hi = lane >> 5, wid = tid >> 6;
;     const bf16_t* zr = (const bf16_t*)(a->ws + A_ZR); const bf16_t* ST = (const bf16_t*)(a->ws + A_ST); bf16_t* og = (bf16_t*)(a->ws + A_OG);
;     float* LA = (float*)shm; char* QT = shm + 33792; char* KTt = shm + 52224; char* VT = shm + 70656; char* AM = shm + 89088; float* OS = (float*)shm;
;     const float* ggl = a->in[I_GGLA] + l * 128;
;     for (int bh = vcu >> 3; bh < 32; bh += (G >> 3)) {
;         const int h = bh & 3, b = bh >> 2;
;         const int ldir = wid >> 2, ljb = (wid >> 1) & 1, lkb = wid & 1;
;         const float* wa2 = a->in[I_WA2] + ((size_t)l * 2 + ldir) * 16 * 256 + h * 64; const float* ba2 = a->in[I_BA2] + ((size_t)l * 2 + ldir) * 256 + h * 64;
;         const bf16x8 wfr = gla_wfrag(wa2, lkb * 32 + r32, hi); const float bias = ba2[lkb * 32 + r32];
;         const int j = tid >> 3, kg = tid & 7;
;     ...
;         int pst = vcu & 7; if (pst < 4 && !with_ctx) pst += 8;
;         bf16x8 ngfr; u32x4 nqw, nkw, nv0, nv1;
;         GLA3_LOAD(pst, ngfr, nqw, nkw, nv0, nv1);
;         for (int p = pst; p < NSLOT; p += 8) {
;             const int m0 = GLA3_M0(p);
;             const int slot_f = p, slot_b = p < 4 ? 3 - p : 71 - p;
;             const bf16x8 gfr = ngfr; const u32x4 qw = nqw, kw = nkw, v0 = nv0, v1 = nv1;
;             if (p + 8 < NSLOT) GLA3_LOAD(p + 8, ngfr, nqw, nkw, nv0, nv1);
;     ...
;               for (int q = 0; q < 16; ++q) y[q] = o[q] * rn * ggl[vg * 16 + q] * silu_f(gr[q]);
	v_cmp_le_u32_e64 s[24:25], v14, v26
	v_cndmask_b32_e64 v2, 0, 1, s[22:23]
	v_cmp_ge_u32_e64 s[22:23], v14, v3
	v_cmp_le_u32_e64 s[26:27], v14, v27
	v_cmp_le_u32_e64 s[28:29], v14, v28
	v_cndmask_b32_e64 v3, 0, 1, s[22:23]
	v_cndmask_b32_e32 v2, v3, v2, vcc
	v_and_b32_e32 v2, 1, v2
	v_cmp_eq_u32_e64 s[22:23], 1, v2
	v_cndmask_b32_e64 v2, 0, 1, s[24:25]
	v_cmp_ge_u32_e64 s[24:25], v14, v26
	v_cmp_le_u32_e64 s[30:31], v14, v29
	v_cmp_le_u32_e64 s[34:35], v14, v30
	v_cndmask_b32_e64 v3, 0, 1, s[24:25]
	v_cndmask_b32_e32 v2, v3, v2, vcc
	v_and_b32_e32 v2, 1, v2
	v_cmp_eq_u32_e64 s[24:25], 1, v2
	v_cndmask_b32_e64 v2, 0, 1, s[26:27]
	v_cmp_ge_u32_e64 s[26:27], v14, v27
	v_cmp_le_u32_e64 s[36:37], v14, v31
	v_cmp_le_u32_e64 s[38:39], v14, v32
	v_cndmask_b32_e64 v3, 0, 1, s[26:27]
	v_cndmask_b32_e32 v2, v3, v2, vcc
	v_and_b32_e32 v2, 1, v2
	v_cmp_eq_u32_e64 s[26:27], 1, v2
	v_cndmask_b32_e64 v2, 0, 1, s[28:29]
	v_cmp_ge_u32_e64 s[28:29], v14, v28
	v_cmp_le_u32_e64 s[40:41], v14, v33
	v_cmp_le_u32_e64 s[42:43], v14, v34
	v_cndmask_b32_e64 v3, 0, 1, s[28:29]
	v_cndmask_b32_e32 v2, v3, v2, vcc
	v_and_b32_e32 v2, 1, v2
	v_cmp_eq_u32_e64 s[28:29], 1, v2
	v_cndmask_b32_e64 v2, 0, 1, s[30:31]
	v_cmp_ge_u32_e64 s[30:31], v14, v29
	v_cmp_le_u32_e64 s[44:45], v14, v35
	v_cmp_le_u32_e64 s[46:47], v14, v36
	v_cndmask_b32_e64 v3, 0, 1, s[30:31]
	v_cndmask_b32_e32 v2, v3, v2, vcc
	v_and_b32_e32 v2, 1, v2
	v_cmp_eq_u32_e64 s[30:31], 1, v2
	v_cndmask_b32_e64 v2, 0, 1, s[34:35]
	v_cmp_ge_u32_e64 s[34:35], v14, v30
	v_cmp_le_u32_e64 s[48:49], v14, v37
	v_cmp_le_u32_e64 s[50:51], v14, v38
	v_cndmask_b32_e64 v3, 0, 1, s[34:35]
	v_cndmask_b32_e32 v2, v3, v2, vcc
	v_and_b32_e32 v2, 1, v2
	v_cmp_eq_u32_e64 s[34:35], 1, v2
	v_cndmask_b32_e64 v2, 0, 1, s[36:37]
	v_cmp_ge_u32_e64 s[36:37], v14, v31
	s_movk_i32 s33, 0x210
	v_lshlrev_b32_e32 v66, 4, v15
	v_cndmask_b32_e64 v3, 0, 1, s[36:37]
	v_cndmask_b32_e32 v2, v3, v2, vcc
	v_and_b32_e32 v2, 1, v2
	v_cmp_eq_u32_e64 s[36:37], 1, v2
	v_cndmask_b32_e64 v2, 0, 1, s[38:39]
	v_cmp_ge_u32_e64 s[38:39], v14, v32
	v_add_u32_e32 v17, 0, v4
	v_mul_lo_u32 v11, v63, s33
	v_cndmask_b32_e64 v3, 0, 1, s[38:39]
	v_cndmask_b32_e32 v2, v3, v2, vcc
	v_and_b32_e32 v2, 1, v2
	v_cmp_eq_u32_e64 s[38:39], 1, v2
	v_cndmask_b32_e64 v2, 0, 1, s[40:41]
	v_cmp_ge_u32_e64 s[40:41], v14, v33
	v_mul_lo_u32 v9, v1, s33
	s_lshl_b32 s33, s85, 14
	v_cndmask_b32_e64 v3, 0, 1, s[40:41]
	v_cndmask_b32_e32 v2, v3, v2, vcc
	v_and_b32_e32 v2, 1, v2
	v_cmp_eq_u32_e64 s[40:41], 1, v2
	v_cndmask_b32_e64 v2, 0, 1, s[42:43]
	v_cmp_ge_u32_e64 s[42:43], v14, v34
	v_sub_u32_e32 v18, v17, v66
	v_or3_b32 v0, s33, v188, v0
	v_cndmask_b32_e64 v3, 0, 1, s[42:43]
	v_cndmask_b32_e32 v2, v3, v2, vcc
	v_and_b32_e32 v2, 1, v2
	v_cmp_eq_u32_e64 s[42:43], 1, v2
	v_cndmask_b32_e64 v2, 0, 1, s[44:45]
	v_cmp_ge_u32_e64 s[44:45], v14, v35
	v_mov_b32_e32 v1, v189
	s_lshl_b32 s96, s5, 1
	v_cndmask_b32_e64 v3, 0, 1, s[44:45]
	v_cndmask_b32_e32 v2, v3, v2, vcc
	v_and_b32_e32 v2, 1, v2
	v_cmp_eq_u32_e64 s[44:45], 1, v2
	v_cndmask_b32_e64 v2, 0, 1, s[46:47]
	v_cmp_ge_u32_e64 s[46:47], v14, v36
	s_lshl_b32 s97, s4, 1
	s_add_i32 s33, s2, 0x100
	v_cndmask_b32_e64 v3, 0, 1, s[46:47]
	v_cndmask_b32_e32 v2, v3, v2, vcc
	v_and_b32_e32 v2, 1, v2
	v_cmp_eq_u32_e64 s[46:47], 1, v2
	v_cndmask_b32_e64 v2, 0, 1, s[48:49]
	v_cmp_ge_u32_e64 s[48:49], v14, v37
	v_mad_u32_u24 v19, v15, 48, v18
	v_lshlrev_b32_e32 v20, 1, v63
	v_cndmask_b32_e64 v3, 0, 1, s[48:49]
	v_cndmask_b32_e32 v2, v3, v2, vcc
	v_and_b32_e32 v2, 1, v2
	v_cmp_eq_u32_e64 s[48:49], 1, v2
	v_cndmask_b32_e64 v2, 0, 1, s[50:51]
	v_cmp_ge_u32_e64 s[50:51], v14, v38
	v_lshl_add_u64 v[0:1], s[54:55], 0, v[0:1]
	s_mov_b64 s[54:55], 0x1a300040
	v_cndmask_b32_e64 v3, 0, 1, s[50:51]
	v_cndmask_b32_e32 v2, v3, v2, vcc
	v_and_b32_e32 v2, 1, v2
	v_cmp_eq_u32_e64 s[50:51], 1, v2
	v_lshlrev_b32_e32 v2, 6, v15
	v_mov_b32_e32 v3, v189
	s_sub_u32 s63, 0, s85
	v_ashrrev_i32_e32 v61, 31, v60
	v_lshlrev_b32_e32 v64, 3, v15
	v_lshl_add_u64 v[72:73], s[60:61], 0, v[2:3]
	global_load_dwordx4 v[192:195], v[72:73], off
	global_load_dwordx4 v[196:199], v[72:73], off offset:16
	global_load_dwordx4 v[200:203], v[72:73], off offset:32
	global_load_dwordx4 v[204:207], v[72:73], off offset:48
	s_waitcnt vmcnt(0)
	v_lshl_add_u64 v[74:75], s[68:69], 0, v[4:5]
	v_lshl_add_u64 v[76:77], v[0:1], 0, s[54:55]
	v_or_b32_e32 v97, s33, v65
	v_add_u32_e32 v98, s2, v63
	s_subb_u32 s52, 0, 0
	s_or_b32 s58, s96, 1
	v_add_u32_e32 v99, v13, v21
	v_add_u32_e32 v100, v17, v12
	v_add_u32_e32 v101, v18, v16
	v_add_u32_e32 v102, v24, v20
	v_add_u32_e32 v103, v7, v188
	v_add_u32_e32 v104, v6, v188
	v_add_u32_e32 v105, v22, v39
	v_add_u32_e32 v106, v23, v188
	v_add_u32_e32 v107, v10, v188
	v_add_u32_e32 v108, v25, v188
	v_add_u32_e32 v109, v8, v9
	v_add_u32_e32 v110, v19, v11
	s_branch .LBB0_1416

; DI int crow(int r, int hi) { return (r & 3) + 8 * (r >> 2) + 4 * hi; }
; DI float logsig(float x) { return fminf(x, 0.f) - __logf(1.f + __expf(-fabsf(x))); }
; DI void phase_gla3(ArgsP a, int tb_, int l, bool with_ctx, char* shm, int vcu, int G) {
;     ...
;             { f32x16 acc;
; #pragma unroll
;               for (int r = 0; r < 16; ++r) acc[r] = 0.f;
;               acc = __builtin_amdgcn_mfma_f32_32x32x16_bf16(gfr, wfr, acc, 0, 0, 0);
; #pragma unroll
;               for (int r = 0; r < 16; ++r) LA[ldir * 4160 + (ljb * 32 + crow(r, hi)) * 65 + lkb * 32 + r32] = logsig(acc[r] + bias) * (1.f / 16.f); }
.LBB0_1417:
	v_mfma_f32_32x32x16_bf16 v[0:15], v[0:3], v[16:19], 0
	v_lshlrev_b32_e32 v118, 16, v54
	v_and_b32_e32 v119, 0xffff0000, v54
	v_mul_f32_e64 v118, v118, s90
	v_mul_f32_e64 v119, v119, s90
	v_lshlrev_b32_e32 v120, 16, v50
	v_and_b32_e32 v121, 0xffff0000, v50
	v_lshlrev_b32_e32 v54, 16, v55
	v_and_b32_e32 v55, 0xffff0000, v55
	s_nop 3
	v_add_f32_e32 v0, v111, v0
	v_mul_f32_e64 v79, |v0|, s77
	v_exp_f32_e32 v79, v79
	v_add_f32_e32 v1, v111, v1
	v_mul_f32_e64 v81, |v1|, s77
	v_exp_f32_e32 v81, v81
	v_add_f32_e32 v79, 1.0, v79
	v_cmp_gt_f32_e32 vcc, s76, v79
	v_min_f32_e32 v0, 0, v0
	v_add_f32_e32 v81, 1.0, v81
	v_cndmask_b32_e64 v114, 0, 32, vcc
	v_ldexp_f32 v79, v79, v114
	v_log_f32_e32 v79, v79
	v_cmp_gt_f32_e64 s[54:55], s76, v81
	v_cndmask_b32_e32 v114, 0, v240, vcc
	v_add_f32_e32 v2, v111, v2
	v_cndmask_b32_e64 v115, 0, 32, s[54:55]
	v_ldexp_f32 v81, v81, v115
	v_mul_f32_e32 v115, 0x3f317217, v79
	v_log_f32_e32 v81, v81
	v_fma_f32 v115, v79, s62, -v115
	v_fmac_f32_e32 v115, 0x3377d1cf, v79
	v_cmp_lt_f32_e64 vcc, |v79|, s95
	v_fmac_f32_e32 v115, 0x3f317217, v79
	v_mul_f32_e32 v116, 0x3f317217, v81
	v_cndmask_b32_e32 v79, v79, v115, vcc
	v_sub_f32_e32 v79, v79, v114
	v_sub_f32_e32 v0, v0, v79
	v_fma_f32 v79, v81, s62, -v116
	v_fmac_f32_e32 v79, 0x3377d1cf, v81
	v_fmac_f32_e32 v79, 0x3f317217, v81
	v_cmp_lt_f32_e64 vcc, |v81|, s95
	v_cndmask_b32_e64 v114, 0, v240, s[54:55]
	v_min_f32_e32 v1, 0, v1
	v_cndmask_b32_e32 v79, v81, v79, vcc
	v_mul_f32_e64 v81, |v2|, s77
	v_exp_f32_e32 v81, v81
	v_sub_f32_e32 v79, v79, v114
	v_sub_f32_e32 v1, v1, v79
	v_mul_f32_e32 v0, 0x3d800000, v0
	v_add_f32_e32 v79, 1.0, v81
	v_cmp_gt_f32_e32 vcc, s76, v79
	v_mul_f32_e32 v1, 0x3d800000, v1
	ds_write2_b32 v99, v0, v1 offset1:65
	v_cndmask_b32_e64 v81, 0, 32, vcc
	v_ldexp_f32 v79, v79, v81
	v_log_f32_e32 v79, v79
	v_min_f32_e32 v0, 0, v2
	v_add_f32_e32 v2, v111, v3
	v_mul_f32_e64 v3, |v2|, s77
	v_exp_f32_e32 v3, v3
	v_mul_f32_e32 v1, 0x3f317217, v79
	v_fma_f32 v1, v79, s62, -v1
	v_fmac_f32_e32 v1, 0x3377d1cf, v79
	v_fmac_f32_e32 v1, 0x3f317217, v79
	v_cmp_lt_f32_e64 s[54:55], |v79|, s95
	v_add_f32_e32 v3, 1.0, v3
	v_pk_mul_f32 v[54:55], v[54:55], s[90:91] op_sel_hi:[1,0]
	v_cndmask_b32_e64 v1, v79, v1, s[54:55]
	v_cndmask_b32_e32 v79, 0, v240, vcc
	v_cmp_gt_f32_e32 vcc, s76, v3
	v_sub_f32_e32 v1, v1, v79
	v_sub_f32_e32 v0, v0, v1
	v_cndmask_b32_e64 v79, 0, 32, vcc
	v_ldexp_f32 v3, v3, v79
	v_log_f32_e32 v3, v3
	v_min_f32_e32 v1, 0, v2
	v_cndmask_b32_e32 v79, 0, v240, vcc
	v_mul_f32_e32 v0, 0x3d800000, v0
	v_mul_f32_e32 v2, 0x3f317217, v3
	v_fma_f32 v2, v3, s62, -v2
	v_fmac_f32_e32 v2, 0x3377d1cf, v3
	v_fmac_f32_e32 v2, 0x3f317217, v3
	v_cmp_lt_f32_e64 s[54:55], |v3|, s95
	v_lshlrev_b32_e32 v50, 16, v51
	v_and_b32_e32 v51, 0xffff0000, v51
	v_cndmask_b32_e64 v2, v3, v2, s[54:55]
	v_add_f32_e32 v3, v111, v4
	v_mul_f32_e64 v4, |v3|, s77
	v_exp_f32_e32 v4, v4
	v_sub_f32_e32 v2, v2, v79
	v_sub_f32_e32 v1, v1, v2
	v_mul_f32_e32 v1, 0x3d800000, v1
	v_add_f32_e32 v2, 1.0, v4
	v_cmp_gt_f32_e32 vcc, s76, v2
	ds_write2_b32 v99, v0, v1 offset0:130 offset1:195
	v_min_f32_e32 v0, 0, v3
	v_cndmask_b32_e64 v4, 0, 32, vcc
	v_ldexp_f32 v2, v2, v4
	v_log_f32_e32 v2, v2
	v_add_f32_e32 v3, v111, v5
	v_mul_f32_e64 v4, |v3|, s77
	v_exp_f32_e32 v4, v4
	v_mul_f32_e32 v1, 0x3f317217, v2
	v_fma_f32 v1, v2, s62, -v1
	v_fmac_f32_e32 v1, 0x3377d1cf, v2
	v_fmac_f32_e32 v1, 0x3f317217, v2
	v_cmp_lt_f32_e64 s[54:55], |v2|, s95
	s_cmp_lt_u32 s70, 4
	v_add_u32_e32 v113, 0x200, v113
	v_cndmask_b32_e64 v1, v2, v1, s[54:55]
	v_cndmask_b32_e32 v2, 0, v240, vcc
	v_sub_f32_e32 v1, v1, v2
	v_add_f32_e32 v2, 1.0, v4
	v_cmp_gt_f32_e32 vcc, s76, v2
	v_sub_f32_e32 v0, v0, v1
	v_min_f32_e32 v1, 0, v3
	v_cndmask_b32_e64 v4, 0, 32, vcc
	v_ldexp_f32 v2, v2, v4
	v_log_f32_e32 v2, v2
	v_add_f32_e32 v4, v111, v6
	v_mul_f32_e64 v5, |v4|, s77
	v_exp_f32_e32 v5, v5
	v_mul_f32_e32 v3, 0x3f317217, v2
	v_fma_f32 v3, v2, s62, -v3
	v_fmac_f32_e32 v3, 0x3377d1cf, v2
	v_fmac_f32_e32 v3, 0x3f317217, v2
	v_cmp_lt_f32_e64 s[54:55], |v2|, s95
	v_mul_f32_e32 v0, 0x3d800000, v0
	s_nop 0
	v_cndmask_b32_e64 v2, v2, v3, s[54:55]
	v_cndmask_b32_e32 v3, 0, v240, vcc
	v_sub_f32_e32 v2, v2, v3
	v_sub_f32_e32 v1, v1, v2
	v_add_f32_e32 v2, 1.0, v5
	v_cmp_gt_f32_e32 vcc, s76, v2
	v_mul_f32_e32 v1, 0x3d800000, v1
	s_nop 0
	v_cndmask_b32_e64 v3, 0, 32, vcc
	v_ldexp_f32 v2, v2, v3
	v_log_f32_e32 v2, v2
	v_add_u32_e32 v3, 0x800, v99
	ds_write2_b32 v3, v0, v1 offset0:8 offset1:73
	v_min_f32_e32 v0, 0, v4
	v_add_f32_e32 v4, v111, v7
	v_mul_f32_e32 v1, 0x3f317217, v2
	v_mul_f32_e64 v5, |v4|, s77
	v_fma_f32 v1, v2, s62, -v1
	v_exp_f32_e32 v5, v5
	v_fmac_f32_e32 v1, 0x3377d1cf, v2
	v_fmac_f32_e32 v1, 0x3f317217, v2
	v_cmp_lt_f32_e64 s[54:55], |v2|, s95
	s_nop 1
	v_cndmask_b32_e64 v1, v2, v1, s[54:55]
	v_cndmask_b32_e32 v2, 0, v240, vcc
	v_sub_f32_e32 v1, v1, v2
	v_add_f32_e32 v2, 1.0, v5
	v_cmp_gt_f32_e32 vcc, s76, v2
	v_sub_f32_e32 v0, v0, v1
	v_min_f32_e32 v1, 0, v4
	v_cndmask_b32_e64 v5, 0, 32, vcc
	v_ldexp_f32 v2, v2, v5
	v_log_f32_e32 v2, v2
	v_cndmask_b32_e32 v6, 0, v240, vcc
	v_mul_f32_e32 v0, 0x3d800000, v0
	v_mul_f32_e32 v4, 0x3f317217, v2
	v_fma_f32 v4, v2, s62, -v4
	v_fmac_f32_e32 v4, 0x3377d1cf, v2
	v_fmac_f32_e32 v4, 0x3f317217, v2
	v_cmp_lt_f32_e64 s[54:55], |v2|, s95
	s_nop 1
	v_cndmask_b32_e64 v2, v2, v4, s[54:55]
	v_add_f32_e32 v4, v111, v8
	v_mul_f32_e64 v5, |v4|, s77
	v_exp_f32_e32 v5, v5
	v_sub_f32_e32 v2, v2, v6
	v_sub_f32_e32 v1, v1, v2
	v_mul_f32_e32 v1, 0x3d800000, v1
	v_add_f32_e32 v2, 1.0, v5
	v_cmp_gt_f32_e32 vcc, s76, v2
	ds_write2_b32 v3, v0, v1 offset0:138 offset1:203
	v_add_f32_e32 v3, v111, v9
; DI int crow(int r, int hi) { return (r & 3) + 8 * (r >> 2) + 4 * hi; }
; DI float logsig(float x) { return fminf(x, 0.f) - __logf(1.f + __expf(-fabsf(x))); }
; DI void phase_gla3(ArgsP a, int tb_, int l, bool with_ctx, char* shm, int vcu, int G) {
;     ...
;               acc = __builtin_amdgcn_mfma_f32_32x32x16_bf16(gfr, wfr, acc, 0, 0, 0);
; #pragma unroll
;               for (int r = 0; r < 16; ++r) LA[ldir * 4160 + (ljb * 32 + crow(r, hi)) * 65 + lkb * 32 + r32] = logsig(acc[r] + bias) * (1.f / 16.f); }
;             __syncthreads();
	v_cndmask_b32_e64 v5, 0, 32, vcc
	v_ldexp_f32 v2, v2, v5
	v_log_f32_e32 v2, v2
	v_min_f32_e32 v0, 0, v4
	v_mul_f32_e64 v4, |v3|, s77
	v_exp_f32_e32 v4, v4
	v_mul_f32_e32 v1, 0x3f317217, v2
	v_fma_f32 v1, v2, s62, -v1
	v_fmac_f32_e32 v1, 0x3377d1cf, v2
	v_fmac_f32_e32 v1, 0x3f317217, v2
	v_cmp_lt_f32_e64 s[54:55], |v2|, s95
	s_nop 1
	v_cndmask_b32_e64 v1, v2, v1, s[54:55]
	v_cndmask_b32_e32 v2, 0, v240, vcc
	v_sub_f32_e32 v1, v1, v2
	v_add_f32_e32 v2, 1.0, v4
	v_cmp_gt_f32_e32 vcc, s76, v2
	v_sub_f32_e32 v0, v0, v1
	v_min_f32_e32 v1, 0, v3
	v_cndmask_b32_e64 v4, 0, 32, vcc
	v_ldexp_f32 v2, v2, v4
	v_log_f32_e32 v2, v2
	v_add_f32_e32 v4, v111, v10
	v_mul_f32_e64 v5, |v4|, s77
	v_exp_f32_e32 v5, v5
	v_mul_f32_e32 v3, 0x3f317217, v2
	v_fma_f32 v3, v2, s62, -v3
	v_fmac_f32_e32 v3, 0x3377d1cf, v2
	v_fmac_f32_e32 v3, 0x3f317217, v2
	v_cmp_lt_f32_e64 s[54:55], |v2|, s95
	v_mul_f32_e32 v0, 0x3d800000, v0
	s_nop 0
	v_cndmask_b32_e64 v2, v2, v3, s[54:55]
	v_cndmask_b32_e32 v3, 0, v240, vcc
	v_sub_f32_e32 v2, v2, v3
	v_sub_f32_e32 v1, v1, v2
	v_add_f32_e32 v2, 1.0, v5
	v_cmp_gt_f32_e32 vcc, s76, v2
	v_mul_f32_e32 v1, 0x3d800000, v1
	s_nop 0
	v_cndmask_b32_e64 v3, 0, 32, vcc
	v_ldexp_f32 v2, v2, v3
	v_log_f32_e32 v2, v2
	v_add_u32_e32 v3, 0x1000, v99
	ds_write2_b32 v3, v0, v1 offset0:16 offset1:81
	v_min_f32_e32 v0, 0, v4
	v_add_f32_e32 v4, v111, v11
	v_mul_f32_e32 v1, 0x3f317217, v2
	v_mul_f32_e64 v5, |v4|, s77
	v_fma_f32 v1, v2, s62, -v1
	v_exp_f32_e32 v5, v5
	v_fmac_f32_e32 v1, 0x3377d1cf, v2
	v_fmac_f32_e32 v1, 0x3f317217, v2
	v_cmp_lt_f32_e64 s[54:55], |v2|, s95
	s_nop 1
	v_cndmask_b32_e64 v1, v2, v1, s[54:55]
	v_cndmask_b32_e32 v2, 0, v240, vcc
	v_sub_f32_e32 v1, v1, v2
	v_add_f32_e32 v2, 1.0, v5
	v_cmp_gt_f32_e32 vcc, s76, v2
	v_sub_f32_e32 v0, v0, v1
	v_min_f32_e32 v1, 0, v4
	v_cndmask_b32_e64 v5, 0, 32, vcc
	v_ldexp_f32 v2, v2, v5
	v_log_f32_e32 v2, v2
	v_cndmask_b32_e32 v6, 0, v240, vcc
	v_mul_f32_e32 v0, 0x3d800000, v0
	v_mul_f32_e32 v4, 0x3f317217, v2
	v_fma_f32 v4, v2, s62, -v4
	v_fmac_f32_e32 v4, 0x3377d1cf, v2
	v_fmac_f32_e32 v4, 0x3f317217, v2
	v_cmp_lt_f32_e64 s[54:55], |v2|, s95
	s_nop 1
	v_cndmask_b32_e64 v2, v2, v4, s[54:55]
	v_add_f32_e32 v4, v111, v12
	v_mul_f32_e64 v5, |v4|, s77
	v_exp_f32_e32 v5, v5
	v_sub_f32_e32 v2, v2, v6
	v_sub_f32_e32 v1, v1, v2
	v_mul_f32_e32 v1, 0x3d800000, v1
	v_add_f32_e32 v2, 1.0, v5
	v_cmp_gt_f32_e32 vcc, s76, v2
	ds_write2_b32 v3, v0, v1 offset0:146 offset1:211
	v_add_f32_e32 v3, v111, v13
	v_cndmask_b32_e64 v5, 0, 32, vcc
	v_ldexp_f32 v2, v2, v5
	v_log_f32_e32 v2, v2
	v_min_f32_e32 v0, 0, v4
	v_mul_f32_e64 v4, |v3|, s77
	v_exp_f32_e32 v4, v4
	v_mul_f32_e32 v1, 0x3f317217, v2
	v_fma_f32 v1, v2, s62, -v1
	v_fmac_f32_e32 v1, 0x3377d1cf, v2
	v_fmac_f32_e32 v1, 0x3f317217, v2
	v_cmp_lt_f32_e64 s[54:55], |v2|, s95
	s_nop 1
	v_cndmask_b32_e64 v1, v2, v1, s[54:55]
	v_cndmask_b32_e32 v2, 0, v240, vcc
	v_sub_f32_e32 v1, v1, v2
	v_add_f32_e32 v2, 1.0, v4
	v_cmp_gt_f32_e32 vcc, s76, v2
	v_sub_f32_e32 v0, v0, v1
	v_min_f32_e32 v1, 0, v3
	v_cndmask_b32_e64 v4, 0, 32, vcc
	v_ldexp_f32 v2, v2, v4
	v_log_f32_e32 v2, v2
	v_add_f32_e32 v4, v111, v14
	v_mul_f32_e64 v5, |v4|, s77
	v_exp_f32_e32 v5, v5
	v_mul_f32_e32 v3, 0x3f317217, v2
	v_fma_f32 v3, v2, s62, -v3
	v_fmac_f32_e32 v3, 0x3377d1cf, v2
	v_fmac_f32_e32 v3, 0x3f317217, v2
	v_cmp_lt_f32_e64 s[54:55], |v2|, s95
	v_mul_f32_e32 v0, 0x3d800000, v0
	s_nop 0
	v_cndmask_b32_e64 v2, v2, v3, s[54:55]
	v_cndmask_b32_e32 v3, 0, v240, vcc
	v_sub_f32_e32 v2, v2, v3
	v_sub_f32_e32 v1, v1, v2
	v_add_f32_e32 v2, 1.0, v5
	v_cmp_gt_f32_e32 vcc, s76, v2
	v_mul_f32_e32 v1, 0x3d800000, v1
	s_nop 0
	v_cndmask_b32_e64 v3, 0, 32, vcc
	v_ldexp_f32 v2, v2, v3
	v_log_f32_e32 v2, v2
	v_add_u32_e32 v3, 0x1800, v99
	ds_write2_b32 v3, v0, v1 offset0:24 offset1:89
	v_min_f32_e32 v0, 0, v4
	v_add_f32_e32 v4, v111, v15
	v_mul_f32_e32 v1, 0x3f317217, v2
	v_mul_f32_e64 v5, |v4|, s77
	v_fma_f32 v1, v2, s62, -v1
	v_exp_f32_e32 v5, v5
	v_fmac_f32_e32 v1, 0x3377d1cf, v2
	v_fmac_f32_e32 v1, 0x3f317217, v2
	v_cmp_lt_f32_e64 s[54:55], |v2|, s95
	s_nop 1
	v_cndmask_b32_e64 v1, v2, v1, s[54:55]
	v_cndmask_b32_e32 v2, 0, v240, vcc
	v_sub_f32_e32 v1, v1, v2
	v_add_f32_e32 v2, 1.0, v5
	v_cmp_gt_f32_e32 vcc, s76, v2
	v_sub_f32_e32 v0, v0, v1
	v_min_f32_e32 v1, 0, v4
	v_cndmask_b32_e64 v5, 0, 32, vcc
	v_ldexp_f32 v2, v2, v5
	v_log_f32_e32 v2, v2
	v_mul_f32_e32 v0, 0x3d800000, v0
	v_mul_f32_e32 v4, 0x3f317217, v2
	v_fma_f32 v4, v2, s62, -v4
	v_fmac_f32_e32 v4, 0x3377d1cf, v2
	v_fmac_f32_e32 v4, 0x3f317217, v2
	v_cmp_lt_f32_e64 s[54:55], |v2|, s95
	s_nop 1
	v_cndmask_b32_e64 v2, v2, v4, s[54:55]
	v_cndmask_b32_e32 v4, 0, v240, vcc
	v_sub_f32_e32 v2, v2, v4
	v_sub_f32_e32 v1, v1, v2
	v_mul_f32_e32 v1, 0x3d800000, v1
	ds_write2_b32 v3, v0, v1 offset0:154 offset1:219
	s_waitcnt lgkmcnt(0)
	s_barrier
; DI float scan64(float x, int lane) {
; #pragma unroll
;     for (int off = 1; off < 64; off <<= 1) { const float y = __int_as_float(__builtin_amdgcn_ds_bpermute((lane - off) << 2, __float_as_int(x))); if (lane >= off) x += y; }
;     return x;
; }
; DI void phase_gla3(ArgsP a, int tb_, int l, bool with_ctx, char* shm, int vcu, int G) {
;     ...
;             { const int dir = wid >> 2;
; #pragma unroll
;               for (int i = 0; i < 16; ++i) { const int kd = (wid & 3) * 16 + i, jj = dir ? 63 - lane : lane; const float x = scan64(LA[dir * 4160 + jj * 65 + kd], lane); LA[dir * 4160 + jj * 65 + kd] = x; } }
;             __syncthreads();
	s_cselect_b32 s54, 3, 0x47
	s_cselect_b32 s55, s74, s94
	s_add_i32 s70, s70, 8
	ds_read2_b32 v[0:1], v67 offset1:1
	ds_read2_b32 v[2:3], v67 offset0:2 offset1:3
	ds_read2_b32 v[4:5], v67 offset0:4 offset1:5
	ds_read2_b32 v[6:7], v67 offset0:6 offset1:7
	ds_read2_b32 v[8:9], v67 offset0:8 offset1:9
	ds_read2_b32 v[10:11], v67 offset0:10 offset1:11
	ds_read2_b32 v[14:15], v67 offset0:12 offset1:13
	ds_read2_b32 v[114:115], v67 offset0:14 offset1:15
	s_waitcnt lgkmcnt(0)
	v_add_f32_dpp v0, v0, v0 row_shr:1 row_mask:0xf bank_mask:0xf bound_ctrl:1
	v_add_f32_dpp v1, v1, v1 row_shr:1 row_mask:0xf bank_mask:0xf bound_ctrl:1
	v_add_f32_dpp v2, v2, v2 row_shr:1 row_mask:0xf bank_mask:0xf bound_ctrl:1
	v_add_f32_dpp v3, v3, v3 row_shr:1 row_mask:0xf bank_mask:0xf bound_ctrl:1
	v_add_f32_dpp v4, v4, v4 row_shr:1 row_mask:0xf bank_mask:0xf bound_ctrl:1
	v_add_f32_dpp v5, v5, v5 row_shr:1 row_mask:0xf bank_mask:0xf bound_ctrl:1
	v_add_f32_dpp v6, v6, v6 row_shr:1 row_mask:0xf bank_mask:0xf bound_ctrl:1
	v_add_f32_dpp v7, v7, v7 row_shr:1 row_mask:0xf bank_mask:0xf bound_ctrl:1
	v_add_f32_dpp v8, v8, v8 row_shr:1 row_mask:0xf bank_mask:0xf bound_ctrl:1
	v_add_f32_dpp v9, v9, v9 row_shr:1 row_mask:0xf bank_mask:0xf bound_ctrl:1
	v_add_f32_dpp v10, v10, v10 row_shr:1 row_mask:0xf bank_mask:0xf bound_ctrl:1
	v_add_f32_dpp v11, v11, v11 row_shr:1 row_mask:0xf bank_mask:0xf bound_ctrl:1
	v_add_f32_dpp v14, v14, v14 row_shr:1 row_mask:0xf bank_mask:0xf bound_ctrl:1
	v_add_f32_dpp v15, v15, v15 row_shr:1 row_mask:0xf bank_mask:0xf bound_ctrl:1
	v_add_f32_dpp v114, v114, v114 row_shr:1 row_mask:0xf bank_mask:0xf bound_ctrl:1
	v_add_f32_dpp v115, v115, v115 row_shr:1 row_mask:0xf bank_mask:0xf bound_ctrl:1
	v_add_f32_dpp v0, v0, v0 row_shr:2 row_mask:0xf bank_mask:0xf bound_ctrl:1
	v_add_f32_dpp v1, v1, v1 row_shr:2 row_mask:0xf bank_mask:0xf bound_ctrl:1
	v_add_f32_dpp v2, v2, v2 row_shr:2 row_mask:0xf bank_mask:0xf bound_ctrl:1
	v_add_f32_dpp v3, v3, v3 row_shr:2 row_mask:0xf bank_mask:0xf bound_ctrl:1
	v_add_f32_dpp v4, v4, v4 row_shr:2 row_mask:0xf bank_mask:0xf bound_ctrl:1
	v_add_f32_dpp v5, v5, v5 row_shr:2 row_mask:0xf bank_mask:0xf bound_ctrl:1
	v_add_f32_dpp v6, v6, v6 row_shr:2 row_mask:0xf bank_mask:0xf bound_ctrl:1
	v_add_f32_dpp v7, v7, v7 row_shr:2 row_mask:0xf bank_mask:0xf bound_ctrl:1
	v_add_f32_dpp v8, v8, v8 row_shr:2 row_mask:0xf bank_mask:0xf bound_ctrl:1
	v_add_f32_dpp v9, v9, v9 row_shr:2 row_mask:0xf bank_mask:0xf bound_ctrl:1
	v_add_f32_dpp v10, v10, v10 row_shr:2 row_mask:0xf bank_mask:0xf bound_ctrl:1
	v_add_f32_dpp v11, v11, v11 row_shr:2 row_mask:0xf bank_mask:0xf bound_ctrl:1
	v_add_f32_dpp v14, v14, v14 row_shr:2 row_mask:0xf bank_mask:0xf bound_ctrl:1
	v_add_f32_dpp v15, v15, v15 row_shr:2 row_mask:0xf bank_mask:0xf bound_ctrl:1
	v_add_f32_dpp v114, v114, v114 row_shr:2 row_mask:0xf bank_mask:0xf bound_ctrl:1
	v_add_f32_dpp v115, v115, v115 row_shr:2 row_mask:0xf bank_mask:0xf bound_ctrl:1
	v_add_f32_dpp v0, v0, v0 row_shr:4 row_mask:0xf bank_mask:0xf bound_ctrl:1
	v_add_f32_dpp v1, v1, v1 row_shr:4 row_mask:0xf bank_mask:0xf bound_ctrl:1
	v_add_f32_dpp v2, v2, v2 row_shr:4 row_mask:0xf bank_mask:0xf bound_ctrl:1
	v_add_f32_dpp v3, v3, v3 row_shr:4 row_mask:0xf bank_mask:0xf bound_ctrl:1
	v_add_f32_dpp v4, v4, v4 row_shr:4 row_mask:0xf bank_mask:0xf bound_ctrl:1
	v_add_f32_dpp v5, v5, v5 row_shr:4 row_mask:0xf bank_mask:0xf bound_ctrl:1
	v_add_f32_dpp v6, v6, v6 row_shr:4 row_mask:0xf bank_mask:0xf bound_ctrl:1
	v_add_f32_dpp v7, v7, v7 row_shr:4 row_mask:0xf bank_mask:0xf bound_ctrl:1
	v_add_f32_dpp v8, v8, v8 row_shr:4 row_mask:0xf bank_mask:0xf bound_ctrl:1
	v_add_f32_dpp v9, v9, v9 row_shr:4 row_mask:0xf bank_mask:0xf bound_ctrl:1
	v_add_f32_dpp v10, v10, v10 row_shr:4 row_mask:0xf bank_mask:0xf bound_ctrl:1
	v_add_f32_dpp v11, v11, v11 row_shr:4 row_mask:0xf bank_mask:0xf bound_ctrl:1
	v_add_f32_dpp v14, v14, v14 row_shr:4 row_mask:0xf bank_mask:0xf bound_ctrl:1
	v_add_f32_dpp v15, v15, v15 row_shr:4 row_mask:0xf bank_mask:0xf bound_ctrl:1
	v_add_f32_dpp v114, v114, v114 row_shr:4 row_mask:0xf bank_mask:0xf bound_ctrl:1
	v_add_f32_dpp v115, v115, v115 row_shr:4 row_mask:0xf bank_mask:0xf bound_ctrl:1
	v_add_f32_dpp v0, v0, v0 row_shr:8 row_mask:0xf bank_mask:0xf bound_ctrl:1
	v_add_f32_dpp v1, v1, v1 row_shr:8 row_mask:0xf bank_mask:0xf bound_ctrl:1
	v_add_f32_dpp v2, v2, v2 row_shr:8 row_mask:0xf bank_mask:0xf bound_ctrl:1
	v_add_f32_dpp v3, v3, v3 row_shr:8 row_mask:0xf bank_mask:0xf bound_ctrl:1
	v_add_f32_dpp v4, v4, v4 row_shr:8 row_mask:0xf bank_mask:0xf bound_ctrl:1
	v_add_f32_dpp v5, v5, v5 row_shr:8 row_mask:0xf bank_mask:0xf bound_ctrl:1
	v_add_f32_dpp v6, v6, v6 row_shr:8 row_mask:0xf bank_mask:0xf bound_ctrl:1
	v_add_f32_dpp v7, v7, v7 row_shr:8 row_mask:0xf bank_mask:0xf bound_ctrl:1
	v_add_f32_dpp v8, v8, v8 row_shr:8 row_mask:0xf bank_mask:0xf bound_ctrl:1
	v_add_f32_dpp v9, v9, v9 row_shr:8 row_mask:0xf bank_mask:0xf bound_ctrl:1
	v_add_f32_dpp v10, v10, v10 row_shr:8 row_mask:0xf bank_mask:0xf bound_ctrl:1
	v_add_f32_dpp v11, v11, v11 row_shr:8 row_mask:0xf bank_mask:0xf bound_ctrl:1
	v_add_f32_dpp v14, v14, v14 row_shr:8 row_mask:0xf bank_mask:0xf bound_ctrl:1
	v_add_f32_dpp v15, v15, v15 row_shr:8 row_mask:0xf bank_mask:0xf bound_ctrl:1
	v_add_f32_dpp v114, v114, v114 row_shr:8 row_mask:0xf bank_mask:0xf bound_ctrl:1
	v_add_f32_dpp v115, v115, v115 row_shr:8 row_mask:0xf bank_mask:0xf bound_ctrl:1
	v_add_f32_dpp v0, v0, v0 row_bcast:15 row_mask:0xa bank_mask:0xf
	v_add_f32_dpp v1, v1, v1 row_bcast:15 row_mask:0xa bank_mask:0xf
	v_add_f32_dpp v2, v2, v2 row_bcast:15 row_mask:0xa bank_mask:0xf
; DI unsigned cvtpk(float lo, float hi) { f32x2_t v = {lo, hi}; bf16x2_t b = __builtin_convertvector(v, bf16x2_t); return __builtin_bit_cast(unsigned, b); }
; DI float bflo(unsigned u) { return __uint_as_float(u << 16); }
; DI float bfhi(unsigned u) { return __uint_as_float(u & 0xffff0000u); }
; DI void phase_gla3(ArgsP a, int tb_, int l, bool with_ctx, char* shm, int vcu, int G) {
;     ...
;             { const int dir = wid >> 2;
; #pragma unroll
;               for (int i = 0; i < 16; ++i) { const int kd = (wid & 3) * 16 + i, jj = dir ? 63 - lane : lane; const float x = scan64(LA[dir * 4160 + jj * 65 + kd], lane); LA[dir * 4160 + jj * 65 + kd] = x; } }
;             __syncthreads();
;             { const float qv[8] = {bflo(qw.x), bfhi(qw.x), bflo(qw.y), bfhi(qw.y), bflo(qw.z), bfhi(qw.z), bflo(qw.w), bfhi(qw.w)};
;               const float kv[8] = {bflo(kw.x), bfhi(kw.x), bflo(kw.y), bfhi(kw.y), bflo(kw.z), bfhi(kw.z), bflo(kw.w), bfhi(kw.w)};
; #pragma unroll
;               for (int dir = 0; dir < 2; ++dir) { float qt[8], kt[8];
; #pragma unroll
;                   for (int kk = 0; kk < 8; ++kk) { const float e = LA[dir * 4160 + j * 65 + kg * 8 + kk]; qt[kk] = qv[kk] * 0.125f * __expf(e); kt[kk] = kv[kk] * __expf(-e); }
;                   u32x4 w; w.x = cvtpk(qt[0], qt[1]); w.y = cvtpk(qt[2], qt[3]); w.z = cvtpk(qt[4], qt[5]); w.w = cvtpk(qt[6], qt[7]); *(u32x4*)(QT + dir * 9216 + j * 144 + kg * 16) = w;
;                   u32x4 w2; w2.x = cvtpk(kt[0], kt[1]); w2.y = cvtpk(kt[2], kt[3]); w2.z = cvtpk(kt[4], kt[5]); w2.w = cvtpk(kt[6], kt[7]); *(u32x4*)(KTt + dir * 9216 + j * 144 + kg * 16) = w2; }
;               const unsigned vv[8] = {v0.x, v0.y, v0.z, v0.w, v1.x, v1.y, v1.z, v1.w};
; #pragma unroll
;               for (int q = 0; q < 8; ++q) { *(bf16_t*)(VT + (kg * 16 + 2 * q) * 144 + j * 2) = (bf16_t)(vv[q] & 0xffffu); *(bf16_t*)(VT + (kg * 16 + 2 * q + 1) * 144 + j * 2) = (bf16_t)(vv[q] >> 16); } }
	v_add_f32_dpp v3, v3, v3 row_bcast:15 row_mask:0xa bank_mask:0xf
	v_add_f32_dpp v4, v4, v4 row_bcast:15 row_mask:0xa bank_mask:0xf
	v_add_f32_dpp v5, v5, v5 row_bcast:15 row_mask:0xa bank_mask:0xf
	v_add_f32_dpp v6, v6, v6 row_bcast:15 row_mask:0xa bank_mask:0xf
	v_add_f32_dpp v7, v7, v7 row_bcast:15 row_mask:0xa bank_mask:0xf
	v_add_f32_dpp v8, v8, v8 row_bcast:15 row_mask:0xa bank_mask:0xf
	v_add_f32_dpp v9, v9, v9 row_bcast:15 row_mask:0xa bank_mask:0xf
	v_add_f32_dpp v10, v10, v10 row_bcast:15 row_mask:0xa bank_mask:0xf
	v_add_f32_dpp v11, v11, v11 row_bcast:15 row_mask:0xa bank_mask:0xf
	v_add_f32_dpp v14, v14, v14 row_bcast:15 row_mask:0xa bank_mask:0xf
	v_add_f32_dpp v15, v15, v15 row_bcast:15 row_mask:0xa bank_mask:0xf
	v_add_f32_dpp v114, v114, v114 row_bcast:15 row_mask:0xa bank_mask:0xf
	v_add_f32_dpp v115, v115, v115 row_bcast:15 row_mask:0xa bank_mask:0xf
	v_add_f32_dpp v0, v0, v0 row_bcast:31 row_mask:0xc bank_mask:0xf
	v_add_f32_dpp v1, v1, v1 row_bcast:31 row_mask:0xc bank_mask:0xf
	v_add_f32_dpp v2, v2, v2 row_bcast:31 row_mask:0xc bank_mask:0xf
	v_add_f32_dpp v3, v3, v3 row_bcast:31 row_mask:0xc bank_mask:0xf
	v_add_f32_dpp v4, v4, v4 row_bcast:31 row_mask:0xc bank_mask:0xf
	v_add_f32_dpp v5, v5, v5 row_bcast:31 row_mask:0xc bank_mask:0xf
	v_add_f32_dpp v6, v6, v6 row_bcast:31 row_mask:0xc bank_mask:0xf
	v_add_f32_dpp v7, v7, v7 row_bcast:31 row_mask:0xc bank_mask:0xf
	v_add_f32_dpp v8, v8, v8 row_bcast:31 row_mask:0xc bank_mask:0xf
	v_add_f32_dpp v9, v9, v9 row_bcast:31 row_mask:0xc bank_mask:0xf
	v_add_f32_dpp v10, v10, v10 row_bcast:31 row_mask:0xc bank_mask:0xf
	v_add_f32_dpp v11, v11, v11 row_bcast:31 row_mask:0xc bank_mask:0xf
	v_add_f32_dpp v14, v14, v14 row_bcast:31 row_mask:0xc bank_mask:0xf
	v_add_f32_dpp v15, v15, v15 row_bcast:31 row_mask:0xc bank_mask:0xf
	v_add_f32_dpp v114, v114, v114 row_bcast:31 row_mask:0xc bank_mask:0xf
	v_add_f32_dpp v115, v115, v115 row_bcast:31 row_mask:0xc bank_mask:0xf
	ds_write2_b32 v67, v0, v1 offset1:1
	ds_write2_b32 v67, v2, v3 offset0:2 offset1:3
	ds_write2_b32 v67, v4, v5 offset0:4 offset1:5
	ds_write2_b32 v67, v6, v7 offset0:6 offset1:7
	ds_write2_b32 v67, v8, v9 offset0:8 offset1:9
	ds_write2_b32 v67, v10, v11 offset0:10 offset1:11
	ds_write2_b32 v67, v14, v15 offset0:12 offset1:13
	ds_write2_b32 v67, v114, v115 offset0:14 offset1:15
	v_lshlrev_b32_e32 v12, 16, v48
	s_waitcnt lgkmcnt(0)
	s_barrier
	ds_read2_b32 v[0:1], v100 offset1:1
	ds_read2_b32 v[2:3], v100 offset0:2 offset1:3
	ds_read2_b32 v[4:5], v100 offset0:4 offset1:5
	ds_read2_b32 v[6:7], v100 offset0:6 offset1:7
	v_and_b32_e32 v13, 0xffff0000, v48
	v_lshlrev_b32_e32 v10, 16, v52
	v_and_b32_e32 v11, 0xffff0000, v52
	s_waitcnt lgkmcnt(3)
	v_mul_f32_e32 v8, 0x3fb8aa3b, v0
	v_mul_f32_e32 v0, 0xbfb8aa3b, v0
	v_mul_f32_e32 v9, 0x3fb8aa3b, v1
	v_mul_f32_e32 v1, 0xbfb8aa3b, v1
	v_exp_f32_e32 v0, v0
	v_exp_f32_e32 v1, v1
	v_lshlrev_b32_e32 v52, 16, v53
	v_and_b32_e32 v53, 0xffff0000, v53
	v_pk_mul_f32 v[52:53], v[52:53], s[90:91] op_sel_hi:[1,0]
	v_pk_mul_f32 v[14:15], v[0:1], v[12:13]
	s_waitcnt lgkmcnt(2)
	v_mul_f32_e32 v1, 0xbfb8aa3b, v2
	v_mul_f32_e32 v0, 0x3fb8aa3b, v2
	v_exp_f32_e32 v2, v1
	v_mul_f32_e32 v1, 0x3fb8aa3b, v3
	v_exp_f32_e32 v0, v0
	v_exp_f32_e32 v1, v1
	v_mul_f32_e32 v3, 0xbfb8aa3b, v3
	v_exp_f32_e32 v3, v3
	v_lshlrev_b32_e32 v48, 16, v49
	v_pk_mul_f32 v[114:115], v[52:53], v[0:1]
	v_and_b32_e32 v49, 0xffff0000, v49
	s_waitcnt lgkmcnt(1)
	v_mul_f32_e32 v1, 0xbfb8aa3b, v4
	v_pk_mul_f32 v[116:117], v[2:3], v[48:49]
	v_mul_f32_e32 v0, 0x3fb8aa3b, v4
	v_exp_f32_e32 v2, v1
	v_mul_f32_e32 v1, 0x3fb8aa3b, v5
	v_exp_f32_e32 v0, v0
	v_exp_f32_e32 v1, v1
	v_mul_f32_e32 v3, 0xbfb8aa3b, v5
	v_exp_f32_e32 v3, v3
	v_exp_f32_e32 v8, v8
	v_pk_mul_f32 v[4:5], v[118:119], v[0:1]
	s_waitcnt lgkmcnt(0)
	v_mul_f32_e32 v1, 0xbfb8aa3b, v6
	v_pk_mul_f32 v[122:123], v[2:3], v[120:121]
	v_mul_f32_e32 v0, 0x3fb8aa3b, v6
	v_exp_f32_e32 v2, v1
	v_mul_f32_e32 v1, 0x3fb8aa3b, v7
	v_exp_f32_e32 v9, v9
	v_exp_f32_e32 v0, v0
	v_exp_f32_e32 v1, v1
	v_mul_f32_e32 v3, 0xbfb8aa3b, v7
	v_exp_f32_e32 v3, v3
	v_pk_mul_f32 v[10:11], v[10:11], s[90:91] op_sel_hi:[1,0]
	v_pk_mul_f32 v[6:7], v[54:55], v[0:1]
	v_pk_mul_f32 v[8:9], v[10:11], v[8:9]
	v_pk_mul_f32 v[124:125], v[2:3], v[50:51]
	v_cvt_pk_bf16_f32 v0, v8, v9
	v_cvt_pk_bf16_f32 v1, v114, v115
	v_cvt_pk_bf16_f32 v2, v4, v5
	v_cvt_pk_bf16_f32 v3, v6, v7
	ds_write_b128 v101, v[0:3] offset:33792
	v_cvt_pk_bf16_f32 v0, v14, v15
	v_cvt_pk_bf16_f32 v1, v116, v117
	v_cvt_pk_bf16_f32 v2, v122, v123
	v_cvt_pk_bf16_f32 v3, v124, v125
	ds_write_b128 v101, v[0:3] offset:52224
	v_add_u32_e32 v0, 0x4100, v100
	ds_read2_b32 v[0:1], v0 offset1:1
	v_add_u32_e32 v2, 0x4108, v100
	v_add_u32_e32 v4, 0x4110, v100
	v_add_u32_e32 v6, 0x4118, v100
	ds_read2_b32 v[2:3], v2 offset1:1
	ds_read2_b32 v[4:5], v4 offset1:1
	ds_read2_b32 v[6:7], v6 offset1:1
	s_waitcnt lgkmcnt(3)
	v_mul_f32_e32 v8, 0x3fb8aa3b, v0
	v_mul_f32_e32 v0, 0xbfb8aa3b, v0
	v_mul_f32_e32 v9, 0x3fb8aa3b, v1
	v_mul_f32_e32 v1, 0xbfb8aa3b, v1
	v_exp_f32_e32 v8, v8
	v_exp_f32_e32 v0, v0
	v_exp_f32_e32 v9, v9
	v_exp_f32_e32 v1, v1
	s_waitcnt lgkmcnt(2)
	v_mul_f32_e32 v14, 0x3fb8aa3b, v2
	v_mul_f32_e32 v2, 0xbfb8aa3b, v2
	v_mul_f32_e32 v15, 0x3fb8aa3b, v3
	v_mul_f32_e32 v3, 0xbfb8aa3b, v3
	v_exp_f32_e32 v14, v14
	v_exp_f32_e32 v2, v2
	v_exp_f32_e32 v15, v15
	v_exp_f32_e32 v3, v3
	v_pk_mul_f32 v[8:9], v[10:11], v[8:9]
	v_pk_mul_f32 v[10:11], v[0:1], v[12:13]
	s_waitcnt lgkmcnt(1)
	v_mul_f32_e32 v1, 0xbfb8aa3b, v4
	v_pk_mul_f32 v[12:13], v[52:53], v[14:15]
	v_pk_mul_f32 v[14:15], v[2:3], v[48:49]
	v_exp_f32_e32 v2, v1
	v_mul_f32_e32 v1, 0x3fb8aa3b, v5
	v_mul_f32_e32 v3, 0xbfb8aa3b, v5
	s_waitcnt lgkmcnt(0)
; DI unsigned cvtpk(float lo, float hi) { f32x2_t v = {lo, hi}; bf16x2_t b = __builtin_convertvector(v, bf16x2_t); return __builtin_bit_cast(unsigned, b); }
; DI void phase_gla3(ArgsP a, int tb_, int l, bool with_ctx, char* shm, int vcu, int G) {
;     ...
;               for (int dir = 0; dir < 2; ++dir) { float qt[8], kt[8];
; #pragma unroll
;                   for (int kk = 0; kk < 8; ++kk) { const float e = LA[dir * 4160 + j * 65 + kg * 8 + kk]; qt[kk] = qv[kk] * 0.125f * __expf(e); kt[kk] = kv[kk] * __expf(-e); }
;                   u32x4 w; w.x = cvtpk(qt[0], qt[1]); w.y = cvtpk(qt[2], qt[3]); w.z = cvtpk(qt[4], qt[5]); w.w = cvtpk(qt[6], qt[7]); *(u32x4*)(QT + dir * 9216 + j * 144 + kg * 16) = w;
;                   u32x4 w2; w2.x = cvtpk(kt[0], kt[1]); w2.y = cvtpk(kt[2], kt[3]); w2.z = cvtpk(kt[4], kt[5]); w2.w = cvtpk(kt[6], kt[7]); *(u32x4*)(KTt + dir * 9216 + j * 144 + kg * 16) = w2; }
;               const unsigned vv[8] = {v0.x, v0.y, v0.z, v0.w, v1.x, v1.y, v1.z, v1.w};
; #pragma unroll
;               for (int q = 0; q < 8; ++q) { *(bf16_t*)(VT + (kg * 16 + 2 * q) * 144 + j * 2) = (bf16_t)(vv[q] & 0xffffu); *(bf16_t*)(VT + (kg * 16 + 2 * q + 1) * 144 + j * 2) = (bf16_t)(vv[q] >> 16); } }
;             const u32x4* rp = (const u32x4*)(zr + (size_t)(m0 + j) * ZR + 1536 + h * 128 + kg * 16); const u32x4 r0 = rp[0], r1 = rp[1];
;             const int oib = wid >> 2, ovb = wid & 3;
;             bf16x8 sfr[2][4];
; #pragma unroll
;             for (int dir = 0; dir < 2; ++dir) { const bf16_t* sp = ST + ((size_t)((b * 4 + h) * 2 + dir) * NSLOT + (dir ? slot_b : slot_f)) * 8192 + (size_t)(ovb * 32 + r32) * 64 + 8 * hi;
; #pragma unroll
;                 for (int s4 = 0; s4 < 4; ++s4) sfr[dir][s4] = *(const bf16x8*)(sp + 16 * s4); }
;             __syncthreads();
;             { const int dir = wid >> 2, ib = (wid >> 1) & 1, jb = wid & 1; f32x16 acc;
; #pragma unroll
;               for (int r = 0; r < 16; ++r) acc[r] = 0.f;
; #pragma unroll
;               for (int s4 = 0; s4 < 4; ++s4) { const bf16x8 af = *(const bf16x8*)(QT + dir * 9216 + (ib * 32 + r32) * 144 + (16 * s4 + 8 * hi) * 2); const bf16x8 bfr = *(const bf16x8*)(KTt + dir * 9216 + (jb * 32 + r32) * 144 + (16 * s4 + 8 * hi) * 2);
;                   acc = __builtin_amdgcn_mfma_f32_32x32x16_bf16(af, bfr, acc, 0, 0, 0); }
;               const int jc = jb * 32 + r32;
; #pragma unroll
	v_mul_f32_e32 v5, 0xbfb8aa3b, v6
	v_mul_f32_e32 v0, 0x3fb8aa3b, v4
	v_mul_f32_e32 v4, 0x3fb8aa3b, v6
	v_exp_f32_e32 v6, v5
	v_mul_f32_e32 v5, 0x3fb8aa3b, v7
	v_exp_f32_e32 v0, v0
	v_exp_f32_e32 v1, v1
	v_exp_f32_e32 v4, v4
	v_exp_f32_e32 v5, v5
	v_mul_f32_e32 v7, 0xbfb8aa3b, v7
	v_exp_f32_e32 v3, v3
	v_exp_f32_e32 v7, v7
	v_pk_mul_f32 v[48:49], v[118:119], v[0:1]
	v_pk_mul_f32 v[4:5], v[54:55], v[4:5]
	v_pk_mul_f32 v[52:53], v[2:3], v[120:121]
	v_pk_mul_f32 v[6:7], v[6:7], v[50:51]
	v_cvt_pk_bf16_f32 v0, v8, v9
	v_cvt_pk_bf16_f32 v1, v12, v13
	v_cvt_pk_bf16_f32 v2, v48, v49
	v_cvt_pk_bf16_f32 v3, v4, v5
	s_add_u32 s54, s33, s54
	ds_write_b128 v101, v[0:3] offset:43008
	v_cvt_pk_bf16_f32 v0, v10, v11
	v_cvt_pk_bf16_f32 v1, v14, v15
	v_cvt_pk_bf16_f32 v2, v52, v53
	v_cvt_pk_bf16_f32 v3, v6, v7
	v_add_u32_e32 v48, s55, v112
	s_addc_u32 s55, s2, 0
	ds_write_b128 v101, v[0:3] offset:61440
	ds_write_b16 v102, v44
	ds_write_b16_d16_hi v102, v44 offset:144
	ds_write_b16 v102, v45 offset:288
	ds_write_b16_d16_hi v102, v45 offset:432
	ds_write_b16 v102, v46 offset:576
	ds_write_b16_d16_hi v102, v46 offset:720
	ds_write_b16 v102, v47 offset:864
	ds_write_b16_d16_hi v102, v47 offset:1008
	ds_write_b16 v102, v40 offset:1152
	ds_write_b16_d16_hi v102, v40 offset:1296
	ds_write_b16 v102, v41 offset:1440
	ds_write_b16_d16_hi v102, v41 offset:1584
	ds_write_b16 v102, v42 offset:1728
	ds_write_b16_d16_hi v102, v42 offset:1872
	ds_write_b16 v102, v43 offset:2016
	ds_write_b16_d16_hi v102, v43 offset:2160
	v_mad_i64_i32 v[0:1], vcc, v48, s67, v[86:87]
	s_lshl_b64 s[54:55], s[54:55], 14
	global_load_dwordx4 v[40:43], v[0:1], off offset:3088
	global_load_dwordx4 v[44:47], v[0:1], off offset:3072
	global_load_dwordx4 v[50:53], v[82:83], off offset:-64
	global_load_dwordx4 v[114:117], v[82:83], off offset:-32
	global_load_dwordx4 v[118:121], v[82:83], off
	global_load_dwordx4 v[122:125], v[82:83], off offset:32
	v_lshl_add_u64 v[0:1], v[70:71], 0, s[54:55]
	global_load_dwordx4 v[126:129], v[0:1], off
	global_load_dwordx4 v[130:133], v[0:1], off offset:32
	global_load_dwordx4 v[134:137], v[0:1], off offset:64
	global_load_dwordx4 v[138:141], v[0:1], off offset:96
	s_waitcnt lgkmcnt(0)
	s_barrier
	ds_read_b128 v[0:3], v103 offset:33792
	ds_read_b128 v[4:7], v104 offset:52224
	s_waitcnt lgkmcnt(0)
	v_mfma_f32_32x32x16_bf16 v[0:15], v[0:3], v[4:7], 0
	ds_read_b128 v[142:145], v103 offset:33824
	ds_read_b128 v[146:149], v104 offset:52256
	s_add_u32 s33, s33, -8
	v_lshl_add_u64 v[82:83], v[82:83], 0, s[88:89]
	v_add_u32_e32 v112, 0x200, v112
	s_addc_u32 s2, s2, -1
	s_waitcnt lgkmcnt(0)
	v_mfma_f32_32x32x16_bf16 v[0:15], v[142:145], v[146:149], v[0:15]
	ds_read_b128 v[142:145], v103 offset:33856
	ds_read_b128 v[146:149], v104 offset:52288
	s_waitcnt lgkmcnt(0)
	v_mfma_f32_32x32x16_bf16 v[0:15], v[142:145], v[146:149], v[0:15]
	ds_read_b128 v[142:145], v103 offset:33888
	ds_read_b128 v[146:149], v104 offset:52320
	s_waitcnt lgkmcnt(0)
	v_mfma_f32_32x32x16_bf16 v[0:15], v[142:145], v[146:149], v[0:15]
	s_nop 11
	v_cvt_pk_bf16_f32 v0, v0, s0
	v_cndmask_b32_e64 v0, 0, v0, s[18:19]
	ds_write_b16 v105, v0
	v_cvt_pk_bf16_f32 v0, v1, s0
	v_cndmask_b32_e64 v0, 0, v0, s[20:21]
	ds_write_b16 v105, v0 offset:144
	v_cvt_pk_bf16_f32 v0, v2, s0
	v_cndmask_b32_e64 v0, 0, v0, s[22:23]
	ds_write_b16 v105, v0 offset:288
	v_cvt_pk_bf16_f32 v0, v3, s0
	v_cndmask_b32_e64 v0, 0, v0, s[24:25]
	ds_write_b16 v105, v0 offset:432
	v_cvt_pk_bf16_f32 v0, v4, s0
	v_cndmask_b32_e64 v0, 0, v0, s[26:27]
	ds_write_b16 v105, v0 offset:1152
	v_cvt_pk_bf16_f32 v0, v5, s0
	v_cndmask_b32_e64 v0, 0, v0, s[28:29]
	ds_write_b16 v105, v0 offset:1296
	v_cvt_pk_bf16_f32 v0, v6, s0
	v_cndmask_b32_e64 v0, 0, v0, s[30:31]
	ds_write_b16 v105, v0 offset:1440
	v_cvt_pk_bf16_f32 v0, v7, s0
	v_cndmask_b32_e64 v0, 0, v0, s[34:35]
	ds_write_b16 v105, v0 offset:1584
	v_cvt_pk_bf16_f32 v0, v8, s0
	v_cndmask_b32_e64 v0, 0, v0, s[36:37]
	ds_write_b16 v105, v0 offset:2304
	v_cvt_pk_bf16_f32 v0, v9, s0
	v_cndmask_b32_e64 v0, 0, v0, s[38:39]
	ds_write_b16 v105, v0 offset:2448
	v_cvt_pk_bf16_f32 v0, v10, s0
	v_cndmask_b32_e64 v0, 0, v0, s[40:41]
	ds_write_b16 v105, v0 offset:2592
	v_cvt_pk_bf16_f32 v0, v11, s0
	v_cndmask_b32_e64 v0, 0, v0, s[42:43]
	ds_write_b16 v105, v0 offset:2736
	v_cvt_pk_bf16_f32 v0, v12, s0
	v_cndmask_b32_e64 v0, 0, v0, s[44:45]
	ds_write_b16 v105, v0 offset:3456
	v_cvt_pk_bf16_f32 v0, v13, s0
	v_cndmask_b32_e64 v0, 0, v0, s[46:47]
	ds_write_b16 v105, v0 offset:3600
	v_cvt_pk_bf16_f32 v0, v14, s0
	v_cndmask_b32_e64 v0, 0, v0, s[48:49]
	ds_write_b16 v105, v0 offset:3744
	v_cvt_pk_bf16_f32 v0, v15, s0
	v_cndmask_b32_e64 v0, 0, v0, s[50:51]
	ds_write_b16 v105, v0 offset:3888
	s_waitcnt lgkmcnt(0)
	s_barrier
; DI int crow(int r, int hi) { return (r & 3) + 8 * (r >> 2) + 4 * hi; }
; DI void phase_gla3(ArgsP a, int tb_, int l, bool with_ctx, char* shm, int vcu, int G) {
;     ...
;             { f32x16 acc;
; #pragma unroll
;               for (int r = 0; r < 16; ++r) acc[r] = 0.f;
; #pragma unroll
;               for (int dir = 0; dir < 2; ++dir) {
; #pragma unroll
;                   for (int s4 = 0; s4 < 4; ++s4) { const bf16x8 af = *(const bf16x8*)(AM + dir * 9216 + (oib * 32 + r32) * 144 + (16 * s4 + 8 * hi) * 2); const bf16x8 bfr = *(const bf16x8*)(VT + (ovb * 32 + r32) * 144 + (16 * s4 + 8 * hi) * 2);
;                       acc = __builtin_amdgcn_mfma_f32_32x32x16_bf16(af, bfr, acc, 0, 0, 0); }
; #pragma unroll
;                   for (int s4 = 0; s4 < 4; ++s4) { const bf16x8 af = *(const bf16x8*)(QT + dir * 9216 + (oib * 32 + r32) * 144 + (16 * s4 + 8 * hi) * 2);
;                       acc = __builtin_amdgcn_mfma_f32_32x32x16_bf16(af, sfr[dir][s4], acc, 0, 0, 0); } }
; #pragma unroll
;               for (int r = 0; r < 16; ++r) OS[(oib * 32 + crow(r, hi)) * 132 + ovb * 32 + r32] = acc[r]; }
;             __syncthreads();
	ds_read_b128 v[0:3], v106
	ds_read_b128 v[142:145], v107
	s_waitcnt lgkmcnt(0)
	v_mfma_f32_32x32x16_bf16 v[0:15], v[0:3], v[142:145], 0
	ds_read_b128 v[146:149], v106 offset:32
	ds_read_b128 v[150:153], v107 offset:32
	s_waitcnt lgkmcnt(0)
	v_mfma_f32_32x32x16_bf16 v[0:15], v[146:149], v[150:153], v[0:15]
	ds_read_b128 v[146:149], v106 offset:64
	ds_read_b128 v[154:157], v107 offset:64
	s_waitcnt lgkmcnt(0)
	v_mfma_f32_32x32x16_bf16 v[0:15], v[146:149], v[154:157], v[0:15]
	ds_read_b128 v[146:149], v106 offset:96
	ds_read_b128 v[158:161], v107 offset:96
	s_waitcnt lgkmcnt(0)
	v_mfma_f32_32x32x16_bf16 v[0:15], v[146:149], v[158:161], v[0:15]
	ds_read_b128 v[146:149], v108 offset:33792
	s_waitcnt vmcnt(7) lgkmcnt(0)
	v_mfma_f32_32x32x16_bf16 v[0:15], v[146:149], v[50:53], v[0:15]
	ds_read_b128 v[50:53], v108 offset:33824
	s_waitcnt vmcnt(6) lgkmcnt(0)
	v_mfma_f32_32x32x16_bf16 v[0:15], v[50:53], v[114:117], v[0:15]
	ds_read_b128 v[50:53], v108 offset:33856
	s_waitcnt vmcnt(5) lgkmcnt(0)
	v_mfma_f32_32x32x16_bf16 v[0:15], v[50:53], v[118:121], v[0:15]
	ds_read_b128 v[50:53], v108 offset:33888
	s_waitcnt vmcnt(4) lgkmcnt(0)
	v_mfma_f32_32x32x16_bf16 v[0:15], v[50:53], v[122:125], v[0:15]
	ds_read_b128 v[50:53], v106 offset:9216
	s_waitcnt lgkmcnt(0)
	v_mfma_f32_32x32x16_bf16 v[0:15], v[50:53], v[142:145], v[0:15]
	ds_read_b128 v[50:53], v106 offset:9248
	s_waitcnt lgkmcnt(0)
	v_mfma_f32_32x32x16_bf16 v[0:15], v[50:53], v[150:153], v[0:15]
	ds_read_b128 v[50:53], v106 offset:9280
	s_waitcnt lgkmcnt(0)
	v_mfma_f32_32x32x16_bf16 v[0:15], v[50:53], v[154:157], v[0:15]
	ds_read_b128 v[50:53], v106 offset:9312
	s_waitcnt lgkmcnt(0)
	v_mfma_f32_32x32x16_bf16 v[0:15], v[50:53], v[158:161], v[0:15]
	ds_read_b128 v[50:53], v108 offset:43008
	s_waitcnt vmcnt(3) lgkmcnt(0)
	v_mfma_f32_32x32x16_bf16 v[0:15], v[50:53], v[126:129], v[0:15]
	ds_read_b128 v[50:53], v108 offset:43040
	s_waitcnt vmcnt(2) lgkmcnt(0)
	v_mfma_f32_32x32x16_bf16 v[0:15], v[50:53], v[130:133], v[0:15]
	ds_read_b128 v[50:53], v108 offset:43072
	s_waitcnt vmcnt(1) lgkmcnt(0)
	v_mfma_f32_32x32x16_bf16 v[0:15], v[50:53], v[134:137], v[0:15]
	ds_read_b128 v[50:53], v108 offset:43104
	s_waitcnt vmcnt(0) lgkmcnt(0)
	v_mfma_f32_32x32x16_bf16 v[0:15], v[50:53], v[138:141], v[0:15]
	s_nop 11
	ds_write2_b32 v109, v0, v1 offset1:132
	v_add_u32_e32 v0, 0x400, v109
	ds_write2_b32 v0, v2, v3 offset0:8 offset1:140
	v_add_u32_e32 v0, 0x1000, v109
	ds_write2_b32 v0, v4, v5 offset0:32 offset1:164
	v_add_u32_e32 v0, 0x1400, v109
	ds_write2_b32 v0, v6, v7 offset0:40 offset1:172
	v_add_u32_e32 v0, 0x2000, v109
	ds_write2_b32 v0, v8, v9 offset0:64 offset1:196
	v_add_u32_e32 v0, 0x2400, v109
	ds_write2_b32 v0, v10, v11 offset0:72 offset1:204
	v_add_u32_e32 v0, 0x3000, v109
	ds_write2_b32 v0, v12, v13 offset0:96 offset1:228
	v_add_u32_e32 v0, 0x3400, v109
	ds_write2_b32 v0, v14, v15 offset0:104 offset1:236
	s_waitcnt lgkmcnt(0)
	s_barrier
; DI unsigned cvtpk(float lo, float hi) { f32x2_t v = {lo, hi}; bf16x2_t b = __builtin_convertvector(v, bf16x2_t); return __builtin_bit_cast(unsigned, b); }
; DI float bflo(unsigned u) { return __uint_as_float(u << 16); }
; DI float bfhi(unsigned u) { return __uint_as_float(u & 0xffff0000u); }
; DI float shx(float v, int mask, int lane) { return __int_as_float(__builtin_amdgcn_ds_bpermute((lane ^ mask) << 2, __float_as_int(v))); }
; DI float silu_f(float x) { return x * sigm_f(x); }
; DI void phase_gla3(ArgsP a, int tb_, int l, bool with_ctx, char* shm, int vcu, int G) {
;     ...
;             { const int i = j, vg = kg; float o[16]; float ss = 0.f;
; #pragma unroll
;               for (int q = 0; q < 4; ++q) { const f32x4 t4 = *(const f32x4*)(OS + i * 132 + vg * 16 + 4 * q); o[4 * q] = t4.x; o[4 * q + 1] = t4.y; o[4 * q + 2] = t4.z; o[4 * q + 3] = t4.w; ss += (t4.x * t4.x + t4.y * t4.y) + (t4.z * t4.z + t4.w * t4.w); }
;               ss += shx(ss, 1, lane); ss += shx(ss, 2, lane); ss += shx(ss, 4, lane);
;               const float rn = rsqrtf(ss * (1.f / 128.f) + EPS);
;               const float gr[16] = {bflo(r0.x), bfhi(r0.x), bflo(r0.y), bfhi(r0.y), bflo(r0.z), bfhi(r0.z), bflo(r0.w), bfhi(r0.w), bflo(r1.x), bfhi(r1.x), bflo(r1.y), bfhi(r1.y), bflo(r1.z), bfhi(r1.z), bflo(r1.w), bfhi(r1.w)};
;               float y[16];
; #pragma unroll
;               for (int q = 0; q < 16; ++q) y[q] = o[q] * rn * ggl[vg * 16 + q] * silu_f(gr[q]);
;               u32x4 w0, w1; w0.x = cvtpk(y[0], y[1]); w0.y = cvtpk(y[2], y[3]); w0.z = cvtpk(y[4], y[5]); w0.w = cvtpk(y[6], y[7]); w1.x = cvtpk(y[8], y[9]); w1.y = cvtpk(y[10], y[11]); w1.z = cvtpk(y[12], y[13]); w1.w = cvtpk(y[14], y[15]);
;               u32x4* op = (u32x4*)(og + (size_t)(m0 + i) * 512 + h * 128 + vg * 16); op[0] = w0; op[1] = w1; }
;             __syncthreads();
	ds_read_b128 v[4:7], v110
	ds_read_b128 v[12:15], v110 offset:16
	ds_read_b128 v[50:53], v110 offset:32
	ds_read_b128 v[114:117], v110 offset:48
	s_waitcnt lgkmcnt(3)
	v_pk_mul_f32 v[54:55], v[6:7], v[6:7]
	v_pk_mul_f32 v[118:119], v[4:5], v[4:5]
	s_waitcnt lgkmcnt(0)
	v_mul_f32_e32 v49, v114, v114
	v_pk_mov_b32 v[120:121], v[118:119], v[54:55] op_sel:[1,0]
	v_mov_b32_e32 v119, v55
	v_pk_add_f32 v[54:55], v[120:121], v[118:119]
	v_pk_mul_f32 v[118:119], v[14:15], v[14:15]
	v_pk_mul_f32 v[120:121], v[12:13], v[12:13]
	v_mul_f32_e32 v79, v115, v115
	v_pk_mov_b32 v[122:123], v[120:121], v[118:119] op_sel:[1,0]
	v_mov_b32_e32 v121, v119
	v_pk_add_f32 v[118:119], v[122:123], v[120:121]
	v_pk_add_f32 v[54:55], v[54:55], v[54:55] op_sel:[0,1] op_sel_hi:[1,0]
	v_pk_add_f32 v[118:119], v[118:119], v[118:119] op_sel:[0,1] op_sel_hi:[1,0]
	v_mov_b32_e32 v55, v49
	v_mov_b32_e32 v119, v79
	v_pk_add_f32 v[54:55], v[54:55], v[118:119]
	v_mul_f32_e32 v118, v51, v51
	v_mul_f32_e32 v120, v53, v53
	v_mul_f32_e32 v81, v116, v116
	v_mul_f32_e32 v122, v117, v117
	v_pk_fma_f32 v[118:119], v[50:51], v[50:51], v[118:119] op_sel_hi:[1,1,0]
	v_pk_fma_f32 v[120:121], v[52:53], v[52:53], v[120:121] op_sel_hi:[1,1,0]
	v_mov_b32_e32 v119, v81
	v_mov_b32_e32 v121, v122
	v_pk_add_f32 v[118:119], v[118:119], v[120:121]
	v_pk_add_f32 v[54:55], v[54:55], v[118:119]
	v_add_f32_e32 v49, v54, v55
	s_waitcnt lgkmcnt(0)
	s_nop 1
	v_add_f32_dpp v49, v49, v49 quad_perm:[1,0,3,2] row_mask:0xf bank_mask:0xf
	s_waitcnt lgkmcnt(0)
	s_nop 1
	v_add_f32_dpp v54, v49, v49 quad_perm:[2,3,0,1] row_mask:0xf bank_mask:0xf
	v_ashrrev_i32_e32 v49, 31, v48
	s_waitcnt lgkmcnt(0)
	s_nop 1
	v_add_f32_dpp v54, v54, v54 row_half_mirror row_mask:0xf bank_mask:0xf
	v_fmamk_f32 v54, v54, 0x3c000000, v230
	v_mul_f32_e32 v55, 0x4b800000, v54
	v_cmp_gt_f32_e32 vcc, s76, v54
	s_nop 1
	v_cndmask_b32_e32 v54, v54, v55, vcc
	v_rsq_f32_e32 v55, v54
	v_lshlrev_b32_e32 v54, 16, v44
	v_mul_f32_e32 v79, 0xbfb8aa3b, v54
	v_exp_f32_e32 v79, v79
	v_mul_f32_e32 v81, 0x45800000, v55
	v_cndmask_b32_e32 v126, v55, v81, vcc
	v_and_b32_e32 v55, 0xffff0000, v44
	v_add_f32_e32 v44, 1.0, v79
	v_mul_f32_e32 v79, 0xbfb8aa3b, v55
	v_exp_f32_e32 v79, v79
	v_pk_mul_f32 v[4:5], v[4:5], v[126:127] op_sel_hi:[1,0]
	v_rcp_f32_e32 v128, v44
	v_pk_mul_f32 v[6:7], v[6:7], v[126:127] op_sel_hi:[1,0]
	v_pk_mul_f32 v[12:13], v[12:13], v[126:127] op_sel_hi:[1,0]
	s_and_b64 vcc, exec, s[60:61]
	s_waitcnt vmcnt(3)
	v_pk_mul_f32 v[0:1], v[192:193], v[4:5]
	v_add_f32_e32 v4, 1.0, v79
	v_rcp_f32_e32 v129, v4
	v_lshlrev_b32_e32 v4, 16, v45
	v_mul_f32_e32 v5, 0xbfb8aa3b, v4
	v_exp_f32_e32 v44, v5
	v_and_b32_e32 v5, 0xffff0000, v45
	v_mul_f32_e32 v45, 0xbfb8aa3b, v5
	v_exp_f32_e32 v45, v45
	v_add_f32_e32 v44, 1.0, v44
	v_pk_mul_f32 v[2:3], v[194:195], v[6:7]
	v_rcp_f32_e32 v44, v44
	v_add_f32_e32 v6, 1.0, v45
	v_rcp_f32_e32 v45, v6
	v_lshlrev_b32_e32 v6, 16, v46
	v_pk_mul_f32 v[54:55], v[128:129], v[54:55]
	v_mul_f32_e32 v7, 0xbfb8aa3b, v6
	v_pk_mul_f32 v[0:1], v[54:55], v[0:1]
	v_exp_f32_e32 v54, v7
	v_pk_mul_f32 v[4:5], v[44:45], v[4:5]
	v_and_b32_e32 v7, 0xffff0000, v46
	v_pk_mul_f32 v[2:3], v[4:5], v[2:3]
	v_mul_f32_e32 v5, 0xbfb8aa3b, v7
	v_exp_f32_e32 v5, v5
	v_add_f32_e32 v4, 1.0, v54
	v_rcp_f32_e32 v4, v4
	s_waitcnt vmcnt(2)
	v_pk_mul_f32 v[8:9], v[196:197], v[12:13]
	v_add_f32_e32 v5, 1.0, v5
	v_rcp_f32_e32 v5, v5
	v_lshlrev_b32_e32 v12, 16, v47
	v_mul_f32_e32 v13, 0xbfb8aa3b, v12
	v_exp_f32_e32 v44, v13
	v_and_b32_e32 v13, 0xffff0000, v47
	v_pk_mul_f32 v[4:5], v[4:5], v[6:7]
	v_mul_f32_e32 v7, 0xbfb8aa3b, v13
	v_exp_f32_e32 v7, v7
	v_add_f32_e32 v6, 1.0, v44
	v_rcp_f32_e32 v6, v6
	v_pk_mul_f32 v[4:5], v[4:5], v[8:9]
	v_add_f32_e32 v7, 1.0, v7
	v_rcp_f32_e32 v7, v7
	v_pk_mul_f32 v[8:9], v[14:15], v[126:127] op_sel_hi:[1,0]
	v_cvt_pk_bf16_f32 v0, v0, v1
	v_pk_mul_f32 v[8:9], v[198:199], v[8:9]
	v_lshlrev_b32_e32 v10, 16, v40
	v_mul_f32_e32 v11, 0xbfb8aa3b, v10
	v_exp_f32_e32 v14, v11
	v_pk_mul_f32 v[6:7], v[6:7], v[12:13]
	v_and_b32_e32 v11, 0xffff0000, v40
	v_pk_mul_f32 v[6:7], v[6:7], v[8:9]
	v_mul_f32_e32 v9, 0xbfb8aa3b, v11
	v_exp_f32_e32 v9, v9
	v_add_f32_e32 v8, 1.0, v14
	v_rcp_f32_e32 v8, v8
	v_lshlrev_b32_e32 v14, 16, v41
	v_add_f32_e32 v9, 1.0, v9
	v_rcp_f32_e32 v9, v9
	v_mul_f32_e32 v15, 0xbfb8aa3b, v14
	v_exp_f32_e32 v40, v15
	v_and_b32_e32 v15, 0xffff0000, v41
	v_pk_mul_f32 v[8:9], v[8:9], v[10:11]
	v_mul_f32_e32 v11, 0xbfb8aa3b, v15
	v_exp_f32_e32 v11, v11
	v_add_f32_e32 v10, 1.0, v40
	v_lshlrev_b32_e32 v40, 16, v42
	v_and_b32_e32 v41, 0xffff0000, v42
	v_add_f32_e32 v11, 1.0, v11
	v_mul_f32_e32 v42, 0xbfb8aa3b, v40
	v_mul_f32_e32 v44, 0xbfb8aa3b, v41
	v_rcp_f32_e32 v10, v10
	v_rcp_f32_e32 v11, v11
	v_exp_f32_e32 v42, v42
	v_exp_f32_e32 v44, v44
	v_pk_mul_f32 v[12:13], v[50:51], v[126:127] op_sel_hi:[1,0]
	v_pk_mul_f32 v[10:11], v[10:11], v[14:15]
	v_add_f32_e32 v14, 1.0, v42
	v_add_f32_e32 v15, 1.0, v44
	s_waitcnt vmcnt(0)
	v_pk_mul_f32 v[12:13], v[200:201], v[12:13]
	v_rcp_f32_e32 v14, v14
	v_rcp_f32_e32 v15, v15
	v_pk_mul_f32 v[8:9], v[8:9], v[12:13]
	v_pk_mul_f32 v[12:13], v[52:53], v[126:127] op_sel_hi:[1,0]
	v_cvt_pk_bf16_f32 v1, v2, v3
	v_pk_mul_f32 v[12:13], v[202:203], v[12:13]
	v_pk_mul_f32 v[14:15], v[14:15], v[40:41]
	v_pk_mul_f32 v[10:11], v[10:11], v[12:13]
	v_pk_mul_f32 v[12:13], v[114:115], v[126:127] op_sel_hi:[1,0]
	v_cvt_pk_bf16_f32 v2, v4, v5
	v_pk_mul_f32 v[12:13], v[12:13], v[204:205]
	v_cvt_pk_bf16_f32 v4, v8, v9
	v_pk_mul_f32 v[12:13], v[14:15], v[12:13]
	v_lshlrev_b32_e32 v14, 16, v43
	v_mul_f32_e32 v15, 0xbfb8aa3b, v14
	v_exp_f32_e32 v40, v15
	v_and_b32_e32 v15, 0xffff0000, v43
	v_mul_f32_e32 v41, 0xbfb8aa3b, v15
	v_exp_f32_e32 v41, v41
	v_add_f32_e32 v40, 1.0, v40
	v_rcp_f32_e32 v40, v40
	v_pk_mul_f32 v[42:43], v[116:117], v[126:127] op_sel_hi:[1,0]
	v_add_f32_e32 v41, 1.0, v41
	v_rcp_f32_e32 v41, v41
	v_cvt_pk_bf16_f32 v5, v10, v11
	v_pk_mul_f32 v[10:11], v[42:43], v[206:207]
	v_cvt_pk_bf16_f32 v3, v6, v7
	v_pk_mul_f32 v[8:9], v[40:41], v[14:15]
	v_cvt_pk_bf16_f32 v6, v12, v13
	v_pk_mul_f32 v[8:9], v[8:9], v[10:11]
	v_mov_b64_e32 v[54:55], v[22:23]
	v_cvt_pk_bf16_f32 v7, v8, v9
	v_lshlrev_b64 v[8:9], 10, v[48:49]
	v_lshl_add_u64 v[8:9], v[84:85], 0, v[8:9]
	global_store_dwordx4 v[8:9], v[0:3], off
	global_store_dwordx4 v[8:9], v[4:7], off offset:16
	v_mov_b64_e32 v[50:51], v[38:39]
	v_mov_b64_e32 v[0:1], v[24:25]
	v_mov_b64_e32 v[46:47], v[34:35]
	v_mov_b64_e32 v[42:43], v[30:31]
	v_mov_b64_e32 v[2:3], v[26:27]
	v_mov_b64_e32 v[52:53], v[20:21]
	v_mov_b64_e32 v[48:49], v[36:37]
	v_mov_b64_e32 v[44:45], v[32:33]
	v_mov_b64_e32 v[40:41], v[28:29]
	s_barrier
	s_cbranch_vccnz .LBB0_1415
